# lean in-proj/gate and up epilogues v2: first-half rstd partials loaded before the K-loop into K-loop-free VGPRs, second-half partials loaded at epilogue entry and consumed after first-half stores
# baseline (speedup 1.0000x reference)
; __device__ __forceinline__ unsigned cvt_pk_bf16(float lo, float hi) { unsigned r; asm volatile("v_cvt_pk_bf16_f32 %0, %1, %2" : "=v"(r) : "v"(lo), "v"(hi)); return r; }
; #define GAS __attribute__((address_space(1)))
; DI int lane_id_opaque() { int l; asm volatile("v_mbcnt_lo_u32_b32 %0, -1, 0\n\tv_mbcnt_hi_u32_b32 %0, -1, %0" : "=v"(l)); return l; }
;     DI void operator()(AccRef acc, const pg8::Unit& u, int wr, int wc, int, int) const {
;         const int lane_ = lane_id_opaque(), fr = lane_ & 15, fq = lane_ >> 4;
;         EPI_PRELOAD_RSTD(ssq)
;         EPI_ROWS_BEGIN
;             const float rs = rs8[ai * 4 + m];
;             EPI_COLS_BEGIN
;                 {
;                     const f32x4 z4 = {0.f, 0.f, 0.f, 0.f}; const float rs2 = rs * rs;
;                     const f32x4 m0 = __builtin_elementwise_max(v0, z4), m1 = __builtin_elementwise_max(v1, z4);
;                     v0 = (v0 * m0) * rs2; v1 = (v1 * m1) * rs2;
;                 }
;                 u32x4 w; w.x = cvt_pk_bf16(v0[0], v0[1]); w.y = cvt_pk_bf16(v0[2], v0[3]); w.z = cvt_pk_bf16(v1[0], v1[1]); w.w = cvt_pk_bf16(v1[2], v1[3]);
;                 *(GAS u32x4*)(U + (size_t)lrow * UP + col) = w;
.Llean_C_entry:
	v_mbcnt_lo_u32_b32 v128, -1, 0
	v_mbcnt_hi_u32_b32 v128, -1, v128
	v_and_b32_e32 v129, 15, v128
	v_lshrrev_b32_e32 v130, 4, v128
	v_or_b32_e32 v129, s49, v129
	v_lshl_add_u32 v131, s88, 8, v129
	v_lshlrev_b32_e32 v132, 4, v130
	v_lshl_add_u32 v132, v131, 6, v132
	v_add_u32_e32 v132, 0x2000, v132
	v_mov_b32_e32 v133, 0
	v_lshl_add_u64 v[136:137], s[60:61], 0, v[132:133]
	global_load_dwordx4 v[140:143], v[136:137], off
	global_load_dwordx4 v[144:147], v[136:137], off offset:1024
	global_load_dwordx4 v[148:151], v[136:137], off offset:2048
	global_load_dwordx4 v[152:155], v[136:137], off offset:3072
	v_readlane_b32 s4, v253, 51
	v_readlane_b32 s5, v253, 52
	v_mul_lo_u32 v196, v131, s43
	v_mov_b32_e32 v197, 0
	s_lshl_b32 s2, s80, 8
	s_or_b32 s2, s2, s62
	v_lshl_add_u32 v138, v130, 3, s2
	v_lshlrev_b32_e32 v138, 1, v138
	v_mov_b32_e32 v139, 0
	v_lshl_add_u64 v[196:197], v[196:197], 0, s[4:5]
	v_lshl_add_u64 v[196:197], v[196:197], 0, v[138:139]
	s_mov_b32 s2, 0x20800
	s_mov_b32 s3, 0
	s_mov_b32 s30, 0xa2800
	s_mov_b32 s31, 0
	v_mov_b32_e32 v195, 0x260
	v_add_f32_e32 v208, v224, v225
	v_add_f32_e32 v209, v226, v227
	v_add_f32_e32 v208, v208, v209
	v_add_f32_e32 v210, v228, v229
	v_add_f32_e32 v211, v230, v231
	v_add_f32_e32 v210, v210, v211
	v_add_f32_e32 v212, v232, v233
	v_add_f32_e32 v213, v234, v235
	v_add_f32_e32 v212, v212, v213
	v_add_f32_e32 v214, v236, v237
	v_add_f32_e32 v215, v238, v239
	v_add_f32_e32 v214, v214, v215
	ds_swizzle_b32 v209, v208 offset:swizzle(SWAP,16)
	ds_swizzle_b32 v211, v210 offset:swizzle(SWAP,16)
	ds_swizzle_b32 v213, v212 offset:swizzle(SWAP,16)
	ds_swizzle_b32 v215, v214 offset:swizzle(SWAP,16)
	s_waitcnt lgkmcnt(0)
	v_add_f32_e32 v208, v208, v209
	v_add_f32_e32 v210, v210, v211
	v_add_f32_e32 v212, v212, v213
	v_add_f32_e32 v214, v214, v215
	v_mov_b32_e32 v209, v208
	v_mov_b32_e32 v211, v210
	v_mov_b32_e32 v213, v212
	v_mov_b32_e32 v215, v214
	s_nop 1
	v_permlane32_swap_b32_e32 v208, v209
	v_permlane32_swap_b32_e32 v210, v211
	v_permlane32_swap_b32_e32 v212, v213
	v_permlane32_swap_b32_e32 v214, v215
	v_add_f32_e32 v208, v208, v209
	v_add_f32_e32 v210, v210, v211
	v_add_f32_e32 v212, v212, v213
	v_add_f32_e32 v214, v214, v215
	v_fmamk_f32 v208, v208, 0x3a800000, v246
	v_cmp_gt_f32_e32 vcc, s33, v208
	v_mul_f32_e32 v188, 0x4f800000, v208
	s_nop 0
	v_cndmask_b32_e32 v208, v208, v188, vcc
	v_sqrt_f32_e32 v188, v208
	s_nop 0
	v_add_u32_e32 v189, -1, v188
	v_fma_f32 v190, -v189, v188, v208
	v_cmp_ge_f32_e64 s[98:99], 0, v190
	v_add_u32_e32 v190, 1, v188
	s_nop 0
	v_cndmask_b32_e64 v189, v188, v189, s[98:99]
	v_fma_f32 v188, -v190, v188, v208
	v_cmp_lt_f32_e64 s[98:99], 0, v188
	s_nop 1
	v_cndmask_b32_e64 v188, v189, v190, s[98:99]
	v_mul_f32_e32 v189, 0x37800000, v188
	v_cndmask_b32_e32 v188, v188, v189, vcc
	v_cmp_class_f32_e32 vcc, v208, v195
	s_nop 1
	v_cndmask_b32_e32 v208, v188, v208, vcc
	v_div_scale_f32 v188, s[98:99], v208, v208, 1.0
	v_rcp_f32_e32 v189, v188
	s_nop 0
	v_fma_f32 v190, -v188, v189, 1.0
	v_fmac_f32_e32 v189, v190, v189
	v_div_scale_f32 v190, vcc, 1.0, v208, 1.0
	v_mul_f32_e32 v191, v190, v189
	v_fma_f32 v194, -v188, v191, v190
	v_fmac_f32_e32 v191, v194, v189
	v_fma_f32 v188, -v188, v191, v190
	v_div_fmas_f32 v188, v188, v189, v191
	v_div_fixup_f32 v208, v188, v208, 1.0
	v_fmamk_f32 v210, v210, 0x3a800000, v246
	v_cmp_gt_f32_e32 vcc, s33, v210
	v_mul_f32_e32 v188, 0x4f800000, v210
	s_nop 0
	v_cndmask_b32_e32 v210, v210, v188, vcc
	v_sqrt_f32_e32 v188, v210
	s_nop 0
	v_add_u32_e32 v189, -1, v188
	v_fma_f32 v190, -v189, v188, v210
	v_cmp_ge_f32_e64 s[98:99], 0, v190
	v_add_u32_e32 v190, 1, v188
	s_nop 0
	v_cndmask_b32_e64 v189, v188, v189, s[98:99]
	v_fma_f32 v188, -v190, v188, v210
	v_cmp_lt_f32_e64 s[98:99], 0, v188
	s_nop 1
	v_cndmask_b32_e64 v188, v189, v190, s[98:99]
	v_mul_f32_e32 v189, 0x37800000, v188
	v_cndmask_b32_e32 v188, v188, v189, vcc
	v_cmp_class_f32_e32 vcc, v210, v195
	s_nop 1
	v_cndmask_b32_e32 v210, v188, v210, vcc
	v_div_scale_f32 v188, s[98:99], v210, v210, 1.0
	v_rcp_f32_e32 v189, v188
	s_nop 0
	v_fma_f32 v190, -v188, v189, 1.0
	v_fmac_f32_e32 v189, v190, v189
	v_div_scale_f32 v190, vcc, 1.0, v210, 1.0
	v_mul_f32_e32 v191, v190, v189
	v_fma_f32 v194, -v188, v191, v190
	v_fmac_f32_e32 v191, v194, v189
	v_fma_f32 v188, -v188, v191, v190
	v_div_fmas_f32 v188, v188, v189, v191
	v_div_fixup_f32 v210, v188, v210, 1.0
	v_fmamk_f32 v212, v212, 0x3a800000, v246
	v_cmp_gt_f32_e32 vcc, s33, v212
	v_mul_f32_e32 v188, 0x4f800000, v212
	s_nop 0
	v_cndmask_b32_e32 v212, v212, v188, vcc
	v_sqrt_f32_e32 v188, v212
	s_nop 0
	v_add_u32_e32 v189, -1, v188
	v_fma_f32 v190, -v189, v188, v212
	v_cmp_ge_f32_e64 s[98:99], 0, v190
	v_add_u32_e32 v190, 1, v188
	s_nop 0
	v_cndmask_b32_e64 v189, v188, v189, s[98:99]
	v_fma_f32 v188, -v190, v188, v212
	v_cmp_lt_f32_e64 s[98:99], 0, v188
	s_nop 1
	v_cndmask_b32_e64 v188, v189, v190, s[98:99]
	v_mul_f32_e32 v189, 0x37800000, v188
	v_cndmask_b32_e32 v188, v188, v189, vcc
	v_cmp_class_f32_e32 vcc, v212, v195
	s_nop 1
	v_cndmask_b32_e32 v212, v188, v212, vcc
	v_div_scale_f32 v188, s[98:99], v212, v212, 1.0
	v_rcp_f32_e32 v189, v188
	s_nop 0
	v_fma_f32 v190, -v188, v189, 1.0
	v_fmac_f32_e32 v189, v190, v189
	v_div_scale_f32 v190, vcc, 1.0, v212, 1.0
	v_mul_f32_e32 v191, v190, v189
	v_fma_f32 v194, -v188, v191, v190
	v_fmac_f32_e32 v191, v194, v189
	v_fma_f32 v188, -v188, v191, v190
	v_div_fmas_f32 v188, v188, v189, v191
	v_div_fixup_f32 v212, v188, v212, 1.0
	v_fmamk_f32 v214, v214, 0x3a800000, v246
	v_cmp_gt_f32_e32 vcc, s33, v214
	v_mul_f32_e32 v188, 0x4f800000, v214
	s_nop 0
	v_cndmask_b32_e32 v214, v214, v188, vcc
	v_sqrt_f32_e32 v188, v214
; __device__ __forceinline__ unsigned cvt_pk_bf16(float lo, float hi) { unsigned r; asm volatile("v_cvt_pk_bf16_f32 %0, %1, %2" : "=v"(r) : "v"(lo), "v"(hi)); return r; }
; #define GAS __attribute__((address_space(1)))
;     DI void operator()(AccRef acc, const pg8::Unit& u, int wr, int wc, int, int) const {
;     ...
;         EPI_ROWS_BEGIN
;             const float rs = rs8[ai * 4 + m];
;             EPI_COLS_BEGIN
;                 {
;                     const f32x4 z4 = {0.f, 0.f, 0.f, 0.f}; const float rs2 = rs * rs;
;                     const f32x4 m0 = __builtin_elementwise_max(v0, z4), m1 = __builtin_elementwise_max(v1, z4);
;                     v0 = (v0 * m0) * rs2; v1 = (v1 * m1) * rs2;
;                 }
;                 u32x4 w; w.x = cvt_pk_bf16(v0[0], v0[1]); w.y = cvt_pk_bf16(v0[2], v0[3]); w.z = cvt_pk_bf16(v1[0], v1[1]); w.w = cvt_pk_bf16(v1[2], v1[3]);
;                 *(GAS u32x4*)(U + (size_t)lrow * UP + col) = w;
	s_nop 0
	v_add_u32_e32 v189, -1, v188
	v_fma_f32 v190, -v189, v188, v214
	v_cmp_ge_f32_e64 s[98:99], 0, v190
	v_add_u32_e32 v190, 1, v188
	s_nop 0
	v_cndmask_b32_e64 v189, v188, v189, s[98:99]
	v_fma_f32 v188, -v190, v188, v214
	v_cmp_lt_f32_e64 s[98:99], 0, v188
	s_nop 1
	v_cndmask_b32_e64 v188, v189, v190, s[98:99]
	v_mul_f32_e32 v189, 0x37800000, v188
	v_cndmask_b32_e32 v188, v188, v189, vcc
	v_cmp_class_f32_e32 vcc, v214, v195
	s_nop 1
	v_cndmask_b32_e32 v214, v188, v214, vcc
	v_div_scale_f32 v188, s[98:99], v214, v214, 1.0
	v_rcp_f32_e32 v189, v188
	s_nop 0
	v_fma_f32 v190, -v188, v189, 1.0
	v_fmac_f32_e32 v189, v190, v189
	v_div_scale_f32 v190, vcc, 1.0, v214, 1.0
	v_mul_f32_e32 v191, v190, v189
	v_fma_f32 v194, -v188, v191, v190
	v_fmac_f32_e32 v191, v194, v189
	v_fma_f32 v188, -v188, v191, v190
	v_div_fmas_f32 v188, v188, v189, v191
	v_div_fixup_f32 v214, v188, v214, 1.0
	v_mul_f32_e32 v208, v208, v208
	v_mul_f32_e32 v210, v210, v210
	v_mul_f32_e32 v212, v212, v212
	v_mul_f32_e32 v214, v214, v214
	v_max_f32_e32 v166, 0, v124
	v_max_f32_e32 v167, 0, v125
	v_max_f32_e32 v168, 0, v126
	v_max_f32_e32 v169, 0, v127
	v_max_f32_e32 v170, 0, v120
	v_max_f32_e32 v171, 0, v121
	v_max_f32_e32 v172, 0, v122
	v_max_f32_e32 v173, 0, v123
	v_pk_mul_f32 v[124:125], v[124:125], v[166:167]
	v_pk_mul_f32 v[126:127], v[126:127], v[168:169]
	v_pk_mul_f32 v[120:121], v[120:121], v[170:171]
	v_pk_mul_f32 v[122:123], v[122:123], v[172:173]
	v_pk_mul_f32 v[124:125], v[124:125], v[208:209] op_sel_hi:[1,0]
	v_pk_mul_f32 v[126:127], v[126:127], v[208:209] op_sel_hi:[1,0]
	v_pk_mul_f32 v[120:121], v[120:121], v[208:209] op_sel_hi:[1,0]
	v_pk_mul_f32 v[122:123], v[122:123], v[208:209] op_sel_hi:[1,0]
	v_cvt_pk_bf16_f32 v174, v124, v125
	v_cvt_pk_bf16_f32 v175, v126, v127
	v_cvt_pk_bf16_f32 v176, v120, v121
	v_cvt_pk_bf16_f32 v177, v122, v123
	global_store_dwordx4 v[196:197], v[174:177], off
	v_max_f32_e32 v166, 0, v116
	v_max_f32_e32 v167, 0, v117
	v_max_f32_e32 v168, 0, v118
	v_max_f32_e32 v169, 0, v119
	v_max_f32_e32 v170, 0, v112
	v_max_f32_e32 v171, 0, v113
	v_max_f32_e32 v172, 0, v114
	v_max_f32_e32 v173, 0, v115
	v_pk_mul_f32 v[116:117], v[116:117], v[166:167]
	v_pk_mul_f32 v[118:119], v[118:119], v[168:169]
	v_pk_mul_f32 v[112:113], v[112:113], v[170:171]
	v_pk_mul_f32 v[114:115], v[114:115], v[172:173]
	v_pk_mul_f32 v[116:117], v[116:117], v[208:209] op_sel_hi:[1,0]
	v_pk_mul_f32 v[118:119], v[118:119], v[208:209] op_sel_hi:[1,0]
	v_pk_mul_f32 v[112:113], v[112:113], v[208:209] op_sel_hi:[1,0]
	v_pk_mul_f32 v[114:115], v[114:115], v[208:209] op_sel_hi:[1,0]
	v_cvt_pk_bf16_f32 v178, v116, v117
	v_cvt_pk_bf16_f32 v179, v118, v119
	v_cvt_pk_bf16_f32 v180, v112, v113
	v_cvt_pk_bf16_f32 v181, v114, v115
	global_store_dwordx4 v[196:197], v[178:181], off offset:256
	v_lshl_add_u64 v[244:245], v[196:197], 0, s[2:3]
	v_max_f32_e32 v166, 0, v108
	v_max_f32_e32 v167, 0, v109
	v_max_f32_e32 v168, 0, v110
	v_max_f32_e32 v169, 0, v111
	v_max_f32_e32 v170, 0, v104
	v_max_f32_e32 v171, 0, v105
	v_max_f32_e32 v172, 0, v106
	v_max_f32_e32 v173, 0, v107
	v_pk_mul_f32 v[108:109], v[108:109], v[166:167]
	v_pk_mul_f32 v[110:111], v[110:111], v[168:169]
	v_pk_mul_f32 v[104:105], v[104:105], v[170:171]
	v_pk_mul_f32 v[106:107], v[106:107], v[172:173]
	v_pk_mul_f32 v[108:109], v[108:109], v[210:211] op_sel_hi:[1,0]
	v_pk_mul_f32 v[110:111], v[110:111], v[210:211] op_sel_hi:[1,0]
	v_pk_mul_f32 v[104:105], v[104:105], v[210:211] op_sel_hi:[1,0]
	v_pk_mul_f32 v[106:107], v[106:107], v[210:211] op_sel_hi:[1,0]
	v_cvt_pk_bf16_f32 v174, v108, v109
	v_cvt_pk_bf16_f32 v175, v110, v111
	v_cvt_pk_bf16_f32 v176, v104, v105
	v_cvt_pk_bf16_f32 v177, v106, v107
	global_store_dwordx4 v[244:245], v[174:177], off
	v_max_f32_e32 v166, 0, v100
	v_max_f32_e32 v167, 0, v101
	v_max_f32_e32 v168, 0, v102
	v_max_f32_e32 v169, 0, v103
	v_max_f32_e32 v170, 0, v96
	v_max_f32_e32 v171, 0, v97
	v_max_f32_e32 v172, 0, v98
	v_max_f32_e32 v173, 0, v99
	v_pk_mul_f32 v[100:101], v[100:101], v[166:167]
	v_pk_mul_f32 v[102:103], v[102:103], v[168:169]
	v_pk_mul_f32 v[96:97], v[96:97], v[170:171]
	v_pk_mul_f32 v[98:99], v[98:99], v[172:173]
	v_pk_mul_f32 v[100:101], v[100:101], v[210:211] op_sel_hi:[1,0]
	v_pk_mul_f32 v[102:103], v[102:103], v[210:211] op_sel_hi:[1,0]
	v_pk_mul_f32 v[96:97], v[96:97], v[210:211] op_sel_hi:[1,0]
	v_pk_mul_f32 v[98:99], v[98:99], v[210:211] op_sel_hi:[1,0]
	v_cvt_pk_bf16_f32 v178, v100, v101
	v_cvt_pk_bf16_f32 v179, v102, v103
	v_cvt_pk_bf16_f32 v180, v96, v97
	v_cvt_pk_bf16_f32 v181, v98, v99
	global_store_dwordx4 v[244:245], v[178:181], off offset:256
	v_lshl_add_u64 v[196:197], v[244:245], 0, s[2:3]
	v_max_f32_e32 v166, 0, v92
	v_max_f32_e32 v167, 0, v93
	v_max_f32_e32 v168, 0, v94
	v_max_f32_e32 v169, 0, v95
	v_max_f32_e32 v170, 0, v88
	v_max_f32_e32 v171, 0, v89
	v_max_f32_e32 v172, 0, v90
	v_max_f32_e32 v173, 0, v91
	v_pk_mul_f32 v[92:93], v[92:93], v[166:167]
	v_pk_mul_f32 v[94:95], v[94:95], v[168:169]
	v_pk_mul_f32 v[88:89], v[88:89], v[170:171]
	v_pk_mul_f32 v[90:91], v[90:91], v[172:173]
	v_pk_mul_f32 v[92:93], v[92:93], v[212:213] op_sel_hi:[1,0]
	v_pk_mul_f32 v[94:95], v[94:95], v[212:213] op_sel_hi:[1,0]
	v_pk_mul_f32 v[88:89], v[88:89], v[212:213] op_sel_hi:[1,0]
	v_pk_mul_f32 v[90:91], v[90:91], v[212:213] op_sel_hi:[1,0]
	v_cvt_pk_bf16_f32 v174, v92, v93
	v_cvt_pk_bf16_f32 v175, v94, v95
	v_cvt_pk_bf16_f32 v176, v88, v89
	v_cvt_pk_bf16_f32 v177, v90, v91
	global_store_dwordx4 v[196:197], v[174:177], off
	v_max_f32_e32 v166, 0, v84
	v_max_f32_e32 v167, 0, v85
	v_max_f32_e32 v168, 0, v86
	v_max_f32_e32 v169, 0, v87
	v_max_f32_e32 v170, 0, v80
	v_max_f32_e32 v171, 0, v81
; __device__ __forceinline__ unsigned cvt_pk_bf16(float lo, float hi) { unsigned r; asm volatile("v_cvt_pk_bf16_f32 %0, %1, %2" : "=v"(r) : "v"(lo), "v"(hi)); return r; }
; #define GAS __attribute__((address_space(1)))
;     DI void operator()(AccRef acc, const pg8::Unit& u, int wr, int wc, int, int) const {
;     ...
;         EPI_ROWS_BEGIN
;             const float rs = rs8[ai * 4 + m];
;             EPI_COLS_BEGIN
;                 {
;                     const f32x4 z4 = {0.f, 0.f, 0.f, 0.f}; const float rs2 = rs * rs;
;                     const f32x4 m0 = __builtin_elementwise_max(v0, z4), m1 = __builtin_elementwise_max(v1, z4);
;                     v0 = (v0 * m0) * rs2; v1 = (v1 * m1) * rs2;
;                 }
;                 u32x4 w; w.x = cvt_pk_bf16(v0[0], v0[1]); w.y = cvt_pk_bf16(v0[2], v0[3]); w.z = cvt_pk_bf16(v1[0], v1[1]); w.w = cvt_pk_bf16(v1[2], v1[3]);
;                 *(GAS u32x4*)(U + (size_t)lrow * UP + col) = w;
	v_max_f32_e32 v172, 0, v82
	v_max_f32_e32 v173, 0, v83
	v_pk_mul_f32 v[84:85], v[84:85], v[166:167]
	v_pk_mul_f32 v[86:87], v[86:87], v[168:169]
	v_pk_mul_f32 v[80:81], v[80:81], v[170:171]
	v_pk_mul_f32 v[82:83], v[82:83], v[172:173]
	v_pk_mul_f32 v[84:85], v[84:85], v[212:213] op_sel_hi:[1,0]
	v_pk_mul_f32 v[86:87], v[86:87], v[212:213] op_sel_hi:[1,0]
	v_pk_mul_f32 v[80:81], v[80:81], v[212:213] op_sel_hi:[1,0]
	v_pk_mul_f32 v[82:83], v[82:83], v[212:213] op_sel_hi:[1,0]
	v_cvt_pk_bf16_f32 v178, v84, v85
	v_cvt_pk_bf16_f32 v179, v86, v87
	v_cvt_pk_bf16_f32 v180, v80, v81
	v_cvt_pk_bf16_f32 v181, v82, v83
	global_store_dwordx4 v[196:197], v[178:181], off offset:256
	v_lshl_add_u64 v[244:245], v[196:197], 0, s[2:3]
	v_max_f32_e32 v166, 0, v76
	v_max_f32_e32 v167, 0, v77
	v_max_f32_e32 v168, 0, v78
	v_max_f32_e32 v169, 0, v79
	v_max_f32_e32 v170, 0, v72
	v_max_f32_e32 v171, 0, v73
	v_max_f32_e32 v172, 0, v74
	v_max_f32_e32 v173, 0, v75
	v_pk_mul_f32 v[76:77], v[76:77], v[166:167]
	v_pk_mul_f32 v[78:79], v[78:79], v[168:169]
	v_pk_mul_f32 v[72:73], v[72:73], v[170:171]
	v_pk_mul_f32 v[74:75], v[74:75], v[172:173]
	v_pk_mul_f32 v[76:77], v[76:77], v[214:215] op_sel_hi:[1,0]
	v_pk_mul_f32 v[78:79], v[78:79], v[214:215] op_sel_hi:[1,0]
	v_pk_mul_f32 v[72:73], v[72:73], v[214:215] op_sel_hi:[1,0]
	v_pk_mul_f32 v[74:75], v[74:75], v[214:215] op_sel_hi:[1,0]
	v_cvt_pk_bf16_f32 v174, v76, v77
	v_cvt_pk_bf16_f32 v175, v78, v79
	v_cvt_pk_bf16_f32 v176, v72, v73
	v_cvt_pk_bf16_f32 v177, v74, v75
	global_store_dwordx4 v[244:245], v[174:177], off
	v_max_f32_e32 v166, 0, v68
	v_max_f32_e32 v167, 0, v69
	v_max_f32_e32 v168, 0, v70
	v_max_f32_e32 v169, 0, v71
	v_max_f32_e32 v170, 0, v64
	v_max_f32_e32 v171, 0, v65
	v_max_f32_e32 v172, 0, v66
	v_max_f32_e32 v173, 0, v67
	v_pk_mul_f32 v[68:69], v[68:69], v[166:167]
	v_pk_mul_f32 v[70:71], v[70:71], v[168:169]
	v_pk_mul_f32 v[64:65], v[64:65], v[170:171]
	v_pk_mul_f32 v[66:67], v[66:67], v[172:173]
	v_pk_mul_f32 v[68:69], v[68:69], v[214:215] op_sel_hi:[1,0]
	v_pk_mul_f32 v[70:71], v[70:71], v[214:215] op_sel_hi:[1,0]
	v_pk_mul_f32 v[64:65], v[64:65], v[214:215] op_sel_hi:[1,0]
	v_pk_mul_f32 v[66:67], v[66:67], v[214:215] op_sel_hi:[1,0]
	v_cvt_pk_bf16_f32 v178, v68, v69
	v_cvt_pk_bf16_f32 v179, v70, v71
	v_cvt_pk_bf16_f32 v180, v64, v65
	v_cvt_pk_bf16_f32 v181, v66, v67
	global_store_dwordx4 v[244:245], v[178:181], off offset:256
	v_lshl_add_u64 v[196:197], v[244:245], 0, s[30:31]
	s_waitcnt vmcnt(8)
	v_add_f32_e32 v216, v140, v141
	v_add_f32_e32 v217, v142, v143
	v_add_f32_e32 v216, v216, v217
	v_add_f32_e32 v218, v144, v145
	v_add_f32_e32 v219, v146, v147
	v_add_f32_e32 v218, v218, v219
	v_add_f32_e32 v184, v148, v149
	v_add_f32_e32 v185, v150, v151
	v_add_f32_e32 v184, v184, v185
	v_add_f32_e32 v186, v152, v153
	v_add_f32_e32 v187, v154, v155
	v_add_f32_e32 v186, v186, v187
	ds_swizzle_b32 v217, v216 offset:swizzle(SWAP,16)
	ds_swizzle_b32 v219, v218 offset:swizzle(SWAP,16)
	ds_swizzle_b32 v185, v184 offset:swizzle(SWAP,16)
	ds_swizzle_b32 v187, v186 offset:swizzle(SWAP,16)
	s_waitcnt lgkmcnt(0)
	v_add_f32_e32 v216, v216, v217
	v_add_f32_e32 v218, v218, v219
	v_add_f32_e32 v184, v184, v185
	v_add_f32_e32 v186, v186, v187
	v_mov_b32_e32 v217, v216
	v_mov_b32_e32 v219, v218
	v_mov_b32_e32 v185, v184
	v_mov_b32_e32 v187, v186
	s_nop 1
	v_permlane32_swap_b32_e32 v216, v217
	v_permlane32_swap_b32_e32 v218, v219
	v_permlane32_swap_b32_e32 v184, v185
	v_permlane32_swap_b32_e32 v186, v187
	v_add_f32_e32 v216, v216, v217
	v_add_f32_e32 v218, v218, v219
	v_add_f32_e32 v184, v184, v185
	v_add_f32_e32 v186, v186, v187
	v_fmamk_f32 v216, v216, 0x3a800000, v246
	v_cmp_gt_f32_e32 vcc, s33, v216
	v_mul_f32_e32 v188, 0x4f800000, v216
	s_nop 0
	v_cndmask_b32_e32 v216, v216, v188, vcc
	v_sqrt_f32_e32 v188, v216
	s_nop 0
	v_add_u32_e32 v189, -1, v188
	v_fma_f32 v190, -v189, v188, v216
	v_cmp_ge_f32_e64 s[98:99], 0, v190
	v_add_u32_e32 v190, 1, v188
	s_nop 0
	v_cndmask_b32_e64 v189, v188, v189, s[98:99]
	v_fma_f32 v188, -v190, v188, v216
	v_cmp_lt_f32_e64 s[98:99], 0, v188
	s_nop 1
	v_cndmask_b32_e64 v188, v189, v190, s[98:99]
	v_mul_f32_e32 v189, 0x37800000, v188
	v_cndmask_b32_e32 v188, v188, v189, vcc
	v_cmp_class_f32_e32 vcc, v216, v195
	s_nop 1
	v_cndmask_b32_e32 v216, v188, v216, vcc
	v_div_scale_f32 v188, s[98:99], v216, v216, 1.0
	v_rcp_f32_e32 v189, v188
	s_nop 0
	v_fma_f32 v190, -v188, v189, 1.0
	v_fmac_f32_e32 v189, v190, v189
	v_div_scale_f32 v190, vcc, 1.0, v216, 1.0
	v_mul_f32_e32 v191, v190, v189
	v_fma_f32 v194, -v188, v191, v190
	v_fmac_f32_e32 v191, v194, v189
	v_fma_f32 v188, -v188, v191, v190
	v_div_fmas_f32 v188, v188, v189, v191
	v_div_fixup_f32 v216, v188, v216, 1.0
	v_fmamk_f32 v218, v218, 0x3a800000, v246
	v_cmp_gt_f32_e32 vcc, s33, v218
	v_mul_f32_e32 v188, 0x4f800000, v218
	s_nop 0
	v_cndmask_b32_e32 v218, v218, v188, vcc
	v_sqrt_f32_e32 v188, v218
	s_nop 0
	v_add_u32_e32 v189, -1, v188
	v_fma_f32 v190, -v189, v188, v218
	v_cmp_ge_f32_e64 s[98:99], 0, v190
	v_add_u32_e32 v190, 1, v188
	s_nop 0
	v_cndmask_b32_e64 v189, v188, v189, s[98:99]
	v_fma_f32 v188, -v190, v188, v218
	v_cmp_lt_f32_e64 s[98:99], 0, v188
	s_nop 1
	v_cndmask_b32_e64 v188, v189, v190, s[98:99]
	v_mul_f32_e32 v189, 0x37800000, v188
	v_cndmask_b32_e32 v188, v188, v189, vcc
	v_cmp_class_f32_e32 vcc, v218, v195
	s_nop 1
	v_cndmask_b32_e32 v218, v188, v218, vcc
	v_div_scale_f32 v188, s[98:99], v218, v218, 1.0
	v_rcp_f32_e32 v189, v188
	s_nop 0
	v_fma_f32 v190, -v188, v189, 1.0
	v_fmac_f32_e32 v189, v190, v189
	v_div_scale_f32 v190, vcc, 1.0, v218, 1.0
	v_mul_f32_e32 v191, v190, v189
	v_fma_f32 v194, -v188, v191, v190
; __device__ __forceinline__ unsigned cvt_pk_bf16(float lo, float hi) { unsigned r; asm volatile("v_cvt_pk_bf16_f32 %0, %1, %2" : "=v"(r) : "v"(lo), "v"(hi)); return r; }
; #define GAS __attribute__((address_space(1)))
;     DI void operator()(AccRef acc, const pg8::Unit& u, int wr, int wc, int, int) const {
;     ...
;         EPI_ROWS_BEGIN
;             const float rs = rs8[ai * 4 + m];
;             EPI_COLS_BEGIN
;                 {
;                     const f32x4 z4 = {0.f, 0.f, 0.f, 0.f}; const float rs2 = rs * rs;
;                     const f32x4 m0 = __builtin_elementwise_max(v0, z4), m1 = __builtin_elementwise_max(v1, z4);
;                     v0 = (v0 * m0) * rs2; v1 = (v1 * m1) * rs2;
;                 }
;                 u32x4 w; w.x = cvt_pk_bf16(v0[0], v0[1]); w.y = cvt_pk_bf16(v0[2], v0[3]); w.z = cvt_pk_bf16(v1[0], v1[1]); w.w = cvt_pk_bf16(v1[2], v1[3]);
;                 *(GAS u32x4*)(U + (size_t)lrow * UP + col) = w;
	v_fmac_f32_e32 v191, v194, v189
	v_fma_f32 v188, -v188, v191, v190
	v_div_fmas_f32 v188, v188, v189, v191
	v_div_fixup_f32 v218, v188, v218, 1.0
	v_fmamk_f32 v184, v184, 0x3a800000, v246
	v_cmp_gt_f32_e32 vcc, s33, v184
	v_mul_f32_e32 v188, 0x4f800000, v184
	s_nop 0
	v_cndmask_b32_e32 v184, v184, v188, vcc
	v_sqrt_f32_e32 v188, v184
	s_nop 0
	v_add_u32_e32 v189, -1, v188
	v_fma_f32 v190, -v189, v188, v184
	v_cmp_ge_f32_e64 s[98:99], 0, v190
	v_add_u32_e32 v190, 1, v188
	s_nop 0
	v_cndmask_b32_e64 v189, v188, v189, s[98:99]
	v_fma_f32 v188, -v190, v188, v184
	v_cmp_lt_f32_e64 s[98:99], 0, v188
	s_nop 1
	v_cndmask_b32_e64 v188, v189, v190, s[98:99]
	v_mul_f32_e32 v189, 0x37800000, v188
	v_cndmask_b32_e32 v188, v188, v189, vcc
	v_cmp_class_f32_e32 vcc, v184, v195
	s_nop 1
	v_cndmask_b32_e32 v184, v188, v184, vcc
	v_div_scale_f32 v188, s[98:99], v184, v184, 1.0
	v_rcp_f32_e32 v189, v188
	s_nop 0
	v_fma_f32 v190, -v188, v189, 1.0
	v_fmac_f32_e32 v189, v190, v189
	v_div_scale_f32 v190, vcc, 1.0, v184, 1.0
	v_mul_f32_e32 v191, v190, v189
	v_fma_f32 v194, -v188, v191, v190
	v_fmac_f32_e32 v191, v194, v189
	v_fma_f32 v188, -v188, v191, v190
	v_div_fmas_f32 v188, v188, v189, v191
	v_div_fixup_f32 v184, v188, v184, 1.0
	v_fmamk_f32 v186, v186, 0x3a800000, v246
	v_cmp_gt_f32_e32 vcc, s33, v186
	v_mul_f32_e32 v188, 0x4f800000, v186
	s_nop 0
	v_cndmask_b32_e32 v186, v186, v188, vcc
	v_sqrt_f32_e32 v188, v186
	s_nop 0
	v_add_u32_e32 v189, -1, v188
	v_fma_f32 v190, -v189, v188, v186
	v_cmp_ge_f32_e64 s[98:99], 0, v190
	v_add_u32_e32 v190, 1, v188
	s_nop 0
	v_cndmask_b32_e64 v189, v188, v189, s[98:99]
	v_fma_f32 v188, -v190, v188, v186
	v_cmp_lt_f32_e64 s[98:99], 0, v188
	s_nop 1
	v_cndmask_b32_e64 v188, v189, v190, s[98:99]
	v_mul_f32_e32 v189, 0x37800000, v188
	v_cndmask_b32_e32 v188, v188, v189, vcc
	v_cmp_class_f32_e32 vcc, v186, v195
	s_nop 1
	v_cndmask_b32_e32 v186, v188, v186, vcc
	v_div_scale_f32 v188, s[98:99], v186, v186, 1.0
	v_rcp_f32_e32 v189, v188
	s_nop 0
	v_fma_f32 v190, -v188, v189, 1.0
	v_fmac_f32_e32 v189, v190, v189
	v_div_scale_f32 v190, vcc, 1.0, v186, 1.0
	v_mul_f32_e32 v191, v190, v189
	v_fma_f32 v194, -v188, v191, v190
	v_fmac_f32_e32 v191, v194, v189
	v_fma_f32 v188, -v188, v191, v190
	v_div_fmas_f32 v188, v188, v189, v191
	v_div_fixup_f32 v186, v188, v186, 1.0
	v_mul_f32_e32 v216, v216, v216
	v_mul_f32_e32 v218, v218, v218
	v_mul_f32_e32 v184, v184, v184
	v_mul_f32_e32 v186, v186, v186
	v_max_f32_e32 v166, 0, v60
	v_max_f32_e32 v167, 0, v61
	v_max_f32_e32 v168, 0, v62
	v_max_f32_e32 v169, 0, v63
	v_max_f32_e32 v170, 0, v56
	v_max_f32_e32 v171, 0, v57
	v_max_f32_e32 v172, 0, v58
	v_max_f32_e32 v173, 0, v59
	v_pk_mul_f32 v[60:61], v[60:61], v[166:167]
	v_pk_mul_f32 v[62:63], v[62:63], v[168:169]
	v_pk_mul_f32 v[56:57], v[56:57], v[170:171]
	v_pk_mul_f32 v[58:59], v[58:59], v[172:173]
	v_pk_mul_f32 v[60:61], v[60:61], v[216:217] op_sel_hi:[1,0]
	v_pk_mul_f32 v[62:63], v[62:63], v[216:217] op_sel_hi:[1,0]
	v_pk_mul_f32 v[56:57], v[56:57], v[216:217] op_sel_hi:[1,0]
	v_pk_mul_f32 v[58:59], v[58:59], v[216:217] op_sel_hi:[1,0]
	v_cvt_pk_bf16_f32 v174, v60, v61
	v_cvt_pk_bf16_f32 v175, v62, v63
	v_cvt_pk_bf16_f32 v176, v56, v57
	v_cvt_pk_bf16_f32 v177, v58, v59
	global_store_dwordx4 v[196:197], v[174:177], off
	v_max_f32_e32 v166, 0, v52
	v_max_f32_e32 v167, 0, v53
	v_max_f32_e32 v168, 0, v54
	v_max_f32_e32 v169, 0, v55
	v_max_f32_e32 v170, 0, v48
	v_max_f32_e32 v171, 0, v49
	v_max_f32_e32 v172, 0, v50
	v_max_f32_e32 v173, 0, v51
	v_pk_mul_f32 v[52:53], v[52:53], v[166:167]
	v_pk_mul_f32 v[54:55], v[54:55], v[168:169]
	v_pk_mul_f32 v[48:49], v[48:49], v[170:171]
	v_pk_mul_f32 v[50:51], v[50:51], v[172:173]
	v_pk_mul_f32 v[52:53], v[52:53], v[216:217] op_sel_hi:[1,0]
	v_pk_mul_f32 v[54:55], v[54:55], v[216:217] op_sel_hi:[1,0]
	v_pk_mul_f32 v[48:49], v[48:49], v[216:217] op_sel_hi:[1,0]
	v_pk_mul_f32 v[50:51], v[50:51], v[216:217] op_sel_hi:[1,0]
	v_cvt_pk_bf16_f32 v178, v52, v53
	v_cvt_pk_bf16_f32 v179, v54, v55
	v_cvt_pk_bf16_f32 v180, v48, v49
	v_cvt_pk_bf16_f32 v181, v50, v51
	global_store_dwordx4 v[196:197], v[178:181], off offset:256
	v_lshl_add_u64 v[244:245], v[196:197], 0, s[2:3]
	v_max_f32_e32 v166, 0, v44
	v_max_f32_e32 v167, 0, v45
	v_max_f32_e32 v168, 0, v46
	v_max_f32_e32 v169, 0, v47
	v_max_f32_e32 v170, 0, v40
	v_max_f32_e32 v171, 0, v41
	v_max_f32_e32 v172, 0, v42
	v_max_f32_e32 v173, 0, v43
	v_pk_mul_f32 v[44:45], v[44:45], v[166:167]
	v_pk_mul_f32 v[46:47], v[46:47], v[168:169]
	v_pk_mul_f32 v[40:41], v[40:41], v[170:171]
	v_pk_mul_f32 v[42:43], v[42:43], v[172:173]
	v_pk_mul_f32 v[44:45], v[44:45], v[218:219] op_sel_hi:[1,0]
	v_pk_mul_f32 v[46:47], v[46:47], v[218:219] op_sel_hi:[1,0]
; __device__ __forceinline__ unsigned cvt_pk_bf16(float lo, float hi) { unsigned r; asm volatile("v_cvt_pk_bf16_f32 %0, %1, %2" : "=v"(r) : "v"(lo), "v"(hi)); return r; }
; #define PG8_BAR __builtin_amdgcn_s_barrier()
; #define GAS __attribute__((address_space(1)))
; template <class Epi, class Sched, bool ALIGN_EPI = false, bool SP2 = false>
; __device__ __forceinline__ void gemm_phase(PG8_LAS unsigned char* lds, const Gemm g, const Sched& S, const Epi& E) {
;     ...
;         if (!has_next) break;
; #pragma unroll
;         for (int a = 0; a < 2; ++a)
; #pragma unroll
;             for (int b = 0; b < 2; ++b)
; #pragma unroll
;                 for (int m = 0; m < 4; ++m)
; #pragma unroll
;                     for (int n = 0; n < 2; ++n) acc[a][b][m][n] = (f32x4){0.f, 0.f, 0.f, 0.f};
;         cur = nxt; cA = nA; cB = nB; ++ui;
;         if constexpr (ALIGN_EPI) { if (wr == 1) PG8_BAR; }
;     DI void operator()(AccRef acc, const pg8::Unit& u, int wr, int wc, int, int) const {
;     ...
;         EPI_ROWS_BEGIN
;             const float rs = rs8[ai * 4 + m];
;             EPI_COLS_BEGIN
;                 {
;                     const f32x4 z4 = {0.f, 0.f, 0.f, 0.f}; const float rs2 = rs * rs;
;                     const f32x4 m0 = __builtin_elementwise_max(v0, z4), m1 = __builtin_elementwise_max(v1, z4);
;                     v0 = (v0 * m0) * rs2; v1 = (v1 * m1) * rs2;
;                 }
;                 u32x4 w; w.x = cvt_pk_bf16(v0[0], v0[1]); w.y = cvt_pk_bf16(v0[2], v0[3]); w.z = cvt_pk_bf16(v1[0], v1[1]); w.w = cvt_pk_bf16(v1[2], v1[3]);
;                 *(GAS u32x4*)(U + (size_t)lrow * UP + col) = w;
;             EPI_END
;         EPI_ROW_END
	v_pk_mul_f32 v[40:41], v[40:41], v[218:219] op_sel_hi:[1,0]
	v_pk_mul_f32 v[42:43], v[42:43], v[218:219] op_sel_hi:[1,0]
	v_cvt_pk_bf16_f32 v174, v44, v45
	v_cvt_pk_bf16_f32 v175, v46, v47
	v_cvt_pk_bf16_f32 v176, v40, v41
	v_cvt_pk_bf16_f32 v177, v42, v43
	global_store_dwordx4 v[244:245], v[174:177], off
	v_max_f32_e32 v166, 0, v36
	v_max_f32_e32 v167, 0, v37
	v_max_f32_e32 v168, 0, v38
	v_max_f32_e32 v169, 0, v39
	v_max_f32_e32 v170, 0, v32
	v_max_f32_e32 v171, 0, v33
	v_max_f32_e32 v172, 0, v34
	v_max_f32_e32 v173, 0, v35
	v_pk_mul_f32 v[36:37], v[36:37], v[166:167]
	v_pk_mul_f32 v[38:39], v[38:39], v[168:169]
	v_pk_mul_f32 v[32:33], v[32:33], v[170:171]
	v_pk_mul_f32 v[34:35], v[34:35], v[172:173]
	v_pk_mul_f32 v[36:37], v[36:37], v[218:219] op_sel_hi:[1,0]
	v_pk_mul_f32 v[38:39], v[38:39], v[218:219] op_sel_hi:[1,0]
	v_pk_mul_f32 v[32:33], v[32:33], v[218:219] op_sel_hi:[1,0]
	v_pk_mul_f32 v[34:35], v[34:35], v[218:219] op_sel_hi:[1,0]
	v_cvt_pk_bf16_f32 v178, v36, v37
	v_cvt_pk_bf16_f32 v179, v38, v39
	v_cvt_pk_bf16_f32 v180, v32, v33
	v_cvt_pk_bf16_f32 v181, v34, v35
	global_store_dwordx4 v[244:245], v[178:181], off offset:256
	v_lshl_add_u64 v[196:197], v[244:245], 0, s[2:3]
	v_max_f32_e32 v166, 0, v28
	v_max_f32_e32 v167, 0, v29
	v_max_f32_e32 v168, 0, v30
	v_max_f32_e32 v169, 0, v31
	v_max_f32_e32 v170, 0, v24
	v_max_f32_e32 v171, 0, v25
	v_max_f32_e32 v172, 0, v26
	v_max_f32_e32 v173, 0, v27
	v_pk_mul_f32 v[28:29], v[28:29], v[166:167]
	v_pk_mul_f32 v[30:31], v[30:31], v[168:169]
	v_pk_mul_f32 v[24:25], v[24:25], v[170:171]
	v_pk_mul_f32 v[26:27], v[26:27], v[172:173]
	v_pk_mul_f32 v[28:29], v[28:29], v[184:185] op_sel_hi:[1,0]
	v_pk_mul_f32 v[30:31], v[30:31], v[184:185] op_sel_hi:[1,0]
	v_pk_mul_f32 v[24:25], v[24:25], v[184:185] op_sel_hi:[1,0]
	v_pk_mul_f32 v[26:27], v[26:27], v[184:185] op_sel_hi:[1,0]
	v_cvt_pk_bf16_f32 v174, v28, v29
	v_cvt_pk_bf16_f32 v175, v30, v31
	v_cvt_pk_bf16_f32 v176, v24, v25
	v_cvt_pk_bf16_f32 v177, v26, v27
	global_store_dwordx4 v[196:197], v[174:177], off
	v_max_f32_e32 v166, 0, v20
	v_max_f32_e32 v167, 0, v21
	v_max_f32_e32 v168, 0, v22
	v_max_f32_e32 v169, 0, v23
	v_max_f32_e32 v170, 0, v16
	v_max_f32_e32 v171, 0, v17
	v_max_f32_e32 v172, 0, v18
	v_max_f32_e32 v173, 0, v19
	v_pk_mul_f32 v[20:21], v[20:21], v[166:167]
	v_pk_mul_f32 v[22:23], v[22:23], v[168:169]
	v_pk_mul_f32 v[16:17], v[16:17], v[170:171]
	v_pk_mul_f32 v[18:19], v[18:19], v[172:173]
	v_pk_mul_f32 v[20:21], v[20:21], v[184:185] op_sel_hi:[1,0]
	v_pk_mul_f32 v[22:23], v[22:23], v[184:185] op_sel_hi:[1,0]
	v_pk_mul_f32 v[16:17], v[16:17], v[184:185] op_sel_hi:[1,0]
	v_pk_mul_f32 v[18:19], v[18:19], v[184:185] op_sel_hi:[1,0]
	v_cvt_pk_bf16_f32 v178, v20, v21
	v_cvt_pk_bf16_f32 v179, v22, v23
	v_cvt_pk_bf16_f32 v180, v16, v17
	v_cvt_pk_bf16_f32 v181, v18, v19
	global_store_dwordx4 v[196:197], v[178:181], off offset:256
	v_lshl_add_u64 v[244:245], v[196:197], 0, s[2:3]
	v_max_f32_e32 v166, 0, v12
	v_max_f32_e32 v167, 0, v13
	v_max_f32_e32 v168, 0, v14
	v_max_f32_e32 v169, 0, v15
	v_max_f32_e32 v170, 0, v8
	v_max_f32_e32 v171, 0, v9
	v_max_f32_e32 v172, 0, v10
	v_max_f32_e32 v173, 0, v11
	v_pk_mul_f32 v[12:13], v[12:13], v[166:167]
	v_pk_mul_f32 v[14:15], v[14:15], v[168:169]
	v_pk_mul_f32 v[8:9], v[8:9], v[170:171]
	v_pk_mul_f32 v[10:11], v[10:11], v[172:173]
	v_pk_mul_f32 v[12:13], v[12:13], v[186:187] op_sel_hi:[1,0]
	v_pk_mul_f32 v[14:15], v[14:15], v[186:187] op_sel_hi:[1,0]
	v_pk_mul_f32 v[8:9], v[8:9], v[186:187] op_sel_hi:[1,0]
	v_pk_mul_f32 v[10:11], v[10:11], v[186:187] op_sel_hi:[1,0]
	v_cvt_pk_bf16_f32 v174, v12, v13
	v_cvt_pk_bf16_f32 v175, v14, v15
	v_cvt_pk_bf16_f32 v176, v8, v9
	v_cvt_pk_bf16_f32 v177, v10, v11
	global_store_dwordx4 v[244:245], v[174:177], off
	v_max_f32_e32 v166, 0, v4
	v_max_f32_e32 v167, 0, v5
	v_max_f32_e32 v168, 0, v6
	v_max_f32_e32 v169, 0, v7
	v_max_f32_e32 v170, 0, v0
	v_max_f32_e32 v171, 0, v1
	v_max_f32_e32 v172, 0, v2
	v_max_f32_e32 v173, 0, v3
	v_pk_mul_f32 v[4:5], v[4:5], v[166:167]
	v_pk_mul_f32 v[6:7], v[6:7], v[168:169]
	v_pk_mul_f32 v[0:1], v[0:1], v[170:171]
	v_pk_mul_f32 v[2:3], v[2:3], v[172:173]
	v_pk_mul_f32 v[4:5], v[4:5], v[186:187] op_sel_hi:[1,0]
	v_pk_mul_f32 v[6:7], v[6:7], v[186:187] op_sel_hi:[1,0]
	v_pk_mul_f32 v[0:1], v[0:1], v[186:187] op_sel_hi:[1,0]
	v_pk_mul_f32 v[2:3], v[2:3], v[186:187] op_sel_hi:[1,0]
	v_cvt_pk_bf16_f32 v178, v4, v5
	v_cvt_pk_bf16_f32 v179, v6, v7
	v_cvt_pk_bf16_f32 v180, v0, v1
	v_cvt_pk_bf16_f32 v181, v2, v3
	global_store_dwordx4 v[244:245], v[178:181], off offset:256
	s_andn2_b64 vcc, exec, s[0:1]
	s_mov_b64 s[4:5], -1
	s_cbranch_vccnz .LBB0_685
	s_andn2_b64 vcc, exec, s[10:11]
	s_cbranch_vccnz .LBB0_684
	s_barrier
	s_branch .LBB0_684

; template <class Epi, class Sched, bool ALIGN_EPI = false, bool SP2 = false>
; __device__ __forceinline__ void gemm_phase(PG8_LAS unsigned char* lds, const Gemm g, const Sched& S, const Epi& E) {
;     ...
; #pragma unroll
;         for (int a = 0; a < 2; ++a)
; #pragma unroll
;             for (int b = 0; b < 2; ++b)
; #pragma unroll
;                 for (int m = 0; m < 4; ++m)
; #pragma unroll
;                     for (int n = 0; n < 2; ++n) acc[a][b][m][n] = (f32x4){0.f, 0.f, 0.f, 0.f};
;         cur = nxt; cA = nA; cB = nB; ++ui;
.LBB0_692:
	s_ashr_i32 s17, s16, 31
	s_lshl_b64 s[2:3], s[16:17], 19
	s_add_u32 s66, s58, s2
	s_addc_u32 s67, s59, s3
	s_and_b64 s[2:3], s[0:1], exec
	s_cselect_b32 s17, s67, s5
	s_cselect_b32 s78, s66, s4
	s_ashr_i32 s15, s14, 31
	s_lshl_b64 s[2:3], s[14:15], 19
	s_add_u32 s82, s38, s2
	s_addc_u32 s83, s41, s3
	s_and_b64 s[2:3], s[0:1], exec
	s_cselect_b32 s15, s83, s85
	s_cselect_b32 s89, s82, s84
	s_add_u32 s90, s84, 0x100
	s_addc_u32 s91, s85, 0
	s_add_u32 s4, s4, 0x40080
	v_mov_b32_e32 v0, 0
	s_addc_u32 s5, s5, 0
	s_mov_b32 s92, -2
	v_mov_b32_e32 v1, v0
	v_mov_b32_e32 v2, v0
	v_mov_b32_e32 v3, v0
	v_mov_b32_e32 v4, v0
	v_mov_b32_e32 v5, v0
	v_mov_b32_e32 v6, v0
	v_mov_b32_e32 v7, v0
	v_mov_b32_e32 v16, v0
	v_mov_b32_e32 v17, v0
	v_mov_b32_e32 v18, v0
	v_mov_b32_e32 v19, v0
	v_mov_b32_e32 v20, v0
	v_mov_b32_e32 v21, v0
	v_mov_b32_e32 v22, v0
	v_mov_b32_e32 v23, v0
	v_mov_b32_e32 v32, v0
	v_mov_b32_e32 v33, v0
	v_mov_b32_e32 v34, v0
	v_mov_b32_e32 v35, v0
	v_mov_b32_e32 v36, v0
	v_mov_b32_e32 v37, v0
	v_mov_b32_e32 v38, v0
	v_mov_b32_e32 v39, v0
	v_mov_b32_e32 v48, v0
	v_mov_b32_e32 v49, v0
	v_mov_b32_e32 v50, v0
	v_mov_b32_e32 v51, v0
	v_mov_b32_e32 v52, v0
	v_mov_b32_e32 v53, v0
	v_mov_b32_e32 v54, v0
	v_mov_b32_e32 v55, v0
	v_mov_b32_e32 v8, v0
	v_mov_b32_e32 v9, v0
	v_mov_b32_e32 v10, v0
	v_mov_b32_e32 v11, v0
	v_mov_b32_e32 v12, v0
	v_mov_b32_e32 v13, v0
	v_mov_b32_e32 v14, v0
	v_mov_b32_e32 v15, v0
	v_mov_b32_e32 v24, v0
	v_mov_b32_e32 v25, v0
	v_mov_b32_e32 v26, v0
	v_mov_b32_e32 v27, v0
	v_mov_b32_e32 v28, v0
	v_mov_b32_e32 v29, v0
	v_mov_b32_e32 v30, v0
	v_mov_b32_e32 v31, v0
	v_mov_b32_e32 v40, v0
	v_mov_b32_e32 v41, v0
	v_mov_b32_e32 v42, v0
	v_mov_b32_e32 v43, v0
	v_mov_b32_e32 v44, v0
	v_mov_b32_e32 v45, v0
	v_mov_b32_e32 v46, v0
	v_mov_b32_e32 v47, v0
	v_mov_b32_e32 v56, v0
	v_mov_b32_e32 v57, v0
	v_mov_b32_e32 v58, v0
	v_mov_b32_e32 v59, v0
	v_mov_b32_e32 v60, v0
	v_mov_b32_e32 v61, v0
	v_mov_b32_e32 v62, v0
	v_mov_b32_e32 v63, v0
	s_waitcnt vmcnt(0)
	v_mov_b32_e32 v64, v0
	v_mov_b32_e32 v65, v0
	v_mov_b32_e32 v66, v0
	v_mov_b32_e32 v67, v0
	v_mov_b32_e32 v68, v0
	v_mov_b32_e32 v69, v0
	v_mov_b32_e32 v70, v0
	v_mov_b32_e32 v71, v0
	v_mov_b32_e32 v80, v0
	v_mov_b32_e32 v81, v0
	v_mov_b32_e32 v82, v0
	v_mov_b32_e32 v83, v0
	v_mov_b32_e32 v84, v0
	v_mov_b32_e32 v85, v0
	v_mov_b32_e32 v86, v0
	v_mov_b32_e32 v87, v0
	v_mov_b32_e32 v96, v0
	v_mov_b32_e32 v97, v0
	v_mov_b32_e32 v98, v0
	v_mov_b32_e32 v99, v0
	v_mov_b32_e32 v100, v0
	v_mov_b32_e32 v101, v0
	v_mov_b32_e32 v102, v0
	v_mov_b32_e32 v103, v0
	v_mov_b32_e32 v112, v0
	v_mov_b32_e32 v113, v0
	v_mov_b32_e32 v114, v0
	v_mov_b32_e32 v115, v0
	v_mov_b32_e32 v116, v0
	v_mov_b32_e32 v117, v0
	v_mov_b32_e32 v118, v0
	v_mov_b32_e32 v119, v0
	v_mov_b32_e32 v72, v0
	v_mov_b32_e32 v73, v0
	v_mov_b32_e32 v74, v0
	v_mov_b32_e32 v75, v0
	v_mov_b32_e32 v76, v0
	v_mov_b32_e32 v77, v0
	v_mov_b32_e32 v78, v0
	v_mov_b32_e32 v79, v0
	v_mov_b32_e32 v88, v0
	v_mov_b32_e32 v89, v0
	v_mov_b32_e32 v90, v0
	v_mov_b32_e32 v91, v0
	v_mov_b32_e32 v92, v0
	v_mov_b32_e32 v93, v0
	v_mov_b32_e32 v94, v0
	v_mov_b32_e32 v95, v0
	v_mov_b32_e32 v104, v0
	v_mov_b32_e32 v105, v0
	v_mov_b32_e32 v106, v0
	v_mov_b32_e32 v107, v0
	v_mov_b32_e32 v108, v0
	v_mov_b32_e32 v109, v0
	v_mov_b32_e32 v110, v0
	v_mov_b32_e32 v111, v0
	v_mov_b32_e32 v120, v0
	v_mov_b32_e32 v121, v0
	v_mov_b32_e32 v122, v0
	v_mov_b32_e32 v123, v0
	v_mov_b32_e32 v124, v0
	v_mov_b32_e32 v125, v0
	v_mov_b32_e32 v126, v0
	v_mov_b32_e32 v127, v0
	v_mbcnt_lo_u32_b32 v220, -1, 0
	v_mbcnt_hi_u32_b32 v220, -1, v220
	v_and_b32_e32 v221, 15, v220
	v_lshrrev_b32_e32 v220, 4, v220
	v_or_b32_e32 v221, s49, v221
	v_lshl_add_u32 v221, s88, 8, v221
	v_lshlrev_b32_e32 v220, 4, v220
	v_lshl_add_u32 v220, v221, 6, v220
	v_mov_b32_e32 v221, 0
	v_lshl_add_u64 v[222:223], s[60:61], 0, v[220:221]
	global_load_dwordx4 v[224:227], v[222:223], off
	global_load_dwordx4 v[228:231], v[222:223], off offset:1024
	global_load_dwordx4 v[232:235], v[222:223], off offset:2048
	global_load_dwordx4 v[236:239], v[222:223], off offset:3072

; DI int lane_id_opaque() { int l; asm volatile("v_mbcnt_lo_u32_b32 %0, -1, 0\n\tv_mbcnt_hi_u32_b32 %0, -1, %0" : "=v"(l)); return l; }
;     DI void operator()(AccRef acc, const pg8::Unit& u, int wr, int wc, int, int) const {
;         const int lane_ = lane_id_opaque(), fr = lane_ & 15, fq = lane_ >> 4;
;         EPI_PRELOAD_RSTD(ssq)
.LBB0_696:
	s_branch .Llean_C_entry
	s_lshl_b32 s2, s88, 8
	v_mbcnt_lo_u32_b32 v128, -1, 0
	v_mbcnt_hi_u32_b32 v128, -1, v128
	s_add_i32 s2, s2, s49
	v_ashrrev_i32_e32 v184, 4, v128
	v_and_or_b32 v180, v128, 15, s2
	v_lshlrev_b32_e32 v128, 2, v184
	v_ashrrev_i32_e32 v129, 31, v128
	v_ashrrev_i32_e32 v181, 31, v180
	v_lshl_add_u64 v[128:129], v[128:129], 2, s[60:61]
	v_lshlrev_b64 v[130:131], 6, v[180:181]
	v_lshl_add_u64 v[130:131], v[128:129], 0, v[130:131]
	global_load_dwordx4 v[186:189], v[130:131], off
	v_or_b32_e32 v178, 16, v180
	v_ashrrev_i32_e32 v179, 31, v178
	v_lshlrev_b64 v[130:131], 6, v[178:179]
	v_lshl_add_u64 v[130:131], v[128:129], 0, v[130:131]
	global_load_dwordx4 v[152:155], v[130:131], off
	v_or_b32_e32 v176, 32, v180
	v_ashrrev_i32_e32 v177, 31, v176
	v_lshlrev_b64 v[130:131], 6, v[176:177]
	v_lshl_add_u64 v[130:131], v[128:129], 0, v[130:131]
	global_load_dwordx4 v[148:151], v[130:131], off
	v_or_b32_e32 v174, 48, v180
	v_ashrrev_i32_e32 v175, 31, v174
	v_lshlrev_b64 v[130:131], 6, v[174:175]
	v_add_u32_e32 v172, 0x80, v180
	v_lshl_add_u64 v[130:131], v[128:129], 0, v[130:131]
	v_ashrrev_i32_e32 v173, 31, v172
	global_load_dwordx4 v[144:147], v[130:131], off
	v_lshlrev_b64 v[130:131], 6, v[172:173]
	v_add_u32_e32 v170, 0x90, v180
	v_lshl_add_u64 v[130:131], v[128:129], 0, v[130:131]
	v_ashrrev_i32_e32 v171, 31, v170
	global_load_dwordx4 v[140:143], v[130:131], off
	v_lshlrev_b64 v[130:131], 6, v[170:171]
	v_add_u32_e32 v168, 0xa0, v180
	v_lshl_add_u64 v[130:131], v[128:129], 0, v[130:131]
	v_ashrrev_i32_e32 v169, 31, v168
	global_load_dwordx4 v[136:139], v[130:131], off
	v_lshlrev_b64 v[130:131], 6, v[168:169]
	v_add_u32_e32 v166, 0xb0, v180
	v_lshl_add_u64 v[130:131], v[128:129], 0, v[130:131]
	v_ashrrev_i32_e32 v167, 31, v166
	global_load_dwordx4 v[132:135], v[130:131], off
	v_lshlrev_b64 v[130:131], 6, v[166:167]
	v_lshl_add_u64 v[128:129], v[128:129], 0, v[130:131]
	global_load_dwordx4 v[128:131], v[128:129], off
	s_waitcnt vmcnt(0)
	v_add_f32_e32 v167, v186, v187
	v_add_f32_e32 v169, v188, v189
	v_add_f32_e32 v167, v167, v169
	ds_swizzle_b32 v169, v167 offset:swizzle(SWAP,16)
	v_add_f32_e32 v152, v152, v153
	v_add_f32_e32 v153, v154, v155
	v_add_f32_e32 v152, v152, v153
	s_waitcnt lgkmcnt(0)
	v_add_f32_e32 v167, v167, v169
	v_mov_b32_e32 v169, v167
	s_nop 1
	v_permlane32_swap_b32_e32 v167, v169
	v_add_f32_e32 v167, v167, v169
	v_fmamk_f32 v167, v167, 0x3a800000, v246
	v_cmp_gt_f32_e32 vcc, s33, v167
	v_mul_f32_e32 v169, 0x4f800000, v167
	ds_swizzle_b32 v153, v152 offset:swizzle(SWAP,16)
	v_cndmask_b32_e32 v167, v167, v169, vcc
	v_sqrt_f32_e32 v169, v167
	v_add_f32_e32 v148, v148, v149
	v_add_f32_e32 v149, v150, v151
	s_waitcnt lgkmcnt(0)
	v_add_f32_e32 v152, v152, v153
	v_add_u32_e32 v171, -1, v169
	v_fma_f32 v173, -v171, v169, v167
	v_cmp_ge_f32_e64 s[4:5], 0, v173
	v_add_u32_e32 v173, 1, v169
	v_mov_b32_e32 v153, v152
	v_cndmask_b32_e64 v171, v169, v171, s[4:5]
	v_fma_f32 v169, -v173, v169, v167
	v_cmp_lt_f32_e64 s[4:5], 0, v169
	v_permlane32_swap_b32_e32 v152, v153
	s_nop 0
	v_cndmask_b32_e64 v169, v171, v173, s[4:5]
	v_mul_f32_e32 v171, 0x37800000, v169
	v_cndmask_b32_e32 v169, v169, v171, vcc
	v_cmp_class_f32_e32 vcc, v167, v252
	v_add_f32_e32 v152, v152, v153
	v_fmamk_f32 v152, v152, 0x3a800000, v246
	v_cndmask_b32_e32 v167, v169, v167, vcc
	v_div_scale_f32 v169, s[2:3], v167, v167, 1.0
	v_rcp_f32_e32 v171, v169
	v_mul_f32_e32 v153, 0x4f800000, v152
	v_add_f32_e32 v148, v148, v149
	ds_swizzle_b32 v149, v148 offset:swizzle(SWAP,16)
	v_fma_f32 v173, -v169, v171, 1.0
	v_fmac_f32_e32 v171, v173, v171
	v_div_scale_f32 v173, vcc, 1.0, v167, 1.0
	v_mul_f32_e32 v175, v173, v171
	v_fma_f32 v177, -v169, v175, v173
	v_fmac_f32_e32 v175, v177, v171
	v_fma_f32 v169, -v169, v175, v173
	v_div_fmas_f32 v169, v169, v171, v175
	v_cmp_gt_f32_e32 vcc, s33, v152
	s_waitcnt lgkmcnt(0)
	v_add_f32_e32 v148, v148, v149
	v_div_fixup_f32 v167, v169, v167, 1.0
	v_cndmask_b32_e32 v152, v152, v153, vcc
	v_sqrt_f32_e32 v153, v152
	v_mov_b32_e32 v149, v148
	s_nop 1
	v_permlane32_swap_b32_e32 v148, v149
	v_add_u32_e32 v154, -1, v153
	v_fma_f32 v155, -v154, v153, v152
	v_cmp_ge_f32_e64 s[4:5], 0, v155
	v_add_u32_e32 v155, 1, v153
	v_add_f32_e32 v148, v148, v149
	v_cndmask_b32_e64 v154, v153, v154, s[4:5]
	v_fma_f32 v153, -v155, v153, v152
	v_cmp_lt_f32_e64 s[4:5], 0, v153
	v_fmamk_f32 v148, v148, 0x3a800000, v246
	v_mul_f32_e32 v149, 0x4f800000, v148
	v_cndmask_b32_e64 v153, v154, v155, s[4:5]
	v_mul_f32_e32 v154, 0x37800000, v153
	v_cndmask_b32_e32 v153, v153, v154, vcc
	v_cmp_class_f32_e32 vcc, v152, v252
	v_add_f32_e32 v144, v144, v145
	v_add_f32_e32 v145, v146, v147
	v_cndmask_b32_e32 v152, v153, v152, vcc
	v_div_scale_f32 v153, s[2:3], v152, v152, 1.0
	v_rcp_f32_e32 v154, v153
	v_add_f32_e32 v144, v144, v145
	ds_swizzle_b32 v145, v144 offset:swizzle(SWAP,16)
	v_add_f32_e32 v140, v140, v141
	v_fma_f32 v155, -v153, v154, 1.0
	v_fmac_f32_e32 v154, v155, v154
	v_div_scale_f32 v155, vcc, 1.0, v152, 1.0
	v_mul_f32_e32 v169, v155, v154
	v_fma_f32 v171, -v153, v169, v155
	v_fmac_f32_e32 v169, v171, v154
	v_fma_f32 v153, -v153, v169, v155
	v_div_fmas_f32 v153, v153, v154, v169
	v_cmp_gt_f32_e32 vcc, s33, v148
	s_waitcnt lgkmcnt(0)
	v_add_f32_e32 v144, v144, v145
	v_div_fixup_f32 v152, v153, v152, 1.0
	v_cndmask_b32_e32 v148, v148, v149, vcc
	v_sqrt_f32_e32 v149, v148
	v_mov_b32_e32 v145, v144
	s_nop 1
	v_permlane32_swap_b32_e32 v144, v145
	v_add_u32_e32 v150, -1, v149
	v_fma_f32 v151, -v150, v149, v148
	v_cmp_ge_f32_e64 s[4:5], 0, v151
	v_add_u32_e32 v151, 1, v149
	v_add_f32_e32 v144, v144, v145
	v_cndmask_b32_e64 v150, v149, v150, s[4:5]
	v_fma_f32 v149, -v151, v149, v148
	v_cmp_lt_f32_e64 s[4:5], 0, v149
	v_fmamk_f32 v144, v144, 0x3a800000, v246
	v_mul_f32_e32 v145, 0x4f800000, v144
	v_cndmask_b32_e64 v149, v150, v151, s[4:5]
	v_mul_f32_e32 v150, 0x37800000, v149
	v_cndmask_b32_e32 v149, v149, v150, vcc
	v_cmp_class_f32_e32 vcc, v148, v252
	v_add_f32_e32 v141, v142, v143
	v_add_f32_e32 v140, v140, v141
	v_cndmask_b32_e32 v148, v149, v148, vcc
	v_div_scale_f32 v149, s[2:3], v148, v148, 1.0
	v_rcp_f32_e32 v150, v149
	ds_swizzle_b32 v141, v140 offset:swizzle(SWAP,16)
	v_add_f32_e32 v136, v136, v137
	v_add_f32_e32 v137, v138, v139
	v_fma_f32 v151, -v149, v150, 1.0
	v_fmac_f32_e32 v150, v151, v150
	v_div_scale_f32 v151, vcc, 1.0, v148, 1.0
	v_mul_f32_e32 v153, v151, v150
	v_fma_f32 v154, -v149, v153, v151
	v_fmac_f32_e32 v153, v154, v150
	v_fma_f32 v149, -v149, v153, v151
	v_div_fmas_f32 v149, v149, v150, v153
	v_cmp_gt_f32_e32 vcc, s33, v144
	s_waitcnt lgkmcnt(0)
	v_add_f32_e32 v140, v140, v141
	v_div_fixup_f32 v148, v149, v148, 1.0
	v_cndmask_b32_e32 v144, v144, v145, vcc
	v_sqrt_f32_e32 v145, v144
	v_mov_b32_e32 v141, v140
	s_nop 1
	v_permlane32_swap_b32_e32 v140, v141
	v_add_u32_e32 v146, -1, v145
	v_fma_f32 v147, -v146, v145, v144
	v_cmp_ge_f32_e64 s[4:5], 0, v147
	v_add_u32_e32 v147, 1, v145
	v_add_f32_e32 v140, v140, v141
	v_cndmask_b32_e64 v146, v145, v146, s[4:5]
	v_fma_f32 v145, -v147, v145, v144
	v_cmp_lt_f32_e64 s[4:5], 0, v145
	v_fmamk_f32 v140, v140, 0x3a800000, v246
	v_mul_f32_e32 v141, 0x4f800000, v140
	v_cndmask_b32_e64 v145, v146, v147, s[4:5]
	v_mul_f32_e32 v146, 0x37800000, v145
	v_cndmask_b32_e32 v145, v145, v146, vcc
	v_cmp_class_f32_e32 vcc, v144, v252
	v_add_f32_e32 v136, v136, v137
	ds_swizzle_b32 v137, v136 offset:swizzle(SWAP,16)
	v_cndmask_b32_e32 v144, v145, v144, vcc
	v_div_scale_f32 v145, s[2:3], v144, v144, 1.0
	v_rcp_f32_e32 v146, v145
	s_waitcnt lgkmcnt(0)
	v_add_f32_e32 v136, v136, v137
	v_mov_b32_e32 v137, v136
	s_nop 1
	v_permlane32_swap_b32_e32 v136, v137
	v_fma_f32 v147, -v145, v146, 1.0
	v_fmac_f32_e32 v146, v147, v146
	v_div_scale_f32 v147, vcc, 1.0, v144, 1.0
	v_mul_f32_e32 v149, v147, v146
	v_fma_f32 v150, -v145, v149, v147
	v_fmac_f32_e32 v149, v150, v146
	v_fma_f32 v145, -v145, v149, v147
	v_div_fmas_f32 v145, v145, v146, v149
	v_cmp_gt_f32_e32 vcc, s33, v140
	v_div_fixup_f32 v144, v145, v144, 1.0
	v_add_f32_e32 v136, v136, v137
	v_cndmask_b32_e32 v140, v140, v141, vcc
	v_sqrt_f32_e32 v141, v140
	v_fmamk_f32 v136, v136, 0x3a800000, v246
	v_mul_f32_e32 v137, 0x4f800000, v136
	v_add_f32_e32 v132, v132, v133
	v_add_u32_e32 v142, -1, v141
	v_fma_f32 v143, -v142, v141, v140
	v_cmp_ge_f32_e64 s[4:5], 0, v143
	v_add_u32_e32 v143, 1, v141
	v_add_f32_e32 v133, v134, v135
	v_cndmask_b32_e64 v142, v141, v142, s[4:5]
	v_fma_f32 v141, -v143, v141, v140
	v_cmp_lt_f32_e64 s[4:5], 0, v141
	v_add_f32_e32 v132, v132, v133
	ds_swizzle_b32 v133, v132 offset:swizzle(SWAP,16)
	v_cndmask_b32_e64 v141, v142, v143, s[4:5]
	v_mul_f32_e32 v142, 0x37800000, v141
	v_cndmask_b32_e32 v141, v141, v142, vcc
	v_cmp_class_f32_e32 vcc, v140, v252
	s_waitcnt lgkmcnt(0)
	v_add_f32_e32 v132, v132, v133
	v_mov_b32_e32 v133, v132
	v_cndmask_b32_e32 v140, v141, v140, vcc
	v_div_scale_f32 v141, s[2:3], v140, v140, 1.0
	v_rcp_f32_e32 v142, v141
	v_permlane32_swap_b32_e32 v132, v133
	v_add_f32_e32 v132, v132, v133
	v_fma_f32 v143, -v141, v142, 1.0
	v_fmac_f32_e32 v142, v143, v142
	v_div_scale_f32 v143, vcc, 1.0, v140, 1.0
	v_mul_f32_e32 v145, v143, v142
	v_fma_f32 v146, -v141, v145, v143
	v_fmac_f32_e32 v145, v146, v142
	v_fma_f32 v141, -v141, v145, v143
	v_div_fmas_f32 v141, v141, v142, v145
	v_cmp_gt_f32_e32 vcc, s33, v136
	v_div_fixup_f32 v140, v141, v140, 1.0
	v_fmamk_f32 v132, v132, 0x3a800000, v246
	v_cndmask_b32_e32 v136, v136, v137, vcc
	v_sqrt_f32_e32 v137, v136
	v_mul_f32_e32 v133, 0x4f800000, v132
	v_add_f32_e32 v128, v128, v129
	v_add_f32_e32 v129, v130, v131
	v_add_u32_e32 v138, -1, v137
	v_fma_f32 v139, -v138, v137, v136
	v_cmp_ge_f32_e64 s[4:5], 0, v139
	v_add_u32_e32 v139, 1, v137
	v_add_f32_e32 v128, v128, v129
	v_cndmask_b32_e64 v138, v137, v138, s[4:5]
	v_fma_f32 v137, -v139, v137, v136
	v_cmp_lt_f32_e64 s[4:5], 0, v137
	ds_swizzle_b32 v129, v128 offset:swizzle(SWAP,16)
	s_waitcnt lgkmcnt(0)
; __device__ __forceinline__ unsigned cvt_pk_bf16(float lo, float hi) { unsigned r; asm volatile("v_cvt_pk_bf16_f32 %0, %1, %2" : "=v"(r) : "v"(lo), "v"(hi)); return r; }
; #define GAS __attribute__((address_space(1)))
;     DI void operator()(AccRef acc, const pg8::Unit& u, int wr, int wc, int, int) const {
;     ...
;         EPI_ROWS_BEGIN
;             const float rs = rs8[ai * 4 + m];
;             EPI_COLS_BEGIN
;                 {
;                     const f32x4 z4 = {0.f, 0.f, 0.f, 0.f}; const float rs2 = rs * rs;
;                     const f32x4 m0 = __builtin_elementwise_max(v0, z4), m1 = __builtin_elementwise_max(v1, z4);
;                     v0 = (v0 * m0) * rs2; v1 = (v1 * m1) * rs2;
;                 }
;                 u32x4 w; w.x = cvt_pk_bf16(v0[0], v0[1]); w.y = cvt_pk_bf16(v0[2], v0[3]); w.z = cvt_pk_bf16(v1[0], v1[1]); w.w = cvt_pk_bf16(v1[2], v1[3]);
;                 *(GAS u32x4*)(U + (size_t)lrow * UP + col) = w;
	v_add_f32_e32 v128, v128, v129
	v_cndmask_b32_e64 v137, v138, v139, s[4:5]
	v_mul_f32_e32 v138, 0x37800000, v137
	v_cndmask_b32_e32 v137, v137, v138, vcc
	v_cmp_class_f32_e32 vcc, v136, v252
	v_mov_b32_e32 v129, v128
	s_nop 1
	v_permlane32_swap_b32_e32 v128, v129
	v_cndmask_b32_e32 v136, v137, v136, vcc
	v_div_scale_f32 v137, s[2:3], v136, v136, 1.0
	v_rcp_f32_e32 v138, v137
	v_add_f32_e32 v128, v128, v129
	v_fmamk_f32 v128, v128, 0x3a800000, v246
	v_mul_f32_e32 v129, 0x4f800000, v128
	v_fma_f32 v139, -v137, v138, 1.0
	v_fmac_f32_e32 v138, v139, v138
	v_div_scale_f32 v139, vcc, 1.0, v136, 1.0
	v_mul_f32_e32 v141, v139, v138
	v_fma_f32 v142, -v137, v141, v139
	v_fmac_f32_e32 v141, v142, v138
	v_fma_f32 v137, -v137, v141, v139
	v_div_fmas_f32 v137, v137, v138, v141
	v_cmp_gt_f32_e32 vcc, s33, v132
	v_div_fixup_f32 v136, v137, v136, 1.0
	s_nop 0
	v_cndmask_b32_e32 v132, v132, v133, vcc
	v_sqrt_f32_e32 v133, v132
	s_nop 0
	v_add_u32_e32 v134, -1, v133
	v_fma_f32 v135, -v134, v133, v132
	v_cmp_ge_f32_e64 s[4:5], 0, v135
	v_add_u32_e32 v135, 1, v133
	s_nop 0
	v_cndmask_b32_e64 v134, v133, v134, s[4:5]
	v_fma_f32 v133, -v135, v133, v132
	v_cmp_lt_f32_e64 s[4:5], 0, v133
	s_nop 1
	v_cndmask_b32_e64 v133, v134, v135, s[4:5]
	v_mul_f32_e32 v134, 0x37800000, v133
	v_cndmask_b32_e32 v133, v133, v134, vcc
	v_cmp_class_f32_e32 vcc, v132, v252
	s_nop 1
	v_cndmask_b32_e32 v132, v133, v132, vcc
	v_div_scale_f32 v133, s[2:3], v132, v132, 1.0
	v_rcp_f32_e32 v134, v133
	s_nop 0
	v_fma_f32 v135, -v133, v134, 1.0
	v_fmac_f32_e32 v134, v135, v134
	v_div_scale_f32 v135, vcc, 1.0, v132, 1.0
	v_mul_f32_e32 v137, v135, v134
	v_fma_f32 v138, -v133, v137, v135
	v_fmac_f32_e32 v137, v138, v134
	v_fma_f32 v133, -v133, v137, v135
	v_div_fmas_f32 v133, v133, v134, v137
	v_cmp_gt_f32_e32 vcc, s33, v128
	v_div_fixup_f32 v132, v133, v132, 1.0
	s_nop 0
	v_cndmask_b32_e32 v128, v128, v129, vcc
	v_sqrt_f32_e32 v129, v128
	s_nop 0
	v_add_u32_e32 v130, -1, v129
	v_fma_f32 v131, -v130, v129, v128
	v_cmp_ge_f32_e64 s[4:5], 0, v131
	v_add_u32_e32 v131, 1, v129
	s_nop 0
	v_cndmask_b32_e64 v130, v129, v130, s[4:5]
	v_fma_f32 v129, -v131, v129, v128
	v_cmp_lt_f32_e64 s[4:5], 0, v129
	s_nop 1
	v_cndmask_b32_e64 v129, v130, v131, s[4:5]
	v_mul_f32_e32 v130, 0x37800000, v129
	v_cndmask_b32_e32 v129, v129, v130, vcc
	v_cmp_class_f32_e32 vcc, v128, v252
	s_mov_b64 s[4:5], -1
	s_nop 0
	v_cndmask_b32_e32 v128, v129, v128, vcc
	v_div_scale_f32 v129, s[2:3], v128, v128, 1.0
	v_rcp_f32_e32 v130, v129
	s_lshl_b32 s2, s80, 8
	s_or_b32 s2, s2, s62
	v_fma_f32 v131, -v129, v130, 1.0
	v_fmac_f32_e32 v130, v131, v130
	v_div_scale_f32 v131, vcc, 1.0, v128, 1.0
	v_mul_f32_e32 v133, v131, v130
	v_fma_f32 v134, -v129, v133, v131
	v_fmac_f32_e32 v133, v134, v130
	v_fma_f32 v129, -v129, v133, v131
	v_div_fmas_f32 v129, v129, v130, v133
	v_div_fixup_f32 v128, v129, v128, 1.0
	v_max_f32_e32 v129, v127, v127
	v_max_f32_e32 v139, 0, v129
	v_max_f32_e32 v129, v126, v126
	v_max_f32_e32 v138, 0, v129
	v_max_f32_e32 v129, v125, v125
	v_max_f32_e32 v143, 0, v129
	v_max_f32_e32 v129, v124, v124
	v_max_f32_e32 v142, 0, v129
	v_max_f32_e32 v129, v123, v123
	v_max_f32_e32 v147, 0, v129
	v_max_f32_e32 v129, v122, v122
	v_max_f32_e32 v146, 0, v129
	v_max_f32_e32 v129, v121, v121
	v_max_f32_e32 v151, 0, v129
	v_max_f32_e32 v129, v120, v120
	v_max_f32_e32 v150, 0, v129
	v_lshl_add_u32 v130, v184, 3, s2
	v_mul_f32_e32 v134, v167, v167
	v_pk_mul_f32 v[124:125], v[124:125], v[142:143]
	v_pk_mul_f32 v[126:127], v[126:127], v[138:139]
	v_pk_mul_f32 v[120:121], v[120:121], v[150:151]
	v_readlane_b32 s2, v253, 51
	v_pk_mul_f32 v[126:127], v[126:127], v[134:135] op_sel_hi:[1,0]
	v_pk_mul_f32 v[124:125], v[124:125], v[134:135] op_sel_hi:[1,0]
	v_pk_mul_f32 v[122:123], v[122:123], v[146:147]
	v_pk_mul_f32 v[120:121], v[120:121], v[134:135] op_sel_hi:[1,0]
	v_readlane_b32 s3, v253, 52
	v_pk_mul_f32 v[122:123], v[122:123], v[134:135] op_sel_hi:[1,0]
	v_cvt_pk_bf16_f32 v124, v124, v125
	v_cvt_pk_bf16_f32 v125, v126, v127
	v_cvt_pk_bf16_f32 v126, v120, v121
	v_ashrrev_i32_e32 v131, 31, v130
	v_mov_b64_e32 v[120:121], s[2:3]
	v_cvt_pk_bf16_f32 v127, v122, v123
	v_mad_i64_i32 v[138:139], s[2:3], v180, s43, v[120:121]
	v_lshlrev_b64 v[122:123], 1, v[130:131]
	v_max_f32_e32 v129, v115, v115
	v_lshl_add_u64 v[130:131], v[138:139], 0, v[122:123]
	v_max_f32_e32 v139, 0, v129
	v_max_f32_e32 v129, v114, v114
	global_store_dwordx4 v[130:131], v[124:127], off
	v_max_f32_e32 v138, 0, v129
	v_max_f32_e32 v129, v113, v113
	v_max_f32_e32 v124, v119, v119
	v_max_f32_e32 v126, v117, v117
	v_max_f32_e32 v125, 0, v124
	v_max_f32_e32 v124, v118, v118
	v_max_f32_e32 v127, 0, v126
	v_max_f32_e32 v126, v116, v116
	v_max_f32_e32 v143, 0, v129
	v_max_f32_e32 v129, v112, v112
	v_max_f32_e32 v124, 0, v124
	v_max_f32_e32 v126, 0, v126
	v_max_f32_e32 v142, 0, v129
	v_pk_mul_f32 v[116:117], v[116:117], v[126:127]
	v_pk_mul_f32 v[118:119], v[118:119], v[124:125]
	v_pk_mul_f32 v[112:113], v[112:113], v[142:143]
	v_pk_mul_f32 v[114:115], v[114:115], v[138:139]
	v_pk_mul_f32 v[118:119], v[118:119], v[134:135] op_sel_hi:[1,0]
	v_pk_mul_f32 v[116:117], v[116:117], v[134:135] op_sel_hi:[1,0]
	v_pk_mul_f32 v[124:125], v[114:115], v[134:135] op_sel_hi:[1,0]
	v_pk_mul_f32 v[114:115], v[112:113], v[134:135] op_sel_hi:[1,0]
	v_cvt_pk_bf16_f32 v112, v116, v117
	v_cvt_pk_bf16_f32 v113, v118, v119
	s_andn2_b64 vcc, exec, s[0:1]
	v_cvt_pk_bf16_f32 v114, v114, v115
	v_cvt_pk_bf16_f32 v115, v124, v125
	global_store_dwordx4 v[130:131], v[112:115], off offset:256
	s_nop 1
	v_max_f32_e32 v113, v111, v111
	v_max_f32_e32 v115, 0, v113
	v_max_f32_e32 v113, v110, v110
	v_max_f32_e32 v114, 0, v113
; __device__ __forceinline__ unsigned cvt_pk_bf16(float lo, float hi) { unsigned r; asm volatile("v_cvt_pk_bf16_f32 %0, %1, %2" : "=v"(r) : "v"(lo), "v"(hi)); return r; }
; #define GAS __attribute__((address_space(1)))
;     DI void operator()(AccRef acc, const pg8::Unit& u, int wr, int wc, int, int) const {
;     ...
;         EPI_ROWS_BEGIN
;             const float rs = rs8[ai * 4 + m];
;             EPI_COLS_BEGIN
;                 {
;                     const f32x4 z4 = {0.f, 0.f, 0.f, 0.f}; const float rs2 = rs * rs;
;                     const f32x4 m0 = __builtin_elementwise_max(v0, z4), m1 = __builtin_elementwise_max(v1, z4);
;                     v0 = (v0 * m0) * rs2; v1 = (v1 * m1) * rs2;
;                 }
;                 u32x4 w; w.x = cvt_pk_bf16(v0[0], v0[1]); w.y = cvt_pk_bf16(v0[2], v0[3]); w.z = cvt_pk_bf16(v1[0], v1[1]); w.w = cvt_pk_bf16(v1[2], v1[3]);
;                 *(GAS u32x4*)(U + (size_t)lrow * UP + col) = w;
;             EPI_END
;         EPI_ROW_END
	v_max_f32_e32 v113, v109, v109
	v_max_f32_e32 v117, 0, v113
	v_max_f32_e32 v113, v108, v108
	v_max_f32_e32 v116, 0, v113
	v_max_f32_e32 v113, v107, v107
	v_max_f32_e32 v119, 0, v113
	v_max_f32_e32 v113, v106, v106
	v_max_f32_e32 v118, 0, v113
	v_max_f32_e32 v113, v105, v105
	v_max_f32_e32 v125, 0, v113
	v_max_f32_e32 v113, v104, v104
	v_mul_f32_e32 v112, v152, v152
	v_max_f32_e32 v124, 0, v113
	v_pk_mul_f32 v[108:109], v[108:109], v[116:117]
	v_pk_mul_f32 v[104:105], v[104:105], v[124:125]
	v_pk_mul_f32 v[108:109], v[108:109], v[112:113] op_sel_hi:[1,0]
	v_pk_mul_f32 v[106:107], v[106:107], v[118:119]
	v_pk_mul_f32 v[110:111], v[110:111], v[114:115]
	v_pk_mul_f32 v[114:115], v[106:107], v[112:113] op_sel_hi:[1,0]
	v_pk_mul_f32 v[106:107], v[104:105], v[112:113] op_sel_hi:[1,0]
	v_cvt_pk_bf16_f32 v104, v108, v109
	v_mad_i64_i32 v[108:109], s[2:3], v178, s43, v[120:121]
	v_pk_mul_f32 v[110:111], v[110:111], v[112:113] op_sel_hi:[1,0]
	v_lshl_add_u64 v[108:109], v[108:109], 0, v[122:123]
	v_cvt_pk_bf16_f32 v105, v110, v111
	v_cvt_pk_bf16_f32 v106, v106, v107
	v_cvt_pk_bf16_f32 v107, v114, v115
	global_store_dwordx4 v[108:109], v[104:107], off
	v_max_f32_e32 v110, v99, v99
	v_max_f32_e32 v113, v97, v97
	v_max_f32_e32 v104, v103, v103
	v_max_f32_e32 v106, v101, v101
	v_max_f32_e32 v105, 0, v104
	v_max_f32_e32 v104, v102, v102
	v_max_f32_e32 v107, 0, v106
	v_max_f32_e32 v106, v100, v100
	v_max_f32_e32 v111, 0, v110
	v_max_f32_e32 v110, v98, v98
	v_max_f32_e32 v115, 0, v113
	v_max_f32_e32 v113, v96, v96
	v_max_f32_e32 v104, 0, v104
	v_max_f32_e32 v106, 0, v106
	v_max_f32_e32 v110, 0, v110
	v_max_f32_e32 v114, 0, v113
	v_pk_mul_f32 v[100:101], v[100:101], v[106:107]
	v_pk_mul_f32 v[102:103], v[102:103], v[104:105]
	v_pk_mul_f32 v[96:97], v[96:97], v[114:115]
	v_pk_mul_f32 v[98:99], v[98:99], v[110:111]
	v_pk_mul_f32 v[102:103], v[102:103], v[112:113] op_sel_hi:[1,0]
	v_pk_mul_f32 v[100:101], v[100:101], v[112:113] op_sel_hi:[1,0]
	v_pk_mul_f32 v[104:105], v[98:99], v[112:113] op_sel_hi:[1,0]
	v_pk_mul_f32 v[98:99], v[96:97], v[112:113] op_sel_hi:[1,0]
	v_cvt_pk_bf16_f32 v96, v100, v101
	v_cvt_pk_bf16_f32 v97, v102, v103
	s_nop 0
	v_cvt_pk_bf16_f32 v98, v98, v99
	v_cvt_pk_bf16_f32 v99, v104, v105
	global_store_dwordx4 v[108:109], v[96:99], off offset:256
	s_nop 1
	v_max_f32_e32 v97, v95, v95
	v_max_f32_e32 v99, 0, v97
	v_max_f32_e32 v97, v94, v94
	v_max_f32_e32 v98, 0, v97
	v_max_f32_e32 v97, v93, v93
	v_max_f32_e32 v101, 0, v97
	v_max_f32_e32 v97, v92, v92
	v_max_f32_e32 v100, 0, v97
	v_max_f32_e32 v97, v91, v91
	v_max_f32_e32 v103, 0, v97
	v_max_f32_e32 v97, v90, v90
	v_max_f32_e32 v102, 0, v97
	v_max_f32_e32 v97, v89, v89
	v_max_f32_e32 v105, 0, v97
	v_max_f32_e32 v97, v88, v88
	v_mul_f32_e32 v96, v148, v148
	v_max_f32_e32 v104, 0, v97
	v_pk_mul_f32 v[92:93], v[92:93], v[100:101]
	v_pk_mul_f32 v[88:89], v[88:89], v[104:105]
	v_pk_mul_f32 v[92:93], v[92:93], v[96:97] op_sel_hi:[1,0]
	v_pk_mul_f32 v[90:91], v[90:91], v[102:103]
	v_pk_mul_f32 v[94:95], v[94:95], v[98:99]
	v_pk_mul_f32 v[98:99], v[90:91], v[96:97] op_sel_hi:[1,0]
	v_pk_mul_f32 v[90:91], v[88:89], v[96:97] op_sel_hi:[1,0]
	v_cvt_pk_bf16_f32 v88, v92, v93
	v_mad_i64_i32 v[92:93], s[2:3], v176, s43, v[120:121]
	v_pk_mul_f32 v[94:95], v[94:95], v[96:97] op_sel_hi:[1,0]
	v_lshl_add_u64 v[92:93], v[92:93], 0, v[122:123]
	v_cvt_pk_bf16_f32 v89, v94, v95
	v_cvt_pk_bf16_f32 v90, v90, v91
	v_cvt_pk_bf16_f32 v91, v98, v99
	global_store_dwordx4 v[92:93], v[88:91], off
	v_max_f32_e32 v94, v83, v83
	v_max_f32_e32 v97, v81, v81
	v_max_f32_e32 v88, v87, v87
	v_max_f32_e32 v90, v85, v85
	v_max_f32_e32 v89, 0, v88
	v_max_f32_e32 v88, v86, v86
	v_max_f32_e32 v91, 0, v90
	v_max_f32_e32 v90, v84, v84
	v_max_f32_e32 v95, 0, v94
	v_max_f32_e32 v94, v82, v82
	v_max_f32_e32 v99, 0, v97
	v_max_f32_e32 v97, v80, v80
	v_max_f32_e32 v88, 0, v88
	v_max_f32_e32 v90, 0, v90
	v_max_f32_e32 v94, 0, v94
	v_max_f32_e32 v98, 0, v97
	v_pk_mul_f32 v[84:85], v[84:85], v[90:91]
	v_pk_mul_f32 v[86:87], v[86:87], v[88:89]
	v_pk_mul_f32 v[80:81], v[80:81], v[98:99]
	v_pk_mul_f32 v[82:83], v[82:83], v[94:95]
	v_pk_mul_f32 v[86:87], v[86:87], v[96:97] op_sel_hi:[1,0]
	v_pk_mul_f32 v[84:85], v[84:85], v[96:97] op_sel_hi:[1,0]
	v_pk_mul_f32 v[88:89], v[82:83], v[96:97] op_sel_hi:[1,0]
	v_pk_mul_f32 v[82:83], v[80:81], v[96:97] op_sel_hi:[1,0]
	v_cvt_pk_bf16_f32 v80, v84, v85
	v_cvt_pk_bf16_f32 v81, v86, v87
	s_nop 0
	v_cvt_pk_bf16_f32 v82, v82, v83
	v_cvt_pk_bf16_f32 v83, v88, v89
	global_store_dwordx4 v[92:93], v[80:83], off offset:256
	s_nop 1
	v_max_f32_e32 v81, v79, v79
	v_max_f32_e32 v83, 0, v81
	v_max_f32_e32 v81, v78, v78
	v_max_f32_e32 v82, 0, v81
	v_max_f32_e32 v81, v77, v77
	v_max_f32_e32 v85, 0, v81
	v_max_f32_e32 v81, v76, v76
	v_max_f32_e32 v84, 0, v81
	v_max_f32_e32 v81, v75, v75
	v_max_f32_e32 v87, 0, v81
	v_max_f32_e32 v81, v74, v74
	v_max_f32_e32 v86, 0, v81
	v_max_f32_e32 v81, v73, v73
	v_max_f32_e32 v89, 0, v81
	v_max_f32_e32 v81, v72, v72
	v_mul_f32_e32 v80, v144, v144
	v_max_f32_e32 v88, 0, v81
	v_pk_mul_f32 v[76:77], v[76:77], v[84:85]
	v_pk_mul_f32 v[72:73], v[72:73], v[88:89]
	v_pk_mul_f32 v[76:77], v[76:77], v[80:81] op_sel_hi:[1,0]
	v_pk_mul_f32 v[74:75], v[74:75], v[86:87]
	v_pk_mul_f32 v[78:79], v[78:79], v[82:83]
	v_pk_mul_f32 v[82:83], v[74:75], v[80:81] op_sel_hi:[1,0]
	v_pk_mul_f32 v[74:75], v[72:73], v[80:81] op_sel_hi:[1,0]
	v_cvt_pk_bf16_f32 v72, v76, v77
	v_mad_i64_i32 v[76:77], s[2:3], v174, s43, v[120:121]
	v_pk_mul_f32 v[78:79], v[78:79], v[80:81] op_sel_hi:[1,0]
	v_lshl_add_u64 v[76:77], v[76:77], 0, v[122:123]
	v_cvt_pk_bf16_f32 v73, v78, v79
	v_cvt_pk_bf16_f32 v74, v74, v75
; __device__ __forceinline__ unsigned cvt_pk_bf16(float lo, float hi) { unsigned r; asm volatile("v_cvt_pk_bf16_f32 %0, %1, %2" : "=v"(r) : "v"(lo), "v"(hi)); return r; }
; #define GAS __attribute__((address_space(1)))
;     DI void operator()(AccRef acc, const pg8::Unit& u, int wr, int wc, int, int) const {
;     ...
;         EPI_ROWS_BEGIN
;             const float rs = rs8[ai * 4 + m];
;             EPI_COLS_BEGIN
;                 {
;                     const f32x4 z4 = {0.f, 0.f, 0.f, 0.f}; const float rs2 = rs * rs;
;                     const f32x4 m0 = __builtin_elementwise_max(v0, z4), m1 = __builtin_elementwise_max(v1, z4);
;                     v0 = (v0 * m0) * rs2; v1 = (v1 * m1) * rs2;
;                 }
;                 u32x4 w; w.x = cvt_pk_bf16(v0[0], v0[1]); w.y = cvt_pk_bf16(v0[2], v0[3]); w.z = cvt_pk_bf16(v1[0], v1[1]); w.w = cvt_pk_bf16(v1[2], v1[3]);
;                 *(GAS u32x4*)(U + (size_t)lrow * UP + col) = w;
;             EPI_END
;         EPI_ROW_END
	v_cvt_pk_bf16_f32 v75, v82, v83
	global_store_dwordx4 v[76:77], v[72:75], off
	v_max_f32_e32 v78, v67, v67
	v_max_f32_e32 v81, v65, v65
	v_max_f32_e32 v72, v71, v71
	v_max_f32_e32 v74, v69, v69
	v_max_f32_e32 v73, 0, v72
	v_max_f32_e32 v72, v70, v70
	v_max_f32_e32 v75, 0, v74
	v_max_f32_e32 v74, v68, v68
	v_max_f32_e32 v79, 0, v78
	v_max_f32_e32 v78, v66, v66
	v_max_f32_e32 v83, 0, v81
	v_max_f32_e32 v81, v64, v64
	v_max_f32_e32 v72, 0, v72
	v_max_f32_e32 v74, 0, v74
	v_max_f32_e32 v78, 0, v78
	v_max_f32_e32 v82, 0, v81
	v_pk_mul_f32 v[68:69], v[68:69], v[74:75]
	v_pk_mul_f32 v[70:71], v[70:71], v[72:73]
	v_pk_mul_f32 v[64:65], v[64:65], v[82:83]
	v_pk_mul_f32 v[66:67], v[66:67], v[78:79]
	v_pk_mul_f32 v[70:71], v[70:71], v[80:81] op_sel_hi:[1,0]
	v_pk_mul_f32 v[68:69], v[68:69], v[80:81] op_sel_hi:[1,0]
	v_pk_mul_f32 v[72:73], v[66:67], v[80:81] op_sel_hi:[1,0]
	v_pk_mul_f32 v[66:67], v[64:65], v[80:81] op_sel_hi:[1,0]
	v_cvt_pk_bf16_f32 v64, v68, v69
	v_cvt_pk_bf16_f32 v65, v70, v71
	s_nop 0
	v_cvt_pk_bf16_f32 v66, v66, v67
	v_cvt_pk_bf16_f32 v67, v72, v73
	global_store_dwordx4 v[76:77], v[64:67], off offset:256
	s_nop 1
	v_max_f32_e32 v65, v63, v63
	v_max_f32_e32 v67, 0, v65
	v_max_f32_e32 v65, v62, v62
	v_max_f32_e32 v66, 0, v65
	v_max_f32_e32 v65, v61, v61
	v_max_f32_e32 v69, 0, v65
	v_max_f32_e32 v65, v60, v60
	v_max_f32_e32 v68, 0, v65
	v_max_f32_e32 v65, v59, v59
	v_max_f32_e32 v71, 0, v65
	v_max_f32_e32 v65, v58, v58
	v_max_f32_e32 v70, 0, v65
	v_max_f32_e32 v65, v57, v57
	v_max_f32_e32 v73, 0, v65
	v_max_f32_e32 v65, v56, v56
	v_mul_f32_e32 v64, v140, v140
	v_max_f32_e32 v72, 0, v65
	v_pk_mul_f32 v[60:61], v[60:61], v[68:69]
	v_pk_mul_f32 v[56:57], v[56:57], v[72:73]
	v_pk_mul_f32 v[60:61], v[60:61], v[64:65] op_sel_hi:[1,0]
	v_pk_mul_f32 v[58:59], v[58:59], v[70:71]
	v_pk_mul_f32 v[62:63], v[62:63], v[66:67]
	v_pk_mul_f32 v[66:67], v[58:59], v[64:65] op_sel_hi:[1,0]
	v_pk_mul_f32 v[58:59], v[56:57], v[64:65] op_sel_hi:[1,0]
	v_cvt_pk_bf16_f32 v56, v60, v61
	v_mad_i64_i32 v[60:61], s[2:3], v172, s43, v[120:121]
	v_pk_mul_f32 v[62:63], v[62:63], v[64:65] op_sel_hi:[1,0]
	v_lshl_add_u64 v[60:61], v[60:61], 0, v[122:123]
	v_cvt_pk_bf16_f32 v57, v62, v63
	v_cvt_pk_bf16_f32 v58, v58, v59
	v_cvt_pk_bf16_f32 v59, v66, v67
	global_store_dwordx4 v[60:61], v[56:59], off
	v_max_f32_e32 v62, v51, v51
	v_max_f32_e32 v65, v49, v49
	v_max_f32_e32 v56, v55, v55
	v_max_f32_e32 v58, v53, v53
	v_max_f32_e32 v57, 0, v56
	v_max_f32_e32 v56, v54, v54
	v_max_f32_e32 v59, 0, v58
	v_max_f32_e32 v58, v52, v52
	v_max_f32_e32 v63, 0, v62
	v_max_f32_e32 v62, v50, v50
	v_max_f32_e32 v67, 0, v65
	v_max_f32_e32 v65, v48, v48
	v_max_f32_e32 v56, 0, v56
	v_max_f32_e32 v58, 0, v58
	v_max_f32_e32 v62, 0, v62
	v_max_f32_e32 v66, 0, v65
	v_pk_mul_f32 v[52:53], v[52:53], v[58:59]
	v_pk_mul_f32 v[54:55], v[54:55], v[56:57]
	v_pk_mul_f32 v[48:49], v[48:49], v[66:67]
	v_pk_mul_f32 v[50:51], v[50:51], v[62:63]
	v_pk_mul_f32 v[54:55], v[54:55], v[64:65] op_sel_hi:[1,0]
	v_pk_mul_f32 v[52:53], v[52:53], v[64:65] op_sel_hi:[1,0]
	v_pk_mul_f32 v[56:57], v[50:51], v[64:65] op_sel_hi:[1,0]
	v_pk_mul_f32 v[50:51], v[48:49], v[64:65] op_sel_hi:[1,0]
	v_cvt_pk_bf16_f32 v48, v52, v53
	v_cvt_pk_bf16_f32 v49, v54, v55
	s_nop 0
	v_cvt_pk_bf16_f32 v50, v50, v51
	v_cvt_pk_bf16_f32 v51, v56, v57
	global_store_dwordx4 v[60:61], v[48:51], off offset:256
	s_nop 1
	v_max_f32_e32 v49, v47, v47
	v_max_f32_e32 v51, 0, v49
	v_max_f32_e32 v49, v46, v46
	v_max_f32_e32 v50, 0, v49
	v_max_f32_e32 v49, v45, v45
	v_max_f32_e32 v53, 0, v49
	v_max_f32_e32 v49, v44, v44
	v_max_f32_e32 v52, 0, v49
	v_max_f32_e32 v49, v43, v43
	v_max_f32_e32 v55, 0, v49
	v_max_f32_e32 v49, v42, v42
	v_max_f32_e32 v54, 0, v49
	v_max_f32_e32 v49, v41, v41
	v_max_f32_e32 v57, 0, v49
	v_max_f32_e32 v49, v40, v40
	v_mul_f32_e32 v48, v136, v136
	v_max_f32_e32 v56, 0, v49
	v_pk_mul_f32 v[44:45], v[44:45], v[52:53]
	v_pk_mul_f32 v[40:41], v[40:41], v[56:57]
	v_pk_mul_f32 v[44:45], v[44:45], v[48:49] op_sel_hi:[1,0]
	v_pk_mul_f32 v[42:43], v[42:43], v[54:55]
	v_pk_mul_f32 v[46:47], v[46:47], v[50:51]
	v_pk_mul_f32 v[50:51], v[42:43], v[48:49] op_sel_hi:[1,0]
	v_pk_mul_f32 v[42:43], v[40:41], v[48:49] op_sel_hi:[1,0]
	v_cvt_pk_bf16_f32 v40, v44, v45
	v_mad_i64_i32 v[44:45], s[2:3], v170, s43, v[120:121]
	v_pk_mul_f32 v[46:47], v[46:47], v[48:49] op_sel_hi:[1,0]
	v_lshl_add_u64 v[44:45], v[44:45], 0, v[122:123]
	v_cvt_pk_bf16_f32 v41, v46, v47
	v_cvt_pk_bf16_f32 v42, v42, v43
	v_cvt_pk_bf16_f32 v43, v50, v51
	global_store_dwordx4 v[44:45], v[40:43], off
	v_max_f32_e32 v46, v35, v35
	v_max_f32_e32 v49, v33, v33
	v_max_f32_e32 v40, v39, v39
	v_max_f32_e32 v42, v37, v37
	v_max_f32_e32 v41, 0, v40
	v_max_f32_e32 v40, v38, v38
	v_max_f32_e32 v43, 0, v42
	v_max_f32_e32 v42, v36, v36
	v_max_f32_e32 v47, 0, v46
	v_max_f32_e32 v46, v34, v34
	v_max_f32_e32 v51, 0, v49
	v_max_f32_e32 v49, v32, v32
	v_max_f32_e32 v40, 0, v40
	v_max_f32_e32 v42, 0, v42
	v_max_f32_e32 v46, 0, v46
	v_max_f32_e32 v50, 0, v49
	v_pk_mul_f32 v[36:37], v[36:37], v[42:43]
; __device__ __forceinline__ unsigned cvt_pk_bf16(float lo, float hi) { unsigned r; asm volatile("v_cvt_pk_bf16_f32 %0, %1, %2" : "=v"(r) : "v"(lo), "v"(hi)); return r; }
; #define PG8_BAR __builtin_amdgcn_s_barrier()
; #define GAS __attribute__((address_space(1)))
; template <class Epi, class Sched, bool ALIGN_EPI = false, bool SP2 = false>
; __device__ __forceinline__ void gemm_phase(PG8_LAS unsigned char* lds, const Gemm g, const Sched& S, const Epi& E) {
;     ...
;         if (!has_next) break;
; #pragma unroll
;         for (int a = 0; a < 2; ++a)
; #pragma unroll
;             for (int b = 0; b < 2; ++b)
; #pragma unroll
;                 for (int m = 0; m < 4; ++m)
; #pragma unroll
;                     for (int n = 0; n < 2; ++n) acc[a][b][m][n] = (f32x4){0.f, 0.f, 0.f, 0.f};
;         cur = nxt; cA = nA; cB = nB; ++ui;
;         if constexpr (ALIGN_EPI) { if (wr == 1) PG8_BAR; }
;     DI void operator()(AccRef acc, const pg8::Unit& u, int wr, int wc, int, int) const {
;     ...
;         EPI_ROWS_BEGIN
;             const float rs = rs8[ai * 4 + m];
;             EPI_COLS_BEGIN
;                 {
;                     const f32x4 z4 = {0.f, 0.f, 0.f, 0.f}; const float rs2 = rs * rs;
;                     const f32x4 m0 = __builtin_elementwise_max(v0, z4), m1 = __builtin_elementwise_max(v1, z4);
;                     v0 = (v0 * m0) * rs2; v1 = (v1 * m1) * rs2;
;                 }
;                 u32x4 w; w.x = cvt_pk_bf16(v0[0], v0[1]); w.y = cvt_pk_bf16(v0[2], v0[3]); w.z = cvt_pk_bf16(v1[0], v1[1]); w.w = cvt_pk_bf16(v1[2], v1[3]);
;                 *(GAS u32x4*)(U + (size_t)lrow * UP + col) = w;
;             EPI_END
;         EPI_ROW_END
	v_pk_mul_f32 v[38:39], v[38:39], v[40:41]
	v_pk_mul_f32 v[32:33], v[32:33], v[50:51]
	v_pk_mul_f32 v[34:35], v[34:35], v[46:47]
	v_pk_mul_f32 v[38:39], v[38:39], v[48:49] op_sel_hi:[1,0]
	v_pk_mul_f32 v[36:37], v[36:37], v[48:49] op_sel_hi:[1,0]
	v_pk_mul_f32 v[40:41], v[34:35], v[48:49] op_sel_hi:[1,0]
	v_pk_mul_f32 v[34:35], v[32:33], v[48:49] op_sel_hi:[1,0]
	v_cvt_pk_bf16_f32 v32, v36, v37
	v_cvt_pk_bf16_f32 v33, v38, v39
	s_nop 0
	v_cvt_pk_bf16_f32 v34, v34, v35
	v_cvt_pk_bf16_f32 v35, v40, v41
	global_store_dwordx4 v[44:45], v[32:35], off offset:256
	s_nop 1
	v_max_f32_e32 v33, v31, v31
	v_max_f32_e32 v35, 0, v33
	v_max_f32_e32 v33, v30, v30
	v_max_f32_e32 v34, 0, v33
	v_max_f32_e32 v33, v29, v29
	v_max_f32_e32 v37, 0, v33
	v_max_f32_e32 v33, v28, v28
	v_max_f32_e32 v36, 0, v33
	v_max_f32_e32 v33, v27, v27
	v_max_f32_e32 v39, 0, v33
	v_max_f32_e32 v33, v26, v26
	v_max_f32_e32 v38, 0, v33
	v_max_f32_e32 v33, v25, v25
	v_max_f32_e32 v41, 0, v33
	v_max_f32_e32 v33, v24, v24
	v_mul_f32_e32 v32, v132, v132
	v_max_f32_e32 v40, 0, v33
	v_pk_mul_f32 v[28:29], v[28:29], v[36:37]
	v_pk_mul_f32 v[24:25], v[24:25], v[40:41]
	v_pk_mul_f32 v[28:29], v[28:29], v[32:33] op_sel_hi:[1,0]
	v_pk_mul_f32 v[26:27], v[26:27], v[38:39]
	v_pk_mul_f32 v[30:31], v[30:31], v[34:35]
	v_pk_mul_f32 v[34:35], v[26:27], v[32:33] op_sel_hi:[1,0]
	v_pk_mul_f32 v[26:27], v[24:25], v[32:33] op_sel_hi:[1,0]
	v_cvt_pk_bf16_f32 v24, v28, v29
	v_mad_i64_i32 v[28:29], s[2:3], v168, s43, v[120:121]
	v_pk_mul_f32 v[30:31], v[30:31], v[32:33] op_sel_hi:[1,0]
	v_lshl_add_u64 v[28:29], v[28:29], 0, v[122:123]
	v_cvt_pk_bf16_f32 v25, v30, v31
	v_cvt_pk_bf16_f32 v26, v26, v27
	v_cvt_pk_bf16_f32 v27, v34, v35
	global_store_dwordx4 v[28:29], v[24:27], off
	v_max_f32_e32 v30, v19, v19
	v_max_f32_e32 v33, v17, v17
	v_max_f32_e32 v24, v23, v23
	v_max_f32_e32 v26, v21, v21
	v_max_f32_e32 v25, 0, v24
	v_max_f32_e32 v24, v22, v22
	v_max_f32_e32 v27, 0, v26
	v_max_f32_e32 v26, v20, v20
	v_max_f32_e32 v31, 0, v30
	v_max_f32_e32 v30, v18, v18
	v_max_f32_e32 v35, 0, v33
	v_max_f32_e32 v33, v16, v16
	v_max_f32_e32 v24, 0, v24
	v_max_f32_e32 v26, 0, v26
	v_max_f32_e32 v30, 0, v30
	v_max_f32_e32 v34, 0, v33
	v_pk_mul_f32 v[20:21], v[20:21], v[26:27]
	v_pk_mul_f32 v[22:23], v[22:23], v[24:25]
	v_pk_mul_f32 v[16:17], v[16:17], v[34:35]
	v_pk_mul_f32 v[18:19], v[18:19], v[30:31]
	v_pk_mul_f32 v[22:23], v[22:23], v[32:33] op_sel_hi:[1,0]
	v_pk_mul_f32 v[20:21], v[20:21], v[32:33] op_sel_hi:[1,0]
	v_pk_mul_f32 v[24:25], v[18:19], v[32:33] op_sel_hi:[1,0]
	v_pk_mul_f32 v[18:19], v[16:17], v[32:33] op_sel_hi:[1,0]
	v_cvt_pk_bf16_f32 v16, v20, v21
	v_cvt_pk_bf16_f32 v17, v22, v23
	s_nop 0
	v_cvt_pk_bf16_f32 v18, v18, v19
	v_cvt_pk_bf16_f32 v19, v24, v25
	global_store_dwordx4 v[28:29], v[16:19], off offset:256
	s_nop 1
	v_max_f32_e32 v17, v15, v15
	v_max_f32_e32 v19, 0, v17
	v_max_f32_e32 v17, v14, v14
	v_max_f32_e32 v18, 0, v17
	v_max_f32_e32 v17, v13, v13
	v_max_f32_e32 v21, 0, v17
	v_max_f32_e32 v17, v12, v12
	v_max_f32_e32 v20, 0, v17
	v_max_f32_e32 v17, v11, v11
	v_max_f32_e32 v23, 0, v17
	v_max_f32_e32 v17, v10, v10
	v_max_f32_e32 v22, 0, v17
	v_max_f32_e32 v17, v9, v9
	v_max_f32_e32 v25, 0, v17
	v_max_f32_e32 v17, v8, v8
	v_mul_f32_e32 v16, v128, v128
	v_max_f32_e32 v24, 0, v17
	v_pk_mul_f32 v[12:13], v[12:13], v[20:21]
	v_pk_mul_f32 v[14:15], v[14:15], v[18:19]
	v_pk_mul_f32 v[12:13], v[12:13], v[16:17] op_sel_hi:[1,0]
	v_pk_mul_f32 v[8:9], v[8:9], v[24:25]
	v_pk_mul_f32 v[10:11], v[10:11], v[22:23]
	v_pk_mul_f32 v[14:15], v[14:15], v[16:17] op_sel_hi:[1,0]
	v_pk_mul_f32 v[18:19], v[10:11], v[16:17] op_sel_hi:[1,0]
	v_pk_mul_f32 v[10:11], v[8:9], v[16:17] op_sel_hi:[1,0]
	v_cvt_pk_bf16_f32 v8, v12, v13
	v_mad_i64_i32 v[12:13], s[2:3], v166, s43, v[120:121]
	v_cvt_pk_bf16_f32 v9, v14, v15
	v_cvt_pk_bf16_f32 v10, v10, v11
	v_lshl_add_u64 v[12:13], v[12:13], 0, v[122:123]
	v_max_f32_e32 v14, v3, v3
	v_max_f32_e32 v17, v1, v1
	v_cvt_pk_bf16_f32 v11, v18, v19
	global_store_dwordx4 v[12:13], v[8:11], off
	v_max_f32_e32 v15, 0, v14
	v_max_f32_e32 v14, v2, v2
	v_max_f32_e32 v8, v7, v7
	v_max_f32_e32 v10, v5, v5
	v_max_f32_e32 v19, 0, v17
	v_max_f32_e32 v17, v0, v0
	v_max_f32_e32 v9, 0, v8
	v_max_f32_e32 v8, v6, v6
	v_max_f32_e32 v11, 0, v10
	v_max_f32_e32 v10, v4, v4
	v_max_f32_e32 v14, 0, v14
	v_max_f32_e32 v18, 0, v17
	v_max_f32_e32 v8, 0, v8
	v_max_f32_e32 v10, 0, v10
	v_pk_mul_f32 v[0:1], v[0:1], v[18:19]
	v_pk_mul_f32 v[2:3], v[2:3], v[14:15]
	v_pk_mul_f32 v[4:5], v[4:5], v[10:11]
	v_pk_mul_f32 v[6:7], v[6:7], v[8:9]
	v_pk_mul_f32 v[8:9], v[2:3], v[16:17] op_sel_hi:[1,0]
	v_pk_mul_f32 v[2:3], v[0:1], v[16:17] op_sel_hi:[1,0]
	v_pk_mul_f32 v[6:7], v[6:7], v[16:17] op_sel_hi:[1,0]
	v_pk_mul_f32 v[4:5], v[4:5], v[16:17] op_sel_hi:[1,0]
	s_nop 0
	v_cvt_pk_bf16_f32 v0, v4, v5
	v_cvt_pk_bf16_f32 v1, v6, v7
	v_cvt_pk_bf16_f32 v2, v2, v3
	v_cvt_pk_bf16_f32 v3, v8, v9
	global_store_dwordx4 v[12:13], v[0:3], off offset:256
	s_cbranch_vccnz .LBB0_685
	s_andn2_b64 vcc, exec, s[10:11]
	s_cbranch_vccnz .LBB0_684
	s_barrier
	s_branch .LBB0_684

;     DI void operator()(AccRef acc, const pg8::Unit& u, int wr, int wc, int, int) const {
;     ...
;         const int kind = dummy ? 2 : (kind_force >= 0 ? kind_force : (pn < 6 ? (pn < 3 ? 0 : 1) : (pn < 15 ? 2 : (pn < 19 ? 3 : 4))));
.Llean_F_entry:
	v_and_b32_e32 v136, 15, v226
	v_lshrrev_b32_e32 v137, 4, v226
	v_or_b32_e32 v136, s49, v136
	v_lshl_add_u32 v138, s6, 8, v136
	v_lshlrev_b32_e32 v140, 4, v137
	v_lshl_add_u32 v140, v138, 6, v140
	v_add_u32_e32 v140, 0x2000, v140
	v_mov_b32_e32 v141, 0
	v_lshl_add_u64 v[144:145], s[26:27], 0, v[140:141]
	global_load_dwordx4 v[72:75], v[144:145], off
	global_load_dwordx4 v[76:79], v[144:145], off offset:1024
	global_load_dwordx4 v[80:83], v[144:145], off offset:2048
	global_load_dwordx4 v[84:87], v[144:145], off offset:3072
	v_mul_lo_u32 v146, v138, s39
	v_mov_b32_e32 v147, 0
	s_lshl_b32 s0, s14, 8
	s_add_i32 s0, s0, s20
	v_lshl_add_u32 v148, v137, 3, s0
	v_lshlrev_b32_e32 v148, 1, v148
	v_mov_b32_e32 v149, 0
	v_lshl_add_u64 v[146:147], v[146:147], 1, s[72:73]
	v_lshl_add_u64 v[146:147], v[146:147], 0, v[148:149]
	s_lshl_b32 s2, s39, 5
	s_mov_b32 s3, 0
	s_mul_i32 s0, s39, 0xa0
	s_mov_b32 s1, 0
	v_mov_b32_e32 v213, 0x260
	v_add_f32_e32 v168, v194, v195
	v_add_f32_e32 v169, v196, v197
	v_add_f32_e32 v168, v168, v169
	v_add_f32_e32 v170, v228, v229
	v_add_f32_e32 v171, v230, v231
	v_add_f32_e32 v170, v170, v171
	v_add_f32_e32 v172, v232, v233
	v_add_f32_e32 v173, v234, v235
	v_add_f32_e32 v172, v172, v173
	v_add_f32_e32 v174, v236, v237
	v_add_f32_e32 v175, v238, v239
	v_add_f32_e32 v174, v174, v175
	ds_swizzle_b32 v169, v168 offset:swizzle(SWAP,16)
	ds_swizzle_b32 v171, v170 offset:swizzle(SWAP,16)
	ds_swizzle_b32 v173, v172 offset:swizzle(SWAP,16)
	ds_swizzle_b32 v175, v174 offset:swizzle(SWAP,16)
	s_waitcnt lgkmcnt(0)
	v_add_f32_e32 v168, v168, v169
	v_add_f32_e32 v170, v170, v171
	v_add_f32_e32 v172, v172, v173
	v_add_f32_e32 v174, v174, v175
	v_mov_b32_e32 v169, v168
	v_mov_b32_e32 v171, v170
	v_mov_b32_e32 v173, v172
	v_mov_b32_e32 v175, v174
	s_nop 1
	v_permlane32_swap_b32_e32 v168, v169
	v_permlane32_swap_b32_e32 v170, v171
	v_permlane32_swap_b32_e32 v172, v173
	v_permlane32_swap_b32_e32 v174, v175
	v_add_f32_e32 v168, v168, v169
	v_add_f32_e32 v170, v170, v171
	v_add_f32_e32 v172, v172, v173
	v_add_f32_e32 v174, v174, v175
	v_fmamk_f32 v168, v168, 0x3a800000, v246
	v_cmp_gt_f32_e32 vcc, s33, v168
	v_mul_f32_e32 v208, 0x4f800000, v168
	s_nop 0
	v_cndmask_b32_e32 v168, v168, v208, vcc
	v_sqrt_f32_e32 v208, v168
	s_nop 0
	v_add_u32_e32 v209, -1, v208
	v_fma_f32 v210, -v209, v208, v168
	v_cmp_ge_f32_e64 s[98:99], 0, v210
	v_add_u32_e32 v210, 1, v208
	s_nop 0
	v_cndmask_b32_e64 v209, v208, v209, s[98:99]
	v_fma_f32 v208, -v210, v208, v168
	v_cmp_lt_f32_e64 s[98:99], 0, v208
	s_nop 1
	v_cndmask_b32_e64 v208, v209, v210, s[98:99]
	v_mul_f32_e32 v209, 0x37800000, v208
	v_cndmask_b32_e32 v208, v208, v209, vcc
	v_cmp_class_f32_e32 vcc, v168, v213
	s_nop 1
	v_cndmask_b32_e32 v168, v208, v168, vcc
	v_div_scale_f32 v208, s[98:99], v168, v168, 1.0
	v_rcp_f32_e32 v209, v208
	s_nop 0
	v_fma_f32 v210, -v208, v209, 1.0
	v_fmac_f32_e32 v209, v210, v209
	v_div_scale_f32 v210, vcc, 1.0, v168, 1.0
	v_mul_f32_e32 v211, v210, v209
	v_fma_f32 v212, -v208, v211, v210
	v_fmac_f32_e32 v211, v212, v209
	v_fma_f32 v208, -v208, v211, v210
	v_div_fmas_f32 v208, v208, v209, v211
	v_div_fixup_f32 v168, v208, v168, 1.0
	v_fmamk_f32 v170, v170, 0x3a800000, v246
	v_cmp_gt_f32_e32 vcc, s33, v170
	v_mul_f32_e32 v208, 0x4f800000, v170
	s_nop 0
	v_cndmask_b32_e32 v170, v170, v208, vcc
	v_sqrt_f32_e32 v208, v170
	s_nop 0
	v_add_u32_e32 v209, -1, v208
	v_fma_f32 v210, -v209, v208, v170
	v_cmp_ge_f32_e64 s[98:99], 0, v210
	v_add_u32_e32 v210, 1, v208
	s_nop 0
	v_cndmask_b32_e64 v209, v208, v209, s[98:99]
	v_fma_f32 v208, -v210, v208, v170
	v_cmp_lt_f32_e64 s[98:99], 0, v208
	s_nop 1
	v_cndmask_b32_e64 v208, v209, v210, s[98:99]
	v_mul_f32_e32 v209, 0x37800000, v208
	v_cndmask_b32_e32 v208, v208, v209, vcc
	v_cmp_class_f32_e32 vcc, v170, v213
	s_nop 1
	v_cndmask_b32_e32 v170, v208, v170, vcc
	v_div_scale_f32 v208, s[98:99], v170, v170, 1.0
	v_rcp_f32_e32 v209, v208
	s_nop 0
	v_fma_f32 v210, -v208, v209, 1.0
	v_fmac_f32_e32 v209, v210, v209
	v_div_scale_f32 v210, vcc, 1.0, v170, 1.0
	v_mul_f32_e32 v211, v210, v209
	v_fma_f32 v212, -v208, v211, v210
	v_fmac_f32_e32 v211, v212, v209
	v_fma_f32 v208, -v208, v211, v210
	v_div_fmas_f32 v208, v208, v209, v211
	v_div_fixup_f32 v170, v208, v170, 1.0
	v_fmamk_f32 v172, v172, 0x3a800000, v246
	v_cmp_gt_f32_e32 vcc, s33, v172
	v_mul_f32_e32 v208, 0x4f800000, v172
	s_nop 0
	v_cndmask_b32_e32 v172, v172, v208, vcc
	v_sqrt_f32_e32 v208, v172
	s_nop 0
	v_add_u32_e32 v209, -1, v208
	v_fma_f32 v210, -v209, v208, v172
	v_cmp_ge_f32_e64 s[98:99], 0, v210
	v_add_u32_e32 v210, 1, v208
	s_nop 0
	v_cndmask_b32_e64 v209, v208, v209, s[98:99]
	v_fma_f32 v208, -v210, v208, v172
	v_cmp_lt_f32_e64 s[98:99], 0, v208
	s_nop 1
	v_cndmask_b32_e64 v208, v209, v210, s[98:99]
	v_mul_f32_e32 v209, 0x37800000, v208
	v_cndmask_b32_e32 v208, v208, v209, vcc
	v_cmp_class_f32_e32 vcc, v172, v213
	s_nop 1
	v_cndmask_b32_e32 v172, v208, v172, vcc
	v_div_scale_f32 v208, s[98:99], v172, v172, 1.0
	v_rcp_f32_e32 v209, v208
	s_nop 0
	v_fma_f32 v210, -v208, v209, 1.0
	v_fmac_f32_e32 v209, v210, v209
	v_div_scale_f32 v210, vcc, 1.0, v172, 1.0
	v_mul_f32_e32 v211, v210, v209
	v_fma_f32 v212, -v208, v211, v210
	v_fmac_f32_e32 v211, v212, v209
	v_fma_f32 v208, -v208, v211, v210
	v_div_fmas_f32 v208, v208, v209, v211
	v_div_fixup_f32 v172, v208, v172, 1.0
	v_fmamk_f32 v174, v174, 0x3a800000, v246
	v_cmp_gt_f32_e32 vcc, s33, v174
	v_mul_f32_e32 v208, 0x4f800000, v174
	s_nop 0
	v_cndmask_b32_e32 v174, v174, v208, vcc
	v_sqrt_f32_e32 v208, v174
	s_nop 0
	v_add_u32_e32 v209, -1, v208
	v_fma_f32 v210, -v209, v208, v174
	v_cmp_ge_f32_e64 s[98:99], 0, v210
	v_add_u32_e32 v210, 1, v208
	s_nop 0
	v_cndmask_b32_e64 v209, v208, v209, s[98:99]
	v_fma_f32 v208, -v210, v208, v174
	v_cmp_lt_f32_e64 s[98:99], 0, v208
	s_nop 1
	v_cndmask_b32_e64 v208, v209, v210, s[98:99]
	v_mul_f32_e32 v209, 0x37800000, v208
	v_cndmask_b32_e32 v208, v208, v209, vcc
	v_cmp_class_f32_e32 vcc, v174, v213
	s_nop 1
	v_cndmask_b32_e32 v174, v208, v174, vcc
	v_div_scale_f32 v208, s[98:99], v174, v174, 1.0
	v_rcp_f32_e32 v209, v208
	s_nop 0
	v_fma_f32 v210, -v208, v209, 1.0
	v_fmac_f32_e32 v209, v210, v209
	v_div_scale_f32 v210, vcc, 1.0, v174, 1.0
	v_mul_f32_e32 v211, v210, v209
	v_fma_f32 v212, -v208, v211, v210
	v_fmac_f32_e32 v211, v212, v209
	v_fma_f32 v208, -v208, v211, v210
	v_div_fmas_f32 v208, v208, v209, v211
	v_div_fixup_f32 v174, v208, v174, 1.0
	s_cmp_eq_u32 s8, 4
	s_cbranch_scc1 .Llean_F_sig
; __device__ __forceinline__ unsigned cvt_pk_bf16(float lo, float hi) { unsigned r; asm volatile("v_cvt_pk_bf16_f32 %0, %1, %2" : "=v"(r) : "v"(lo), "v"(hi)); return r; }
; #define GAS __attribute__((address_space(1)))
;     DI void operator()(AccRef acc, const pg8::Unit& u, int wr, int wc, int, int) const {
;     ...
;                 { const float rsk = (kind == 4) ? rs * -1.4426950408889634f : rs; v0 = v0 * rsk; v1 = v1 * rsk; }
;                 if (kind < 2) {
;                     if (rot) {
;                         f32x4 p0, p1;
; #pragma unroll
;                         for (int e = 0; e < 4; ++e) { p0[e] = lane_xor<16>(v0[e]); p1[e] = lane_xor<16>(v1[e]); }
;                         if (fq == 0) { v0 = v0 * c0 - p0 * s0; v1 = v1 * c1 - p1 * s1; }
;                         else if (fq == 1) { v0 = v0 * c0 + p0 * s0; v1 = v1 * c1 + p1 * s1; }
;                     }
;                     v0 = v0 * qs; v1 = v1 * qs;
;                 } else if (kind == 3) {
;                     f32x2 a = pg8::gelu_pk((f32x2){v0[0], v0[1]}), b = pg8::gelu_pk((f32x2){v0[2], v0[3]}), c = pg8::gelu_pk((f32x2){v1[0], v1[1]}), d = pg8::gelu_pk((f32x2){v1[2], v1[3]});
;                     v0 = (f32x4){a.x, a.y, b.x, b.y}; v1 = (f32x4){c.x, c.y, d.x, d.y};
;                 } else if (kind == 4) {
; #pragma unroll
;                     for (int e = 0; e < 4; ++e) { v0[e] = __builtin_amdgcn_rcpf(1.0f + __builtin_amdgcn_exp2f(v0[e])); v1[e] = __builtin_amdgcn_rcpf(1.0f + __builtin_amdgcn_exp2f(v1[e])); }
;                 }
;                 u32x4 w; w.x = cvt_pk_bf16(v0[0], v0[1]); w.y = cvt_pk_bf16(v0[2], v0[3]); w.z = cvt_pk_bf16(v1[0], v1[1]); w.w = cvt_pk_bf16(v1[2], v1[3]);
;                 *(GAS u32x4*)(dummy ? dummy + lane_ * 8 : Z + (size_t)lrow * ldz + col) = w;
	v_pk_mul_f32 v[188:189], v[188:189], v[168:169] op_sel_hi:[1,0]
	v_pk_mul_f32 v[190:191], v[190:191], v[168:169] op_sel_hi:[1,0]
	v_pk_mul_f32 v[184:185], v[184:185], v[168:169] op_sel_hi:[1,0]
	v_pk_mul_f32 v[186:187], v[186:187], v[168:169] op_sel_hi:[1,0]
	v_cvt_pk_bf16_f32 v104, v188, v189
	v_cvt_pk_bf16_f32 v105, v190, v191
	v_cvt_pk_bf16_f32 v106, v184, v185
	v_cvt_pk_bf16_f32 v107, v186, v187
	global_store_dwordx4 v[146:147], v[104:107], off
	v_pk_mul_f32 v[164:165], v[164:165], v[168:169] op_sel_hi:[1,0]
	v_pk_mul_f32 v[166:167], v[166:167], v[168:169] op_sel_hi:[1,0]
	v_pk_mul_f32 v[160:161], v[160:161], v[168:169] op_sel_hi:[1,0]
	v_pk_mul_f32 v[162:163], v[162:163], v[168:169] op_sel_hi:[1,0]
	v_cvt_pk_bf16_f32 v108, v164, v165
	v_cvt_pk_bf16_f32 v109, v166, v167
	v_cvt_pk_bf16_f32 v110, v160, v161
	v_cvt_pk_bf16_f32 v111, v162, v163
	global_store_dwordx4 v[146:147], v[108:111], off offset:256
	v_lshl_add_u64 v[150:151], v[146:147], 0, s[2:3]
	v_pk_mul_f32 v[156:157], v[156:157], v[170:171] op_sel_hi:[1,0]
	v_pk_mul_f32 v[158:159], v[158:159], v[170:171] op_sel_hi:[1,0]
	v_pk_mul_f32 v[152:153], v[152:153], v[170:171] op_sel_hi:[1,0]
	v_pk_mul_f32 v[154:155], v[154:155], v[170:171] op_sel_hi:[1,0]
	v_cvt_pk_bf16_f32 v112, v156, v157
	v_cvt_pk_bf16_f32 v113, v158, v159
	v_cvt_pk_bf16_f32 v114, v152, v153
	v_cvt_pk_bf16_f32 v115, v154, v155
	global_store_dwordx4 v[150:151], v[112:115], off
	v_pk_mul_f32 v[132:133], v[132:133], v[170:171] op_sel_hi:[1,0]
	v_pk_mul_f32 v[134:135], v[134:135], v[170:171] op_sel_hi:[1,0]
	v_pk_mul_f32 v[128:129], v[128:129], v[170:171] op_sel_hi:[1,0]
	v_pk_mul_f32 v[130:131], v[130:131], v[170:171] op_sel_hi:[1,0]
	v_cvt_pk_bf16_f32 v116, v132, v133
	v_cvt_pk_bf16_f32 v117, v134, v135
	v_cvt_pk_bf16_f32 v118, v128, v129
	v_cvt_pk_bf16_f32 v119, v130, v131
	global_store_dwordx4 v[150:151], v[116:119], off offset:256
	v_lshl_add_u64 v[146:147], v[150:151], 0, s[2:3]
	v_pk_mul_f32 v[124:125], v[124:125], v[172:173] op_sel_hi:[1,0]
	v_pk_mul_f32 v[126:127], v[126:127], v[172:173] op_sel_hi:[1,0]
	v_pk_mul_f32 v[120:121], v[120:121], v[172:173] op_sel_hi:[1,0]
	v_pk_mul_f32 v[122:123], v[122:123], v[172:173] op_sel_hi:[1,0]
	v_cvt_pk_bf16_f32 v104, v124, v125
	v_cvt_pk_bf16_f32 v105, v126, v127
	v_cvt_pk_bf16_f32 v106, v120, v121
	v_cvt_pk_bf16_f32 v107, v122, v123
	global_store_dwordx4 v[146:147], v[104:107], off
	v_pk_mul_f32 v[100:101], v[100:101], v[172:173] op_sel_hi:[1,0]
	v_pk_mul_f32 v[102:103], v[102:103], v[172:173] op_sel_hi:[1,0]
	v_pk_mul_f32 v[96:97], v[96:97], v[172:173] op_sel_hi:[1,0]
	v_pk_mul_f32 v[98:99], v[98:99], v[172:173] op_sel_hi:[1,0]
	v_cvt_pk_bf16_f32 v108, v100, v101
	v_cvt_pk_bf16_f32 v109, v102, v103
	v_cvt_pk_bf16_f32 v110, v96, v97
	v_cvt_pk_bf16_f32 v111, v98, v99
	global_store_dwordx4 v[146:147], v[108:111], off offset:256
	v_lshl_add_u64 v[150:151], v[146:147], 0, s[2:3]
	v_pk_mul_f32 v[92:93], v[92:93], v[174:175] op_sel_hi:[1,0]
	v_pk_mul_f32 v[94:95], v[94:95], v[174:175] op_sel_hi:[1,0]
	v_pk_mul_f32 v[88:89], v[88:89], v[174:175] op_sel_hi:[1,0]
	v_pk_mul_f32 v[90:91], v[90:91], v[174:175] op_sel_hi:[1,0]
	v_cvt_pk_bf16_f32 v112, v92, v93
	v_cvt_pk_bf16_f32 v113, v94, v95
	v_cvt_pk_bf16_f32 v114, v88, v89
	v_cvt_pk_bf16_f32 v115, v90, v91
	global_store_dwordx4 v[150:151], v[112:115], off
	v_pk_mul_f32 v[68:69], v[68:69], v[174:175] op_sel_hi:[1,0]
	v_pk_mul_f32 v[70:71], v[70:71], v[174:175] op_sel_hi:[1,0]
	v_pk_mul_f32 v[64:65], v[64:65], v[174:175] op_sel_hi:[1,0]
	v_pk_mul_f32 v[66:67], v[66:67], v[174:175] op_sel_hi:[1,0]
	v_cvt_pk_bf16_f32 v116, v68, v69
	v_cvt_pk_bf16_f32 v117, v70, v71
	v_cvt_pk_bf16_f32 v118, v64, v65
	v_cvt_pk_bf16_f32 v119, v66, v67
	global_store_dwordx4 v[150:151], v[116:119], off offset:256
	v_lshl_add_u64 v[146:147], v[150:151], 0, s[0:1]
	s_waitcnt vmcnt(8)
	v_add_f32_e32 v176, v72, v73
	v_add_f32_e32 v177, v74, v75
	v_add_f32_e32 v176, v176, v177
	v_add_f32_e32 v178, v76, v77
	v_add_f32_e32 v179, v78, v79
	v_add_f32_e32 v178, v178, v179
	v_add_f32_e32 v180, v80, v81
	v_add_f32_e32 v181, v82, v83
	v_add_f32_e32 v180, v180, v181
	v_add_f32_e32 v182, v84, v85
	v_add_f32_e32 v183, v86, v87
	v_add_f32_e32 v182, v182, v183
	ds_swizzle_b32 v177, v176 offset:swizzle(SWAP,16)
	ds_swizzle_b32 v179, v178 offset:swizzle(SWAP,16)
	ds_swizzle_b32 v181, v180 offset:swizzle(SWAP,16)
	ds_swizzle_b32 v183, v182 offset:swizzle(SWAP,16)
	s_waitcnt lgkmcnt(0)
; #define GAS __attribute__((address_space(1)))
; DI float sum_xor32(float v) { auto rr = __builtin_amdgcn_permlane32_swap(__float_as_uint(v), __float_as_uint(v), false, false); return __uint_as_float(rr[0]) + __uint_as_float(rr[1]); }
; DI float row_rstd(const float* ssq, int row, int fq) {
;     const f32x4 v = *(const GAS f32x4*)(ssq + (size_t)row * 16 + 4 * fq);
;     float s = (v.x + v.y) + (v.z + v.w);
;     s += lane_xor<16>(s); s = sum_xor32(s);
;     return 1.0f / sqrtf(s * (1.0f / 1024.0f) + 1e-6f);
	v_add_f32_e32 v176, v176, v177
	v_add_f32_e32 v178, v178, v179
	v_add_f32_e32 v180, v180, v181
	v_add_f32_e32 v182, v182, v183
	v_mov_b32_e32 v177, v176
	v_mov_b32_e32 v179, v178
	v_mov_b32_e32 v181, v180
	v_mov_b32_e32 v183, v182
	s_nop 1
	v_permlane32_swap_b32_e32 v176, v177
	v_permlane32_swap_b32_e32 v178, v179
	v_permlane32_swap_b32_e32 v180, v181
	v_permlane32_swap_b32_e32 v182, v183
	v_add_f32_e32 v176, v176, v177
	v_add_f32_e32 v178, v178, v179
	v_add_f32_e32 v180, v180, v181
	v_add_f32_e32 v182, v182, v183
	v_fmamk_f32 v176, v176, 0x3a800000, v246
	v_cmp_gt_f32_e32 vcc, s33, v176
	v_mul_f32_e32 v208, 0x4f800000, v176
	s_nop 0
	v_cndmask_b32_e32 v176, v176, v208, vcc
	v_sqrt_f32_e32 v208, v176
	s_nop 0
	v_add_u32_e32 v209, -1, v208
	v_fma_f32 v210, -v209, v208, v176
	v_cmp_ge_f32_e64 s[98:99], 0, v210
	v_add_u32_e32 v210, 1, v208
	s_nop 0
	v_cndmask_b32_e64 v209, v208, v209, s[98:99]
	v_fma_f32 v208, -v210, v208, v176
	v_cmp_lt_f32_e64 s[98:99], 0, v208
	s_nop 1
	v_cndmask_b32_e64 v208, v209, v210, s[98:99]
	v_mul_f32_e32 v209, 0x37800000, v208
	v_cndmask_b32_e32 v208, v208, v209, vcc
	v_cmp_class_f32_e32 vcc, v176, v213
	s_nop 1
	v_cndmask_b32_e32 v176, v208, v176, vcc
	v_div_scale_f32 v208, s[98:99], v176, v176, 1.0
	v_rcp_f32_e32 v209, v208
	s_nop 0
	v_fma_f32 v210, -v208, v209, 1.0
	v_fmac_f32_e32 v209, v210, v209
	v_div_scale_f32 v210, vcc, 1.0, v176, 1.0
	v_mul_f32_e32 v211, v210, v209
	v_fma_f32 v212, -v208, v211, v210
	v_fmac_f32_e32 v211, v212, v209
	v_fma_f32 v208, -v208, v211, v210
	v_div_fmas_f32 v208, v208, v209, v211
	v_div_fixup_f32 v176, v208, v176, 1.0
	v_fmamk_f32 v178, v178, 0x3a800000, v246
	v_cmp_gt_f32_e32 vcc, s33, v178
	v_mul_f32_e32 v208, 0x4f800000, v178
	s_nop 0
	v_cndmask_b32_e32 v178, v178, v208, vcc
	v_sqrt_f32_e32 v208, v178
	s_nop 0
	v_add_u32_e32 v209, -1, v208
	v_fma_f32 v210, -v209, v208, v178
	v_cmp_ge_f32_e64 s[98:99], 0, v210
	v_add_u32_e32 v210, 1, v208
	s_nop 0
	v_cndmask_b32_e64 v209, v208, v209, s[98:99]
	v_fma_f32 v208, -v210, v208, v178
	v_cmp_lt_f32_e64 s[98:99], 0, v208
	s_nop 1
	v_cndmask_b32_e64 v208, v209, v210, s[98:99]
	v_mul_f32_e32 v209, 0x37800000, v208
	v_cndmask_b32_e32 v208, v208, v209, vcc
	v_cmp_class_f32_e32 vcc, v178, v213
	s_nop 1
	v_cndmask_b32_e32 v178, v208, v178, vcc
	v_div_scale_f32 v208, s[98:99], v178, v178, 1.0
	v_rcp_f32_e32 v209, v208
	s_nop 0
	v_fma_f32 v210, -v208, v209, 1.0
	v_fmac_f32_e32 v209, v210, v209
	v_div_scale_f32 v210, vcc, 1.0, v178, 1.0
	v_mul_f32_e32 v211, v210, v209
	v_fma_f32 v212, -v208, v211, v210
	v_fmac_f32_e32 v211, v212, v209
	v_fma_f32 v208, -v208, v211, v210
	v_div_fmas_f32 v208, v208, v209, v211
	v_div_fixup_f32 v178, v208, v178, 1.0
	v_fmamk_f32 v180, v180, 0x3a800000, v246
	v_cmp_gt_f32_e32 vcc, s33, v180
	v_mul_f32_e32 v208, 0x4f800000, v180
	s_nop 0
	v_cndmask_b32_e32 v180, v180, v208, vcc
	v_sqrt_f32_e32 v208, v180
	s_nop 0
	v_add_u32_e32 v209, -1, v208
	v_fma_f32 v210, -v209, v208, v180
	v_cmp_ge_f32_e64 s[98:99], 0, v210
	v_add_u32_e32 v210, 1, v208
	s_nop 0
	v_cndmask_b32_e64 v209, v208, v209, s[98:99]
	v_fma_f32 v208, -v210, v208, v180
	v_cmp_lt_f32_e64 s[98:99], 0, v208
	s_nop 1
	v_cndmask_b32_e64 v208, v209, v210, s[98:99]
	v_mul_f32_e32 v209, 0x37800000, v208
	v_cndmask_b32_e32 v208, v208, v209, vcc
	v_cmp_class_f32_e32 vcc, v180, v213
	s_nop 1
	v_cndmask_b32_e32 v180, v208, v180, vcc
	v_div_scale_f32 v208, s[98:99], v180, v180, 1.0
	v_rcp_f32_e32 v209, v208
	s_nop 0
	v_fma_f32 v210, -v208, v209, 1.0
	v_fmac_f32_e32 v209, v210, v209
	v_div_scale_f32 v210, vcc, 1.0, v180, 1.0
	v_mul_f32_e32 v211, v210, v209
	v_fma_f32 v212, -v208, v211, v210
	v_fmac_f32_e32 v211, v212, v209
	v_fma_f32 v208, -v208, v211, v210
	v_div_fmas_f32 v208, v208, v209, v211
	v_div_fixup_f32 v180, v208, v180, 1.0
	v_fmamk_f32 v182, v182, 0x3a800000, v246
	v_cmp_gt_f32_e32 vcc, s33, v182
	v_mul_f32_e32 v208, 0x4f800000, v182
	s_nop 0
	v_cndmask_b32_e32 v182, v182, v208, vcc
	v_sqrt_f32_e32 v208, v182
	s_nop 0
	v_add_u32_e32 v209, -1, v208
	v_fma_f32 v210, -v209, v208, v182
	v_cmp_ge_f32_e64 s[98:99], 0, v210
	v_add_u32_e32 v210, 1, v208
	s_nop 0
	v_cndmask_b32_e64 v209, v208, v209, s[98:99]
	v_fma_f32 v208, -v210, v208, v182
	v_cmp_lt_f32_e64 s[98:99], 0, v208
	s_nop 1
	v_cndmask_b32_e64 v208, v209, v210, s[98:99]
	v_mul_f32_e32 v209, 0x37800000, v208
	v_cndmask_b32_e32 v208, v208, v209, vcc
	v_cmp_class_f32_e32 vcc, v182, v213
	s_nop 1
	v_cndmask_b32_e32 v182, v208, v182, vcc
	v_div_scale_f32 v208, s[98:99], v182, v182, 1.0
	v_rcp_f32_e32 v209, v208
	s_nop 0
	v_fma_f32 v210, -v208, v209, 1.0
	v_fmac_f32_e32 v209, v210, v209
	v_div_scale_f32 v210, vcc, 1.0, v182, 1.0
	v_mul_f32_e32 v211, v210, v209
	v_fma_f32 v212, -v208, v211, v210
	v_fmac_f32_e32 v211, v212, v209
	v_fma_f32 v208, -v208, v211, v210
	v_div_fmas_f32 v208, v208, v209, v211
	v_div_fixup_f32 v182, v208, v182, 1.0
	v_pk_mul_f32 v[60:61], v[60:61], v[176:177] op_sel_hi:[1,0]
	v_pk_mul_f32 v[62:63], v[62:63], v[176:177] op_sel_hi:[1,0]
	v_pk_mul_f32 v[56:57], v[56:57], v[176:177] op_sel_hi:[1,0]
	v_pk_mul_f32 v[58:59], v[58:59], v[176:177] op_sel_hi:[1,0]
	v_cvt_pk_bf16_f32 v104, v60, v61
	v_cvt_pk_bf16_f32 v105, v62, v63
	v_cvt_pk_bf16_f32 v106, v56, v57
	v_cvt_pk_bf16_f32 v107, v58, v59
	global_store_dwordx4 v[146:147], v[104:107], off
	v_pk_mul_f32 v[52:53], v[52:53], v[176:177] op_sel_hi:[1,0]
	v_pk_mul_f32 v[54:55], v[54:55], v[176:177] op_sel_hi:[1,0]
	v_pk_mul_f32 v[48:49], v[48:49], v[176:177] op_sel_hi:[1,0]
	v_pk_mul_f32 v[50:51], v[50:51], v[176:177] op_sel_hi:[1,0]
	v_cvt_pk_bf16_f32 v108, v52, v53
	v_cvt_pk_bf16_f32 v109, v54, v55
	v_cvt_pk_bf16_f32 v110, v48, v49
; __device__ __forceinline__ unsigned cvt_pk_bf16(float lo, float hi) { unsigned r; asm volatile("v_cvt_pk_bf16_f32 %0, %1, %2" : "=v"(r) : "v"(lo), "v"(hi)); return r; }
; #define GAS __attribute__((address_space(1)))
;     DI void operator()(AccRef acc, const pg8::Unit& u, int wr, int wc, int, int) const {
;     ...
;                 { const float rsk = (kind == 4) ? rs * -1.4426950408889634f : rs; v0 = v0 * rsk; v1 = v1 * rsk; }
;                 if (kind < 2) {
;                     if (rot) {
;                         f32x4 p0, p1;
; #pragma unroll
;                         for (int e = 0; e < 4; ++e) { p0[e] = lane_xor<16>(v0[e]); p1[e] = lane_xor<16>(v1[e]); }
;                         if (fq == 0) { v0 = v0 * c0 - p0 * s0; v1 = v1 * c1 - p1 * s1; }
;                         else if (fq == 1) { v0 = v0 * c0 + p0 * s0; v1 = v1 * c1 + p1 * s1; }
;                     }
;                     v0 = v0 * qs; v1 = v1 * qs;
;                 } else if (kind == 3) {
;                     f32x2 a = pg8::gelu_pk((f32x2){v0[0], v0[1]}), b = pg8::gelu_pk((f32x2){v0[2], v0[3]}), c = pg8::gelu_pk((f32x2){v1[0], v1[1]}), d = pg8::gelu_pk((f32x2){v1[2], v1[3]});
;                     v0 = (f32x4){a.x, a.y, b.x, b.y}; v1 = (f32x4){c.x, c.y, d.x, d.y};
;                 } else if (kind == 4) {
; #pragma unroll
;                     for (int e = 0; e < 4; ++e) { v0[e] = __builtin_amdgcn_rcpf(1.0f + __builtin_amdgcn_exp2f(v0[e])); v1[e] = __builtin_amdgcn_rcpf(1.0f + __builtin_amdgcn_exp2f(v1[e])); }
;                 }
;                 u32x4 w; w.x = cvt_pk_bf16(v0[0], v0[1]); w.y = cvt_pk_bf16(v0[2], v0[3]); w.z = cvt_pk_bf16(v1[0], v1[1]); w.w = cvt_pk_bf16(v1[2], v1[3]);
;                 *(GAS u32x4*)(dummy ? dummy + lane_ * 8 : Z + (size_t)lrow * ldz + col) = w;
	v_cvt_pk_bf16_f32 v111, v50, v51
	global_store_dwordx4 v[146:147], v[108:111], off offset:256
	v_lshl_add_u64 v[150:151], v[146:147], 0, s[2:3]
	v_pk_mul_f32 v[44:45], v[44:45], v[178:179] op_sel_hi:[1,0]
	v_pk_mul_f32 v[46:47], v[46:47], v[178:179] op_sel_hi:[1,0]
	v_pk_mul_f32 v[40:41], v[40:41], v[178:179] op_sel_hi:[1,0]
	v_pk_mul_f32 v[42:43], v[42:43], v[178:179] op_sel_hi:[1,0]
	v_cvt_pk_bf16_f32 v112, v44, v45
	v_cvt_pk_bf16_f32 v113, v46, v47
	v_cvt_pk_bf16_f32 v114, v40, v41
	v_cvt_pk_bf16_f32 v115, v42, v43
	global_store_dwordx4 v[150:151], v[112:115], off
	v_pk_mul_f32 v[36:37], v[36:37], v[178:179] op_sel_hi:[1,0]
	v_pk_mul_f32 v[38:39], v[38:39], v[178:179] op_sel_hi:[1,0]
	v_pk_mul_f32 v[32:33], v[32:33], v[178:179] op_sel_hi:[1,0]
	v_pk_mul_f32 v[34:35], v[34:35], v[178:179] op_sel_hi:[1,0]
	v_cvt_pk_bf16_f32 v116, v36, v37
	v_cvt_pk_bf16_f32 v117, v38, v39
	v_cvt_pk_bf16_f32 v118, v32, v33
	v_cvt_pk_bf16_f32 v119, v34, v35
	global_store_dwordx4 v[150:151], v[116:119], off offset:256
	v_lshl_add_u64 v[146:147], v[150:151], 0, s[2:3]
	v_pk_mul_f32 v[28:29], v[28:29], v[180:181] op_sel_hi:[1,0]
	v_pk_mul_f32 v[30:31], v[30:31], v[180:181] op_sel_hi:[1,0]
	v_pk_mul_f32 v[24:25], v[24:25], v[180:181] op_sel_hi:[1,0]
	v_pk_mul_f32 v[26:27], v[26:27], v[180:181] op_sel_hi:[1,0]
	v_cvt_pk_bf16_f32 v104, v28, v29
	v_cvt_pk_bf16_f32 v105, v30, v31
	v_cvt_pk_bf16_f32 v106, v24, v25
	v_cvt_pk_bf16_f32 v107, v26, v27
	global_store_dwordx4 v[146:147], v[104:107], off
	v_pk_mul_f32 v[20:21], v[20:21], v[180:181] op_sel_hi:[1,0]
	v_pk_mul_f32 v[22:23], v[22:23], v[180:181] op_sel_hi:[1,0]
	v_pk_mul_f32 v[16:17], v[16:17], v[180:181] op_sel_hi:[1,0]
	v_pk_mul_f32 v[18:19], v[18:19], v[180:181] op_sel_hi:[1,0]
	v_cvt_pk_bf16_f32 v108, v20, v21
	v_cvt_pk_bf16_f32 v109, v22, v23
	v_cvt_pk_bf16_f32 v110, v16, v17
	v_cvt_pk_bf16_f32 v111, v18, v19
	global_store_dwordx4 v[146:147], v[108:111], off offset:256
	v_lshl_add_u64 v[150:151], v[146:147], 0, s[2:3]
	v_pk_mul_f32 v[12:13], v[12:13], v[182:183] op_sel_hi:[1,0]
	v_pk_mul_f32 v[14:15], v[14:15], v[182:183] op_sel_hi:[1,0]
	v_pk_mul_f32 v[8:9], v[8:9], v[182:183] op_sel_hi:[1,0]
	v_pk_mul_f32 v[10:11], v[10:11], v[182:183] op_sel_hi:[1,0]
	v_cvt_pk_bf16_f32 v112, v12, v13
	v_cvt_pk_bf16_f32 v113, v14, v15
	v_cvt_pk_bf16_f32 v114, v8, v9
	v_cvt_pk_bf16_f32 v115, v10, v11
	global_store_dwordx4 v[150:151], v[112:115], off
	v_pk_mul_f32 v[4:5], v[4:5], v[182:183] op_sel_hi:[1,0]
	v_pk_mul_f32 v[6:7], v[6:7], v[182:183] op_sel_hi:[1,0]
	v_pk_mul_f32 v[0:1], v[0:1], v[182:183] op_sel_hi:[1,0]
	v_pk_mul_f32 v[2:3], v[2:3], v[182:183] op_sel_hi:[1,0]
	v_cvt_pk_bf16_f32 v116, v4, v5
	v_cvt_pk_bf16_f32 v117, v6, v7
	v_cvt_pk_bf16_f32 v118, v0, v1
	v_cvt_pk_bf16_f32 v119, v2, v3
	global_store_dwordx4 v[150:151], v[116:119], off offset:256
	s_branch .Llean_F_exit
.Llean_F_sig:
	v_mul_f32_e32 v168, 0xbfb8aa3b, v168
	v_mul_f32_e32 v170, 0xbfb8aa3b, v170
	v_mul_f32_e32 v172, 0xbfb8aa3b, v172
	v_mul_f32_e32 v174, 0xbfb8aa3b, v174
	v_pk_mul_f32 v[188:189], v[188:189], v[168:169] op_sel_hi:[1,0]
	v_pk_mul_f32 v[190:191], v[190:191], v[168:169] op_sel_hi:[1,0]
	v_pk_mul_f32 v[184:185], v[184:185], v[168:169] op_sel_hi:[1,0]
	v_pk_mul_f32 v[186:187], v[186:187], v[168:169] op_sel_hi:[1,0]
	v_exp_f32_e32 v188, v188
	v_exp_f32_e32 v189, v189
	v_exp_f32_e32 v190, v190
	v_exp_f32_e32 v191, v191
	v_exp_f32_e32 v184, v184
	v_exp_f32_e32 v185, v185
	v_exp_f32_e32 v186, v186
	v_exp_f32_e32 v187, v187
	v_add_f32_e32 v188, 1.0, v188
	v_add_f32_e32 v189, 1.0, v189
	v_add_f32_e32 v190, 1.0, v190
	v_add_f32_e32 v191, 1.0, v191
	v_add_f32_e32 v184, 1.0, v184
	v_add_f32_e32 v185, 1.0, v185
	v_add_f32_e32 v186, 1.0, v186
	v_add_f32_e32 v187, 1.0, v187
	v_rcp_f32_e32 v188, v188
	v_rcp_f32_e32 v189, v189
	v_rcp_f32_e32 v190, v190
	v_rcp_f32_e32 v191, v191
	v_rcp_f32_e32 v184, v184
	v_rcp_f32_e32 v185, v185
	v_rcp_f32_e32 v186, v186
	v_rcp_f32_e32 v187, v187
	s_nop 0
	v_cvt_pk_bf16_f32 v104, v188, v189
	v_cvt_pk_bf16_f32 v105, v190, v191
	v_cvt_pk_bf16_f32 v106, v184, v185
	v_cvt_pk_bf16_f32 v107, v186, v187
	global_store_dwordx4 v[146:147], v[104:107], off
	v_pk_mul_f32 v[164:165], v[164:165], v[168:169] op_sel_hi:[1,0]
	v_pk_mul_f32 v[166:167], v[166:167], v[168:169] op_sel_hi:[1,0]
	v_pk_mul_f32 v[160:161], v[160:161], v[168:169] op_sel_hi:[1,0]
	v_pk_mul_f32 v[162:163], v[162:163], v[168:169] op_sel_hi:[1,0]
	v_exp_f32_e32 v164, v164
	v_exp_f32_e32 v165, v165
	v_exp_f32_e32 v166, v166
	v_exp_f32_e32 v167, v167
	v_exp_f32_e32 v160, v160
	v_exp_f32_e32 v161, v161
	v_exp_f32_e32 v162, v162
	v_exp_f32_e32 v163, v163
	v_add_f32_e32 v164, 1.0, v164
	v_add_f32_e32 v165, 1.0, v165
	v_add_f32_e32 v166, 1.0, v166
	v_add_f32_e32 v167, 1.0, v167
	v_add_f32_e32 v160, 1.0, v160
	v_add_f32_e32 v161, 1.0, v161
	v_add_f32_e32 v162, 1.0, v162
	v_add_f32_e32 v163, 1.0, v163
	v_rcp_f32_e32 v164, v164
	v_rcp_f32_e32 v165, v165
	v_rcp_f32_e32 v166, v166
	v_rcp_f32_e32 v167, v167
	v_rcp_f32_e32 v160, v160
	v_rcp_f32_e32 v161, v161
	v_rcp_f32_e32 v162, v162
	v_rcp_f32_e32 v163, v163
	s_nop 0
	v_cvt_pk_bf16_f32 v108, v164, v165
	v_cvt_pk_bf16_f32 v109, v166, v167
	v_cvt_pk_bf16_f32 v110, v160, v161
	v_cvt_pk_bf16_f32 v111, v162, v163
	global_store_dwordx4 v[146:147], v[108:111], off offset:256
	v_lshl_add_u64 v[150:151], v[146:147], 0, s[2:3]
	v_pk_mul_f32 v[156:157], v[156:157], v[170:171] op_sel_hi:[1,0]
	v_pk_mul_f32 v[158:159], v[158:159], v[170:171] op_sel_hi:[1,0]
	v_pk_mul_f32 v[152:153], v[152:153], v[170:171] op_sel_hi:[1,0]
	v_pk_mul_f32 v[154:155], v[154:155], v[170:171] op_sel_hi:[1,0]
	v_exp_f32_e32 v156, v156
	v_exp_f32_e32 v157, v157
; __device__ __forceinline__ unsigned cvt_pk_bf16(float lo, float hi) { unsigned r; asm volatile("v_cvt_pk_bf16_f32 %0, %1, %2" : "=v"(r) : "v"(lo), "v"(hi)); return r; }
; #define GAS __attribute__((address_space(1)))
;     DI void operator()(AccRef acc, const pg8::Unit& u, int wr, int wc, int, int) const {
;     ...
;                 } else if (kind == 4) {
; #pragma unroll
;                     for (int e = 0; e < 4; ++e) { v0[e] = __builtin_amdgcn_rcpf(1.0f + __builtin_amdgcn_exp2f(v0[e])); v1[e] = __builtin_amdgcn_rcpf(1.0f + __builtin_amdgcn_exp2f(v1[e])); }
;                 }
;                 u32x4 w; w.x = cvt_pk_bf16(v0[0], v0[1]); w.y = cvt_pk_bf16(v0[2], v0[3]); w.z = cvt_pk_bf16(v1[0], v1[1]); w.w = cvt_pk_bf16(v1[2], v1[3]);
;                 *(GAS u32x4*)(dummy ? dummy + lane_ * 8 : Z + (size_t)lrow * ldz + col) = w;
	v_exp_f32_e32 v158, v158
	v_exp_f32_e32 v159, v159
	v_exp_f32_e32 v152, v152
	v_exp_f32_e32 v153, v153
	v_exp_f32_e32 v154, v154
	v_exp_f32_e32 v155, v155
	v_add_f32_e32 v156, 1.0, v156
	v_add_f32_e32 v157, 1.0, v157
	v_add_f32_e32 v158, 1.0, v158
	v_add_f32_e32 v159, 1.0, v159
	v_add_f32_e32 v152, 1.0, v152
	v_add_f32_e32 v153, 1.0, v153
	v_add_f32_e32 v154, 1.0, v154
	v_add_f32_e32 v155, 1.0, v155
	v_rcp_f32_e32 v156, v156
	v_rcp_f32_e32 v157, v157
	v_rcp_f32_e32 v158, v158
	v_rcp_f32_e32 v159, v159
	v_rcp_f32_e32 v152, v152
	v_rcp_f32_e32 v153, v153
	v_rcp_f32_e32 v154, v154
	v_rcp_f32_e32 v155, v155
	s_nop 0
	v_cvt_pk_bf16_f32 v112, v156, v157
	v_cvt_pk_bf16_f32 v113, v158, v159
	v_cvt_pk_bf16_f32 v114, v152, v153
	v_cvt_pk_bf16_f32 v115, v154, v155
	global_store_dwordx4 v[150:151], v[112:115], off
	v_pk_mul_f32 v[132:133], v[132:133], v[170:171] op_sel_hi:[1,0]
	v_pk_mul_f32 v[134:135], v[134:135], v[170:171] op_sel_hi:[1,0]
	v_pk_mul_f32 v[128:129], v[128:129], v[170:171] op_sel_hi:[1,0]
	v_pk_mul_f32 v[130:131], v[130:131], v[170:171] op_sel_hi:[1,0]
	v_exp_f32_e32 v132, v132
	v_exp_f32_e32 v133, v133
	v_exp_f32_e32 v134, v134
	v_exp_f32_e32 v135, v135
	v_exp_f32_e32 v128, v128
	v_exp_f32_e32 v129, v129
	v_exp_f32_e32 v130, v130
	v_exp_f32_e32 v131, v131
	v_add_f32_e32 v132, 1.0, v132
	v_add_f32_e32 v133, 1.0, v133
	v_add_f32_e32 v134, 1.0, v134
	v_add_f32_e32 v135, 1.0, v135
	v_add_f32_e32 v128, 1.0, v128
	v_add_f32_e32 v129, 1.0, v129
	v_add_f32_e32 v130, 1.0, v130
	v_add_f32_e32 v131, 1.0, v131
	v_rcp_f32_e32 v132, v132
	v_rcp_f32_e32 v133, v133
	v_rcp_f32_e32 v134, v134
	v_rcp_f32_e32 v135, v135
	v_rcp_f32_e32 v128, v128
	v_rcp_f32_e32 v129, v129
	v_rcp_f32_e32 v130, v130
	v_rcp_f32_e32 v131, v131
	s_nop 0
	v_cvt_pk_bf16_f32 v116, v132, v133
	v_cvt_pk_bf16_f32 v117, v134, v135
	v_cvt_pk_bf16_f32 v118, v128, v129
	v_cvt_pk_bf16_f32 v119, v130, v131
	global_store_dwordx4 v[150:151], v[116:119], off offset:256
	v_lshl_add_u64 v[146:147], v[150:151], 0, s[2:3]
	v_pk_mul_f32 v[124:125], v[124:125], v[172:173] op_sel_hi:[1,0]
	v_pk_mul_f32 v[126:127], v[126:127], v[172:173] op_sel_hi:[1,0]
	v_pk_mul_f32 v[120:121], v[120:121], v[172:173] op_sel_hi:[1,0]
	v_pk_mul_f32 v[122:123], v[122:123], v[172:173] op_sel_hi:[1,0]
	v_exp_f32_e32 v124, v124
	v_exp_f32_e32 v125, v125
	v_exp_f32_e32 v126, v126
	v_exp_f32_e32 v127, v127
	v_exp_f32_e32 v120, v120
	v_exp_f32_e32 v121, v121
	v_exp_f32_e32 v122, v122
	v_exp_f32_e32 v123, v123
	v_add_f32_e32 v124, 1.0, v124
	v_add_f32_e32 v125, 1.0, v125
	v_add_f32_e32 v126, 1.0, v126
	v_add_f32_e32 v127, 1.0, v127
	v_add_f32_e32 v120, 1.0, v120
	v_add_f32_e32 v121, 1.0, v121
	v_add_f32_e32 v122, 1.0, v122
	v_add_f32_e32 v123, 1.0, v123
	v_rcp_f32_e32 v124, v124
	v_rcp_f32_e32 v125, v125
	v_rcp_f32_e32 v126, v126
	v_rcp_f32_e32 v127, v127
	v_rcp_f32_e32 v120, v120
	v_rcp_f32_e32 v121, v121
	v_rcp_f32_e32 v122, v122
	v_rcp_f32_e32 v123, v123
	s_nop 0
	v_cvt_pk_bf16_f32 v104, v124, v125
	v_cvt_pk_bf16_f32 v105, v126, v127
	v_cvt_pk_bf16_f32 v106, v120, v121
	v_cvt_pk_bf16_f32 v107, v122, v123
	global_store_dwordx4 v[146:147], v[104:107], off
	v_pk_mul_f32 v[100:101], v[100:101], v[172:173] op_sel_hi:[1,0]
	v_pk_mul_f32 v[102:103], v[102:103], v[172:173] op_sel_hi:[1,0]
	v_pk_mul_f32 v[96:97], v[96:97], v[172:173] op_sel_hi:[1,0]
	v_pk_mul_f32 v[98:99], v[98:99], v[172:173] op_sel_hi:[1,0]
	v_exp_f32_e32 v100, v100
	v_exp_f32_e32 v101, v101
	v_exp_f32_e32 v102, v102
	v_exp_f32_e32 v103, v103
	v_exp_f32_e32 v96, v96
	v_exp_f32_e32 v97, v97
	v_exp_f32_e32 v98, v98
	v_exp_f32_e32 v99, v99
	v_add_f32_e32 v100, 1.0, v100
	v_add_f32_e32 v101, 1.0, v101
	v_add_f32_e32 v102, 1.0, v102
	v_add_f32_e32 v103, 1.0, v103
	v_add_f32_e32 v96, 1.0, v96
	v_add_f32_e32 v97, 1.0, v97
	v_add_f32_e32 v98, 1.0, v98
	v_add_f32_e32 v99, 1.0, v99
	v_rcp_f32_e32 v100, v100
	v_rcp_f32_e32 v101, v101
	v_rcp_f32_e32 v102, v102
	v_rcp_f32_e32 v103, v103
	v_rcp_f32_e32 v96, v96
	v_rcp_f32_e32 v97, v97
	v_rcp_f32_e32 v98, v98
	v_rcp_f32_e32 v99, v99
	s_nop 0
	v_cvt_pk_bf16_f32 v108, v100, v101
	v_cvt_pk_bf16_f32 v109, v102, v103
	v_cvt_pk_bf16_f32 v110, v96, v97
	v_cvt_pk_bf16_f32 v111, v98, v99
	global_store_dwordx4 v[146:147], v[108:111], off offset:256
	v_lshl_add_u64 v[150:151], v[146:147], 0, s[2:3]
	v_pk_mul_f32 v[92:93], v[92:93], v[174:175] op_sel_hi:[1,0]
	v_pk_mul_f32 v[94:95], v[94:95], v[174:175] op_sel_hi:[1,0]
	v_pk_mul_f32 v[88:89], v[88:89], v[174:175] op_sel_hi:[1,0]
	v_pk_mul_f32 v[90:91], v[90:91], v[174:175] op_sel_hi:[1,0]
	v_exp_f32_e32 v92, v92
	v_exp_f32_e32 v93, v93
	v_exp_f32_e32 v94, v94
	v_exp_f32_e32 v95, v95
	v_exp_f32_e32 v88, v88
	v_exp_f32_e32 v89, v89
	v_exp_f32_e32 v90, v90
	v_exp_f32_e32 v91, v91
	v_add_f32_e32 v92, 1.0, v92
	v_add_f32_e32 v93, 1.0, v93
	v_add_f32_e32 v94, 1.0, v94
	v_add_f32_e32 v95, 1.0, v95
	v_add_f32_e32 v88, 1.0, v88
	v_add_f32_e32 v89, 1.0, v89
	v_add_f32_e32 v90, 1.0, v90
	v_add_f32_e32 v91, 1.0, v91
	v_rcp_f32_e32 v92, v92
	v_rcp_f32_e32 v93, v93
	v_rcp_f32_e32 v94, v94
	v_rcp_f32_e32 v95, v95
	v_rcp_f32_e32 v88, v88
	v_rcp_f32_e32 v89, v89
	v_rcp_f32_e32 v90, v90
	v_rcp_f32_e32 v91, v91
	s_nop 0
	v_cvt_pk_bf16_f32 v112, v92, v93
	v_cvt_pk_bf16_f32 v113, v94, v95
	v_cvt_pk_bf16_f32 v114, v88, v89
	v_cvt_pk_bf16_f32 v115, v90, v91
	global_store_dwordx4 v[150:151], v[112:115], off
	v_pk_mul_f32 v[68:69], v[68:69], v[174:175] op_sel_hi:[1,0]
	v_pk_mul_f32 v[70:71], v[70:71], v[174:175] op_sel_hi:[1,0]
	v_pk_mul_f32 v[64:65], v[64:65], v[174:175] op_sel_hi:[1,0]
	v_pk_mul_f32 v[66:67], v[66:67], v[174:175] op_sel_hi:[1,0]
	v_exp_f32_e32 v68, v68
	v_exp_f32_e32 v69, v69
	v_exp_f32_e32 v70, v70
	v_exp_f32_e32 v71, v71
	v_exp_f32_e32 v64, v64
	v_exp_f32_e32 v65, v65
	v_exp_f32_e32 v66, v66
	v_exp_f32_e32 v67, v67
	v_add_f32_e32 v68, 1.0, v68
	v_add_f32_e32 v69, 1.0, v69
	v_add_f32_e32 v70, 1.0, v70
	v_add_f32_e32 v71, 1.0, v71
	v_add_f32_e32 v64, 1.0, v64
	v_add_f32_e32 v65, 1.0, v65
	v_add_f32_e32 v66, 1.0, v66
	v_add_f32_e32 v67, 1.0, v67
	v_rcp_f32_e32 v68, v68
	v_rcp_f32_e32 v69, v69
	v_rcp_f32_e32 v70, v70
	v_rcp_f32_e32 v71, v71
	v_rcp_f32_e32 v64, v64
	v_rcp_f32_e32 v65, v65
	v_rcp_f32_e32 v66, v66
	v_rcp_f32_e32 v67, v67
	s_nop 0
	v_cvt_pk_bf16_f32 v116, v68, v69
	v_cvt_pk_bf16_f32 v117, v70, v71
	v_cvt_pk_bf16_f32 v118, v64, v65
	v_cvt_pk_bf16_f32 v119, v66, v67
	global_store_dwordx4 v[150:151], v[116:119], off offset:256
	v_lshl_add_u64 v[146:147], v[150:151], 0, s[0:1]
	s_waitcnt vmcnt(8)
; #define GAS __attribute__((address_space(1)))
; DI float sum_xor32(float v) { auto rr = __builtin_amdgcn_permlane32_swap(__float_as_uint(v), __float_as_uint(v), false, false); return __uint_as_float(rr[0]) + __uint_as_float(rr[1]); }
; DI float row_rstd(const float* ssq, int row, int fq) {
;     const f32x4 v = *(const GAS f32x4*)(ssq + (size_t)row * 16 + 4 * fq);
;     float s = (v.x + v.y) + (v.z + v.w);
;     s += lane_xor<16>(s); s = sum_xor32(s);
;     return 1.0f / sqrtf(s * (1.0f / 1024.0f) + 1e-6f);
;     DI void operator()(AccRef acc, const pg8::Unit& u, int wr, int wc, int, int) const {
;     ...
;                 { const float rsk = (kind == 4) ? rs * -1.4426950408889634f : rs; v0 = v0 * rsk; v1 = v1 * rsk; }
	v_add_f32_e32 v176, v72, v73
	v_add_f32_e32 v177, v74, v75
	v_add_f32_e32 v176, v176, v177
	v_add_f32_e32 v178, v76, v77
	v_add_f32_e32 v179, v78, v79
	v_add_f32_e32 v178, v178, v179
	v_add_f32_e32 v180, v80, v81
	v_add_f32_e32 v181, v82, v83
	v_add_f32_e32 v180, v180, v181
	v_add_f32_e32 v182, v84, v85
	v_add_f32_e32 v183, v86, v87
	v_add_f32_e32 v182, v182, v183
	ds_swizzle_b32 v177, v176 offset:swizzle(SWAP,16)
	ds_swizzle_b32 v179, v178 offset:swizzle(SWAP,16)
	ds_swizzle_b32 v181, v180 offset:swizzle(SWAP,16)
	ds_swizzle_b32 v183, v182 offset:swizzle(SWAP,16)
	s_waitcnt lgkmcnt(0)
	v_add_f32_e32 v176, v176, v177
	v_add_f32_e32 v178, v178, v179
	v_add_f32_e32 v180, v180, v181
	v_add_f32_e32 v182, v182, v183
	v_mov_b32_e32 v177, v176
	v_mov_b32_e32 v179, v178
	v_mov_b32_e32 v181, v180
	v_mov_b32_e32 v183, v182
	s_nop 1
	v_permlane32_swap_b32_e32 v176, v177
	v_permlane32_swap_b32_e32 v178, v179
	v_permlane32_swap_b32_e32 v180, v181
	v_permlane32_swap_b32_e32 v182, v183
	v_add_f32_e32 v176, v176, v177
	v_add_f32_e32 v178, v178, v179
	v_add_f32_e32 v180, v180, v181
	v_add_f32_e32 v182, v182, v183
	v_fmamk_f32 v176, v176, 0x3a800000, v246
	v_cmp_gt_f32_e32 vcc, s33, v176
	v_mul_f32_e32 v208, 0x4f800000, v176
	s_nop 0
	v_cndmask_b32_e32 v176, v176, v208, vcc
	v_sqrt_f32_e32 v208, v176
	s_nop 0
	v_add_u32_e32 v209, -1, v208
	v_fma_f32 v210, -v209, v208, v176
	v_cmp_ge_f32_e64 s[98:99], 0, v210
	v_add_u32_e32 v210, 1, v208
	s_nop 0
	v_cndmask_b32_e64 v209, v208, v209, s[98:99]
	v_fma_f32 v208, -v210, v208, v176
	v_cmp_lt_f32_e64 s[98:99], 0, v208
	s_nop 1
	v_cndmask_b32_e64 v208, v209, v210, s[98:99]
	v_mul_f32_e32 v209, 0x37800000, v208
	v_cndmask_b32_e32 v208, v208, v209, vcc
	v_cmp_class_f32_e32 vcc, v176, v213
	s_nop 1
	v_cndmask_b32_e32 v176, v208, v176, vcc
	v_div_scale_f32 v208, s[98:99], v176, v176, 1.0
	v_rcp_f32_e32 v209, v208
	s_nop 0
	v_fma_f32 v210, -v208, v209, 1.0
	v_fmac_f32_e32 v209, v210, v209
	v_div_scale_f32 v210, vcc, 1.0, v176, 1.0
	v_mul_f32_e32 v211, v210, v209
	v_fma_f32 v212, -v208, v211, v210
	v_fmac_f32_e32 v211, v212, v209
	v_fma_f32 v208, -v208, v211, v210
	v_div_fmas_f32 v208, v208, v209, v211
	v_div_fixup_f32 v176, v208, v176, 1.0
	v_fmamk_f32 v178, v178, 0x3a800000, v246
	v_cmp_gt_f32_e32 vcc, s33, v178
	v_mul_f32_e32 v208, 0x4f800000, v178
	s_nop 0
	v_cndmask_b32_e32 v178, v178, v208, vcc
	v_sqrt_f32_e32 v208, v178
	s_nop 0
	v_add_u32_e32 v209, -1, v208
	v_fma_f32 v210, -v209, v208, v178
	v_cmp_ge_f32_e64 s[98:99], 0, v210
	v_add_u32_e32 v210, 1, v208
	s_nop 0
	v_cndmask_b32_e64 v209, v208, v209, s[98:99]
	v_fma_f32 v208, -v210, v208, v178
	v_cmp_lt_f32_e64 s[98:99], 0, v208
	s_nop 1
	v_cndmask_b32_e64 v208, v209, v210, s[98:99]
	v_mul_f32_e32 v209, 0x37800000, v208
	v_cndmask_b32_e32 v208, v208, v209, vcc
	v_cmp_class_f32_e32 vcc, v178, v213
	s_nop 1
	v_cndmask_b32_e32 v178, v208, v178, vcc
	v_div_scale_f32 v208, s[98:99], v178, v178, 1.0
	v_rcp_f32_e32 v209, v208
	s_nop 0
	v_fma_f32 v210, -v208, v209, 1.0
	v_fmac_f32_e32 v209, v210, v209
	v_div_scale_f32 v210, vcc, 1.0, v178, 1.0
	v_mul_f32_e32 v211, v210, v209
	v_fma_f32 v212, -v208, v211, v210
	v_fmac_f32_e32 v211, v212, v209
	v_fma_f32 v208, -v208, v211, v210
	v_div_fmas_f32 v208, v208, v209, v211
	v_div_fixup_f32 v178, v208, v178, 1.0
	v_fmamk_f32 v180, v180, 0x3a800000, v246
	v_cmp_gt_f32_e32 vcc, s33, v180
	v_mul_f32_e32 v208, 0x4f800000, v180
	s_nop 0
	v_cndmask_b32_e32 v180, v180, v208, vcc
	v_sqrt_f32_e32 v208, v180
	s_nop 0
	v_add_u32_e32 v209, -1, v208
	v_fma_f32 v210, -v209, v208, v180
	v_cmp_ge_f32_e64 s[98:99], 0, v210
	v_add_u32_e32 v210, 1, v208
	s_nop 0
	v_cndmask_b32_e64 v209, v208, v209, s[98:99]
	v_fma_f32 v208, -v210, v208, v180
	v_cmp_lt_f32_e64 s[98:99], 0, v208
	s_nop 1
	v_cndmask_b32_e64 v208, v209, v210, s[98:99]
	v_mul_f32_e32 v209, 0x37800000, v208
	v_cndmask_b32_e32 v208, v208, v209, vcc
	v_cmp_class_f32_e32 vcc, v180, v213
	s_nop 1
	v_cndmask_b32_e32 v180, v208, v180, vcc
	v_div_scale_f32 v208, s[98:99], v180, v180, 1.0
	v_rcp_f32_e32 v209, v208
	s_nop 0
	v_fma_f32 v210, -v208, v209, 1.0
	v_fmac_f32_e32 v209, v210, v209
	v_div_scale_f32 v210, vcc, 1.0, v180, 1.0
	v_mul_f32_e32 v211, v210, v209
	v_fma_f32 v212, -v208, v211, v210
	v_fmac_f32_e32 v211, v212, v209
	v_fma_f32 v208, -v208, v211, v210
	v_div_fmas_f32 v208, v208, v209, v211
	v_div_fixup_f32 v180, v208, v180, 1.0
	v_fmamk_f32 v182, v182, 0x3a800000, v246
	v_cmp_gt_f32_e32 vcc, s33, v182
	v_mul_f32_e32 v208, 0x4f800000, v182
	s_nop 0
	v_cndmask_b32_e32 v182, v182, v208, vcc
	v_sqrt_f32_e32 v208, v182
	s_nop 0
	v_add_u32_e32 v209, -1, v208
	v_fma_f32 v210, -v209, v208, v182
	v_cmp_ge_f32_e64 s[98:99], 0, v210
	v_add_u32_e32 v210, 1, v208
	s_nop 0
	v_cndmask_b32_e64 v209, v208, v209, s[98:99]
	v_fma_f32 v208, -v210, v208, v182
	v_cmp_lt_f32_e64 s[98:99], 0, v208
	s_nop 1
	v_cndmask_b32_e64 v208, v209, v210, s[98:99]
	v_mul_f32_e32 v209, 0x37800000, v208
	v_cndmask_b32_e32 v208, v208, v209, vcc
	v_cmp_class_f32_e32 vcc, v182, v213
	s_nop 1
	v_cndmask_b32_e32 v182, v208, v182, vcc
	v_div_scale_f32 v208, s[98:99], v182, v182, 1.0
	v_rcp_f32_e32 v209, v208
	s_nop 0
	v_fma_f32 v210, -v208, v209, 1.0
	v_fmac_f32_e32 v209, v210, v209
	v_div_scale_f32 v210, vcc, 1.0, v182, 1.0
	v_mul_f32_e32 v211, v210, v209
	v_fma_f32 v212, -v208, v211, v210
	v_fmac_f32_e32 v211, v212, v209
	v_fma_f32 v208, -v208, v211, v210
	v_div_fmas_f32 v208, v208, v209, v211
	v_div_fixup_f32 v182, v208, v182, 1.0
	v_mul_f32_e32 v176, 0xbfb8aa3b, v176
	v_mul_f32_e32 v178, 0xbfb8aa3b, v178
	v_mul_f32_e32 v180, 0xbfb8aa3b, v180
	v_mul_f32_e32 v182, 0xbfb8aa3b, v182
	v_pk_mul_f32 v[60:61], v[60:61], v[176:177] op_sel_hi:[1,0]
; __device__ __forceinline__ unsigned cvt_pk_bf16(float lo, float hi) { unsigned r; asm volatile("v_cvt_pk_bf16_f32 %0, %1, %2" : "=v"(r) : "v"(lo), "v"(hi)); return r; }
; #define GAS __attribute__((address_space(1)))
;     DI void operator()(AccRef acc, const pg8::Unit& u, int wr, int wc, int, int) const {
;     ...
;                 } else if (kind == 4) {
; #pragma unroll
;                     for (int e = 0; e < 4; ++e) { v0[e] = __builtin_amdgcn_rcpf(1.0f + __builtin_amdgcn_exp2f(v0[e])); v1[e] = __builtin_amdgcn_rcpf(1.0f + __builtin_amdgcn_exp2f(v1[e])); }
;                 }
;                 u32x4 w; w.x = cvt_pk_bf16(v0[0], v0[1]); w.y = cvt_pk_bf16(v0[2], v0[3]); w.z = cvt_pk_bf16(v1[0], v1[1]); w.w = cvt_pk_bf16(v1[2], v1[3]);
;                 *(GAS u32x4*)(dummy ? dummy + lane_ * 8 : Z + (size_t)lrow * ldz + col) = w;
	v_pk_mul_f32 v[62:63], v[62:63], v[176:177] op_sel_hi:[1,0]
	v_pk_mul_f32 v[56:57], v[56:57], v[176:177] op_sel_hi:[1,0]
	v_pk_mul_f32 v[58:59], v[58:59], v[176:177] op_sel_hi:[1,0]
	v_exp_f32_e32 v60, v60
	v_exp_f32_e32 v61, v61
	v_exp_f32_e32 v62, v62
	v_exp_f32_e32 v63, v63
	v_exp_f32_e32 v56, v56
	v_exp_f32_e32 v57, v57
	v_exp_f32_e32 v58, v58
	v_exp_f32_e32 v59, v59
	v_add_f32_e32 v60, 1.0, v60
	v_add_f32_e32 v61, 1.0, v61
	v_add_f32_e32 v62, 1.0, v62
	v_add_f32_e32 v63, 1.0, v63
	v_add_f32_e32 v56, 1.0, v56
	v_add_f32_e32 v57, 1.0, v57
	v_add_f32_e32 v58, 1.0, v58
	v_add_f32_e32 v59, 1.0, v59
	v_rcp_f32_e32 v60, v60
	v_rcp_f32_e32 v61, v61
	v_rcp_f32_e32 v62, v62
	v_rcp_f32_e32 v63, v63
	v_rcp_f32_e32 v56, v56
	v_rcp_f32_e32 v57, v57
	v_rcp_f32_e32 v58, v58
	v_rcp_f32_e32 v59, v59
	s_nop 0
	v_cvt_pk_bf16_f32 v104, v60, v61
	v_cvt_pk_bf16_f32 v105, v62, v63
	v_cvt_pk_bf16_f32 v106, v56, v57
	v_cvt_pk_bf16_f32 v107, v58, v59
	global_store_dwordx4 v[146:147], v[104:107], off
	v_pk_mul_f32 v[52:53], v[52:53], v[176:177] op_sel_hi:[1,0]
	v_pk_mul_f32 v[54:55], v[54:55], v[176:177] op_sel_hi:[1,0]
	v_pk_mul_f32 v[48:49], v[48:49], v[176:177] op_sel_hi:[1,0]
	v_pk_mul_f32 v[50:51], v[50:51], v[176:177] op_sel_hi:[1,0]
	v_exp_f32_e32 v52, v52
	v_exp_f32_e32 v53, v53
	v_exp_f32_e32 v54, v54
	v_exp_f32_e32 v55, v55
	v_exp_f32_e32 v48, v48
	v_exp_f32_e32 v49, v49
	v_exp_f32_e32 v50, v50
	v_exp_f32_e32 v51, v51
	v_add_f32_e32 v52, 1.0, v52
	v_add_f32_e32 v53, 1.0, v53
	v_add_f32_e32 v54, 1.0, v54
	v_add_f32_e32 v55, 1.0, v55
	v_add_f32_e32 v48, 1.0, v48
	v_add_f32_e32 v49, 1.0, v49
	v_add_f32_e32 v50, 1.0, v50
	v_add_f32_e32 v51, 1.0, v51
	v_rcp_f32_e32 v52, v52
	v_rcp_f32_e32 v53, v53
	v_rcp_f32_e32 v54, v54
	v_rcp_f32_e32 v55, v55
	v_rcp_f32_e32 v48, v48
	v_rcp_f32_e32 v49, v49
	v_rcp_f32_e32 v50, v50
	v_rcp_f32_e32 v51, v51
	s_nop 0
	v_cvt_pk_bf16_f32 v108, v52, v53
	v_cvt_pk_bf16_f32 v109, v54, v55
	v_cvt_pk_bf16_f32 v110, v48, v49
	v_cvt_pk_bf16_f32 v111, v50, v51
	global_store_dwordx4 v[146:147], v[108:111], off offset:256
	v_lshl_add_u64 v[150:151], v[146:147], 0, s[2:3]
	v_pk_mul_f32 v[44:45], v[44:45], v[178:179] op_sel_hi:[1,0]
	v_pk_mul_f32 v[46:47], v[46:47], v[178:179] op_sel_hi:[1,0]
	v_pk_mul_f32 v[40:41], v[40:41], v[178:179] op_sel_hi:[1,0]
	v_pk_mul_f32 v[42:43], v[42:43], v[178:179] op_sel_hi:[1,0]
	v_exp_f32_e32 v44, v44
	v_exp_f32_e32 v45, v45
	v_exp_f32_e32 v46, v46
	v_exp_f32_e32 v47, v47
	v_exp_f32_e32 v40, v40
	v_exp_f32_e32 v41, v41
	v_exp_f32_e32 v42, v42
	v_exp_f32_e32 v43, v43
	v_add_f32_e32 v44, 1.0, v44
	v_add_f32_e32 v45, 1.0, v45
	v_add_f32_e32 v46, 1.0, v46
	v_add_f32_e32 v47, 1.0, v47
	v_add_f32_e32 v40, 1.0, v40
	v_add_f32_e32 v41, 1.0, v41
	v_add_f32_e32 v42, 1.0, v42
	v_add_f32_e32 v43, 1.0, v43
	v_rcp_f32_e32 v44, v44
	v_rcp_f32_e32 v45, v45
	v_rcp_f32_e32 v46, v46
	v_rcp_f32_e32 v47, v47
	v_rcp_f32_e32 v40, v40
	v_rcp_f32_e32 v41, v41
	v_rcp_f32_e32 v42, v42
	v_rcp_f32_e32 v43, v43
	s_nop 0
	v_cvt_pk_bf16_f32 v112, v44, v45
	v_cvt_pk_bf16_f32 v113, v46, v47
	v_cvt_pk_bf16_f32 v114, v40, v41
	v_cvt_pk_bf16_f32 v115, v42, v43
	global_store_dwordx4 v[150:151], v[112:115], off
	v_pk_mul_f32 v[36:37], v[36:37], v[178:179] op_sel_hi:[1,0]
	v_pk_mul_f32 v[38:39], v[38:39], v[178:179] op_sel_hi:[1,0]
	v_pk_mul_f32 v[32:33], v[32:33], v[178:179] op_sel_hi:[1,0]
	v_pk_mul_f32 v[34:35], v[34:35], v[178:179] op_sel_hi:[1,0]
	v_exp_f32_e32 v36, v36
	v_exp_f32_e32 v37, v37
	v_exp_f32_e32 v38, v38
	v_exp_f32_e32 v39, v39
	v_exp_f32_e32 v32, v32
	v_exp_f32_e32 v33, v33
	v_exp_f32_e32 v34, v34
	v_exp_f32_e32 v35, v35
	v_add_f32_e32 v36, 1.0, v36
	v_add_f32_e32 v37, 1.0, v37
	v_add_f32_e32 v38, 1.0, v38
	v_add_f32_e32 v39, 1.0, v39
	v_add_f32_e32 v32, 1.0, v32
	v_add_f32_e32 v33, 1.0, v33
	v_add_f32_e32 v34, 1.0, v34
	v_add_f32_e32 v35, 1.0, v35
	v_rcp_f32_e32 v36, v36
	v_rcp_f32_e32 v37, v37
	v_rcp_f32_e32 v38, v38
	v_rcp_f32_e32 v39, v39
	v_rcp_f32_e32 v32, v32
	v_rcp_f32_e32 v33, v33
	v_rcp_f32_e32 v34, v34
	v_rcp_f32_e32 v35, v35
	s_nop 0
	v_cvt_pk_bf16_f32 v116, v36, v37
	v_cvt_pk_bf16_f32 v117, v38, v39
	v_cvt_pk_bf16_f32 v118, v32, v33
	v_cvt_pk_bf16_f32 v119, v34, v35
	global_store_dwordx4 v[150:151], v[116:119], off offset:256
; __device__ __forceinline__ unsigned cvt_pk_bf16(float lo, float hi) { unsigned r; asm volatile("v_cvt_pk_bf16_f32 %0, %1, %2" : "=v"(r) : "v"(lo), "v"(hi)); return r; }
; #define GAS __attribute__((address_space(1)))
;     DI void operator()(AccRef acc, const pg8::Unit& u, int wr, int wc, int, int) const {
;     ...
;                 } else if (kind == 4) {
; #pragma unroll
;                     for (int e = 0; e < 4; ++e) { v0[e] = __builtin_amdgcn_rcpf(1.0f + __builtin_amdgcn_exp2f(v0[e])); v1[e] = __builtin_amdgcn_rcpf(1.0f + __builtin_amdgcn_exp2f(v1[e])); }
;                 }
;                 u32x4 w; w.x = cvt_pk_bf16(v0[0], v0[1]); w.y = cvt_pk_bf16(v0[2], v0[3]); w.z = cvt_pk_bf16(v1[0], v1[1]); w.w = cvt_pk_bf16(v1[2], v1[3]);
;                 *(GAS u32x4*)(dummy ? dummy + lane_ * 8 : Z + (size_t)lrow * ldz + col) = w;
	v_lshl_add_u64 v[146:147], v[150:151], 0, s[2:3]
	v_pk_mul_f32 v[28:29], v[28:29], v[180:181] op_sel_hi:[1,0]
	v_pk_mul_f32 v[30:31], v[30:31], v[180:181] op_sel_hi:[1,0]
	v_pk_mul_f32 v[24:25], v[24:25], v[180:181] op_sel_hi:[1,0]
	v_pk_mul_f32 v[26:27], v[26:27], v[180:181] op_sel_hi:[1,0]
	v_exp_f32_e32 v28, v28
	v_exp_f32_e32 v29, v29
	v_exp_f32_e32 v30, v30
	v_exp_f32_e32 v31, v31
	v_exp_f32_e32 v24, v24
	v_exp_f32_e32 v25, v25
	v_exp_f32_e32 v26, v26
	v_exp_f32_e32 v27, v27
	v_add_f32_e32 v28, 1.0, v28
	v_add_f32_e32 v29, 1.0, v29
	v_add_f32_e32 v30, 1.0, v30
	v_add_f32_e32 v31, 1.0, v31
	v_add_f32_e32 v24, 1.0, v24
	v_add_f32_e32 v25, 1.0, v25
	v_add_f32_e32 v26, 1.0, v26
	v_add_f32_e32 v27, 1.0, v27
	v_rcp_f32_e32 v28, v28
	v_rcp_f32_e32 v29, v29
	v_rcp_f32_e32 v30, v30
	v_rcp_f32_e32 v31, v31
	v_rcp_f32_e32 v24, v24
	v_rcp_f32_e32 v25, v25
	v_rcp_f32_e32 v26, v26
	v_rcp_f32_e32 v27, v27
	s_nop 0
	v_cvt_pk_bf16_f32 v104, v28, v29
	v_cvt_pk_bf16_f32 v105, v30, v31
	v_cvt_pk_bf16_f32 v106, v24, v25
	v_cvt_pk_bf16_f32 v107, v26, v27
	global_store_dwordx4 v[146:147], v[104:107], off
	v_pk_mul_f32 v[20:21], v[20:21], v[180:181] op_sel_hi:[1,0]
	v_pk_mul_f32 v[22:23], v[22:23], v[180:181] op_sel_hi:[1,0]
	v_pk_mul_f32 v[16:17], v[16:17], v[180:181] op_sel_hi:[1,0]
	v_pk_mul_f32 v[18:19], v[18:19], v[180:181] op_sel_hi:[1,0]
	v_exp_f32_e32 v20, v20
	v_exp_f32_e32 v21, v21
	v_exp_f32_e32 v22, v22
	v_exp_f32_e32 v23, v23
	v_exp_f32_e32 v16, v16
	v_exp_f32_e32 v17, v17
	v_exp_f32_e32 v18, v18
	v_exp_f32_e32 v19, v19
	v_add_f32_e32 v20, 1.0, v20
	v_add_f32_e32 v21, 1.0, v21
	v_add_f32_e32 v22, 1.0, v22
	v_add_f32_e32 v23, 1.0, v23
	v_add_f32_e32 v16, 1.0, v16
	v_add_f32_e32 v17, 1.0, v17
	v_add_f32_e32 v18, 1.0, v18
	v_add_f32_e32 v19, 1.0, v19
	v_rcp_f32_e32 v20, v20
	v_rcp_f32_e32 v21, v21
	v_rcp_f32_e32 v22, v22
	v_rcp_f32_e32 v23, v23
	v_rcp_f32_e32 v16, v16
	v_rcp_f32_e32 v17, v17
	v_rcp_f32_e32 v18, v18
	v_rcp_f32_e32 v19, v19
	s_nop 0
	v_cvt_pk_bf16_f32 v108, v20, v21
	v_cvt_pk_bf16_f32 v109, v22, v23
	v_cvt_pk_bf16_f32 v110, v16, v17
	v_cvt_pk_bf16_f32 v111, v18, v19
	global_store_dwordx4 v[146:147], v[108:111], off offset:256
	v_lshl_add_u64 v[150:151], v[146:147], 0, s[2:3]
	v_pk_mul_f32 v[12:13], v[12:13], v[182:183] op_sel_hi:[1,0]
	v_pk_mul_f32 v[14:15], v[14:15], v[182:183] op_sel_hi:[1,0]
	v_pk_mul_f32 v[8:9], v[8:9], v[182:183] op_sel_hi:[1,0]
	v_pk_mul_f32 v[10:11], v[10:11], v[182:183] op_sel_hi:[1,0]
	v_exp_f32_e32 v12, v12
	v_exp_f32_e32 v13, v13
	v_exp_f32_e32 v14, v14
	v_exp_f32_e32 v15, v15
	v_exp_f32_e32 v8, v8
	v_exp_f32_e32 v9, v9
	v_exp_f32_e32 v10, v10
	v_exp_f32_e32 v11, v11
	v_add_f32_e32 v12, 1.0, v12
	v_add_f32_e32 v13, 1.0, v13
	v_add_f32_e32 v14, 1.0, v14
	v_add_f32_e32 v15, 1.0, v15
	v_add_f32_e32 v8, 1.0, v8
	v_add_f32_e32 v9, 1.0, v9
	v_add_f32_e32 v10, 1.0, v10
	v_add_f32_e32 v11, 1.0, v11
	v_rcp_f32_e32 v12, v12
	v_rcp_f32_e32 v13, v13
	v_rcp_f32_e32 v14, v14
	v_rcp_f32_e32 v15, v15
	v_rcp_f32_e32 v8, v8
	v_rcp_f32_e32 v9, v9
	v_rcp_f32_e32 v10, v10
	v_rcp_f32_e32 v11, v11
	s_nop 0
	v_cvt_pk_bf16_f32 v112, v12, v13
	v_cvt_pk_bf16_f32 v113, v14, v15
	v_cvt_pk_bf16_f32 v114, v8, v9
	v_cvt_pk_bf16_f32 v115, v10, v11
	global_store_dwordx4 v[150:151], v[112:115], off
	v_pk_mul_f32 v[4:5], v[4:5], v[182:183] op_sel_hi:[1,0]
	v_pk_mul_f32 v[6:7], v[6:7], v[182:183] op_sel_hi:[1,0]
	v_pk_mul_f32 v[0:1], v[0:1], v[182:183] op_sel_hi:[1,0]
	v_pk_mul_f32 v[2:3], v[2:3], v[182:183] op_sel_hi:[1,0]
	v_exp_f32_e32 v4, v4
	v_exp_f32_e32 v5, v5
	v_exp_f32_e32 v6, v6
	v_exp_f32_e32 v7, v7
	v_exp_f32_e32 v0, v0
	v_exp_f32_e32 v1, v1
	v_exp_f32_e32 v2, v2
	v_exp_f32_e32 v3, v3
	v_add_f32_e32 v4, 1.0, v4
	v_add_f32_e32 v5, 1.0, v5
	v_add_f32_e32 v6, 1.0, v6
	v_add_f32_e32 v7, 1.0, v7
	v_add_f32_e32 v0, 1.0, v0
	v_add_f32_e32 v1, 1.0, v1
	v_add_f32_e32 v2, 1.0, v2
	v_add_f32_e32 v3, 1.0, v3
	v_rcp_f32_e32 v4, v4
	v_rcp_f32_e32 v5, v5
	v_rcp_f32_e32 v6, v6
	v_rcp_f32_e32 v7, v7
	v_rcp_f32_e32 v0, v0
	v_rcp_f32_e32 v1, v1
	v_rcp_f32_e32 v2, v2
	v_rcp_f32_e32 v3, v3
	s_nop 0
	v_cvt_pk_bf16_f32 v116, v4, v5
	v_cvt_pk_bf16_f32 v117, v6, v7
	v_cvt_pk_bf16_f32 v118, v0, v1
	v_cvt_pk_bf16_f32 v119, v2, v3
	global_store_dwordx4 v[150:151], v[116:119], off offset:256

; template <class Epi, class Sched, bool ALIGN_EPI = false, bool SP2 = false>
; __device__ __forceinline__ void gemm_phase(PG8_LAS unsigned char* lds, const Gemm g, const Sched& S, const Epi& E) {
;     ...
;     Unit cur, nxt; int ui = 0;
;     if (!S.next(0, cur)) return;
;     f32x4 acc[2][2][4][2];
; #pragma unroll
;     for (int a = 0; a < 2; ++a)
; #pragma unroll
;         for (int b = 0; b < 2; ++b)
; #pragma unroll
;             for (int m = 0; m < 4; ++m)
; #pragma unroll
;                 for (int n = 0; n < 2; ++n) acc[a][b][m][n] = (f32x4){0.f, 0.f, 0.f, 0.f};
;     bf16x8 At[4][2], B0[2][2], B1[2][2];
;     const char* cA = (const char*)g.A + (size_t)cur.pm * tstepA; const char* cB = (const char*)g.Bt + (size_t)cur.pn * tstepB;
.LBB0_816:
	s_ashr_i32 s91, s90, 31
	s_lshl_b64 s[2:3], s[90:91], 19
	s_add_u32 s82, s24, s2
	s_addc_u32 s83, s25, s3
	s_and_b64 s[2:3], s[4:5], exec
	s_cselect_b32 s7, s83, s9
	s_cselect_b32 s12, s82, s8
	s_ashr_i32 s89, s88, 31
	s_lshl_b64 s[2:3], s[88:89], 19
	s_add_u32 s92, s34, s2
	s_addc_u32 s93, s80, s3
	s_and_b64 s[2:3], s[4:5], exec
	s_cselect_b32 s13, s93, s1
	s_cselect_b32 s15, s92, s0
	s_add_u32 s16, s0, 0x100
	s_addc_u32 s17, s1, 0
	s_add_u32 s0, s8, 0x40080
	v_mov_b32_e32 v0, 0
	s_addc_u32 s1, s9, 0
	s_mov_b32 s78, -2
	v_mov_b32_e32 v1, v0
	v_mov_b32_e32 v2, v0
	v_mov_b32_e32 v3, v0
	v_mov_b32_e32 v4, v0
	v_mov_b32_e32 v5, v0
	v_mov_b32_e32 v6, v0
	v_mov_b32_e32 v7, v0
	v_mov_b32_e32 v16, v0
	v_mov_b32_e32 v17, v0
	v_mov_b32_e32 v18, v0
	v_mov_b32_e32 v19, v0
	v_mov_b32_e32 v20, v0
	v_mov_b32_e32 v21, v0
	v_mov_b32_e32 v22, v0
	v_mov_b32_e32 v23, v0
	v_mov_b32_e32 v32, v0
	v_mov_b32_e32 v33, v0
	v_mov_b32_e32 v34, v0
	v_mov_b32_e32 v35, v0
	v_mov_b32_e32 v36, v0
	v_mov_b32_e32 v37, v0
	v_mov_b32_e32 v38, v0
	v_mov_b32_e32 v39, v0
	v_mov_b32_e32 v48, v0
	v_mov_b32_e32 v49, v0
	v_mov_b32_e32 v50, v0
	v_mov_b32_e32 v51, v0
	v_mov_b32_e32 v52, v0
	v_mov_b32_e32 v53, v0
	v_mov_b32_e32 v54, v0
	v_mov_b32_e32 v55, v0
	v_mov_b32_e32 v8, v0
	v_mov_b32_e32 v9, v0
	v_mov_b32_e32 v10, v0
	v_mov_b32_e32 v11, v0
	v_mov_b32_e32 v12, v0
	v_mov_b32_e32 v13, v0
	v_mov_b32_e32 v14, v0
	v_mov_b32_e32 v15, v0
	v_mov_b32_e32 v24, v0
	v_mov_b32_e32 v25, v0
	v_mov_b32_e32 v26, v0
	v_mov_b32_e32 v27, v0
	v_mov_b32_e32 v28, v0
	v_mov_b32_e32 v29, v0
	v_mov_b32_e32 v30, v0
	v_mov_b32_e32 v31, v0
	v_mov_b32_e32 v40, v0
	v_mov_b32_e32 v41, v0
	v_mov_b32_e32 v42, v0
	v_mov_b32_e32 v43, v0
	v_mov_b32_e32 v44, v0
	v_mov_b32_e32 v45, v0
	v_mov_b32_e32 v46, v0
	v_mov_b32_e32 v47, v0
	v_mov_b32_e32 v56, v0
	v_mov_b32_e32 v57, v0
	v_mov_b32_e32 v58, v0
	v_mov_b32_e32 v59, v0
	v_mov_b32_e32 v60, v0
	v_mov_b32_e32 v61, v0
	v_mov_b32_e32 v62, v0
	v_mov_b32_e32 v63, v0
	s_waitcnt vmcnt(0)
	v_mov_b32_e32 v64, v0
	v_mov_b32_e32 v65, v0
	v_mov_b32_e32 v66, v0
	v_mov_b32_e32 v67, v0
	v_mov_b32_e32 v68, v0
	v_mov_b32_e32 v69, v0
	v_mov_b32_e32 v70, v0
	v_mov_b32_e32 v71, v0
	v_mov_b32_e32 v96, v0
	v_mov_b32_e32 v97, v0
	v_mov_b32_e32 v98, v0
	v_mov_b32_e32 v99, v0
	v_mov_b32_e32 v100, v0
	v_mov_b32_e32 v101, v0
	v_mov_b32_e32 v102, v0
	v_mov_b32_e32 v103, v0
	v_mov_b32_e32 v128, v0
	v_mov_b32_e32 v129, v0
	v_mov_b32_e32 v130, v0
	v_mov_b32_e32 v131, v0
	v_mov_b32_e32 v132, v0
	v_mov_b32_e32 v133, v0
	v_mov_b32_e32 v134, v0
	v_mov_b32_e32 v135, v0
	v_mov_b32_e32 v160, v0
	v_mov_b32_e32 v161, v0
	v_mov_b32_e32 v162, v0
	v_mov_b32_e32 v163, v0
	v_mov_b32_e32 v164, v0
	v_mov_b32_e32 v165, v0
	v_mov_b32_e32 v166, v0
	v_mov_b32_e32 v167, v0
	v_mov_b32_e32 v88, v0
	v_mov_b32_e32 v89, v0
	v_mov_b32_e32 v90, v0
	v_mov_b32_e32 v91, v0
	v_mov_b32_e32 v92, v0
	v_mov_b32_e32 v93, v0
	v_mov_b32_e32 v94, v0
	v_mov_b32_e32 v95, v0
	v_mov_b32_e32 v120, v0
	v_mov_b32_e32 v121, v0
	v_mov_b32_e32 v122, v0
	v_mov_b32_e32 v123, v0
	v_mov_b32_e32 v124, v0
	v_mov_b32_e32 v125, v0
	v_mov_b32_e32 v126, v0
	v_mov_b32_e32 v127, v0
	v_mov_b32_e32 v152, v0
	v_mov_b32_e32 v153, v0
	v_mov_b32_e32 v154, v0
	v_mov_b32_e32 v155, v0
	v_mov_b32_e32 v156, v0
	v_mov_b32_e32 v157, v0
	v_mov_b32_e32 v158, v0
	v_mov_b32_e32 v159, v0
	v_mov_b32_e32 v184, v0
	v_mov_b32_e32 v185, v0
	v_mov_b32_e32 v186, v0
	v_mov_b32_e32 v187, v0
	v_mov_b32_e32 v188, v0
	v_mov_b32_e32 v189, v0
	v_mov_b32_e32 v190, v0
	v_mov_b32_e32 v191, v0
	v_mbcnt_lo_u32_b32 v220, -1, 0
	v_mbcnt_hi_u32_b32 v220, -1, v220
	v_and_b32_e32 v221, 15, v220
	v_lshrrev_b32_e32 v220, 4, v220
	v_or_b32_e32 v221, s49, v221
	v_lshl_add_u32 v221, s6, 8, v221
	v_lshlrev_b32_e32 v220, 4, v220
	v_lshl_add_u32 v220, v221, 6, v220
	v_mov_b32_e32 v221, 0
	v_lshl_add_u64 v[222:223], s[26:27], 0, v[220:221]
	global_load_dwordx4 v[194:197], v[222:223], off
	global_load_dwordx4 v[228:231], v[222:223], off offset:1024
	global_load_dwordx4 v[232:235], v[222:223], off offset:2048
	global_load_dwordx4 v[236:239], v[222:223], off offset:3072
